# removed exp2 denormal-range guards around v_exp_f32 in attention loops; hazard fix (5 wait states readlane->VMEM) in last-layer up finalize
# speedup vs baseline: 1.1567x; 1.0065x over previous
; __device__ __forceinline__ unsigned pk2(float lo, float hi) { return f2bf(lo) | (f2bf(hi) << 16); }
; #define CR_KLOAD(cc) do { _Pragma("unroll") for (int kt = 0; kt < 2; ++kt) { const bf16* kr = kb + (size_t)(32 * (cc) + 16 * kt + i) * 2048; _Pragma("unroll") for (int ks = 0; ks < KS; ++ks) kf[kt][ks] = *(const bf16x8*)(kr + ks * 32 + g * 8); } } while (0)
; __device__ __forceinline__ void cross_phase(const Ctx& C, const bf16* Q, const bf16* KV  , bf16* O) {
;     ...
;             for (int c = 0; c < MEML / 32; ++c) {
;                 CR_KLOAD(c);
;                 f32x4 st[2];
; #pragma unroll
;                 for (int kt = 0; kt < 2; ++kt) { st[kt] = (f32x4){0.f, 0.f, 0.f, 0.f};
; #pragma unroll
;                     for (int ks = 0; ks < KS; ++ks) st[kt] = __builtin_amdgcn_mfma_f32_16x16x32_bf16(kf[kt][ks], qf[ks], st[kt], 0, 0, 0); }
;                 float pv[8];
; #pragma unroll
;                 for (int kt = 0; kt < 2; ++kt)
; #pragma unroll
;                     for (int j = 0; j < 4; ++j) pv[kt * 4 + j] = st[kt][j] * (0.0625f * LOG2E);
;                 float cm = pv[0];
; #pragma unroll
;                 for (int r = 1; r < 8; ++r) cm = fmaxf(cm, pv[r]);
;                 cm = fmaxf(cm, __shfl_xor(cm, 16)); cm = fmaxf(cm, __shfl_xor(cm, 32));
;                 const float mn = fmaxf(m_run, cm), sc = exp2f(m_run - mn);
;                 float ls = 0.f;
; #pragma unroll
;                 for (int r = 0; r < 8; ++r) { pv[r] = exp2f(pv[r] - mn); ls += pv[r]; }
;                 ls += __shfl_xor(ls, 16); ls += __shfl_xor(ls, 32);
;                 l_run = l_run * sc + ls; m_run = mn;
; #pragma unroll
;                 for (int dt = 0; dt < DT; ++dt) oacc[dt] = oacc[dt] * sc;
;                 bf16x8 pb; { v4u t; t.x = pk2(pv[0], pv[1]); t.y = pk2(pv[2], pv[3]); t.z = pk2(pv[4], pv[5]); t.w = pk2(pv[6], pv[7]); pb = __builtin_bit_cast(bf16x8, t); }
; #pragma unroll
;                 for (int d4 = 0; d4 < DT; d4 += 4) { bf16x8 vf4[4]; read_vfrags4_trp<P>(vs + (32 * c) * P + 16 * d4, i, g, vf4);
; #pragma unroll
;                     for (int dt = 0; dt < 4; ++dt) oacc[d4 + dt] = __builtin_amdgcn_mfma_f32_16x16x32_bf16(vf4[dt], pb, oacc[d4 + dt], 0, 0, 0); }
.LBB0_293:
	v_lshl_add_u64 v[74:75], v[142:143], 0, s[8:9]
	s_mov_b32 s13, 0x11600000
	v_mov_b32_e32 v164, v162
	v_add_co_u32_e32 v162, vcc, s13, v74
	s_mov_b32 s13, 0x11610000
	s_nop 0
	v_addc_co_u32_e32 v163, vcc, 0, v75, vcc
	global_load_dwordx4 v[166:169], v[162:163], off
	global_load_dwordx4 v[170:173], v[162:163], off offset:64
	global_load_dwordx4 v[190:193], v[162:163], off offset:128
	global_load_dwordx4 v[194:197], v[162:163], off offset:192
	global_load_dwordx4 v[198:201], v[162:163], off offset:256
	global_load_dwordx4 v[202:205], v[162:163], off offset:320
	global_load_dwordx4 v[206:209], v[162:163], off offset:384
	global_load_dwordx4 v[210:213], v[162:163], off offset:448
	v_add_co_u32_e32 v74, vcc, s13, v74
	s_add_u32 s8, s8, 0x20000
	s_nop 0
	v_addc_co_u32_e32 v75, vcc, 0, v75, vcc
	global_load_dwordx4 v[214:217], v[74:75], off
	global_load_dwordx4 v[218:221], v[74:75], off offset:64
	global_load_dwordx4 v[222:225], v[74:75], off offset:128
	global_load_dwordx4 v[226:229], v[74:75], off offset:192
	global_load_dwordx4 v[230:233], v[74:75], off offset:256
	global_load_dwordx4 v[234:237], v[74:75], off offset:320
	global_load_dwordx4 v[238:241], v[74:75], off offset:384
	global_load_dwordx4 v[242:245], v[74:75], off offset:448
	s_addc_u32 s9, s9, 0
	s_cmp_lg_u32 s8, 0x100000
	s_waitcnt vmcnt(15)
	v_mfma_f32_16x16x32_bf16 v[166:169], v[166:169], v[0:3], 0
	s_waitcnt vmcnt(14)
	v_mfma_f32_16x16x32_bf16 v[166:169], v[170:173], v[4:7], v[166:169]
	s_waitcnt vmcnt(7)
	v_mfma_f32_16x16x32_bf16 v[170:173], v[214:217], v[0:3], 0
	s_waitcnt vmcnt(6)
	v_mfma_f32_16x16x32_bf16 v[170:173], v[218:221], v[4:7], v[170:173]
	v_mfma_f32_16x16x32_bf16 v[166:169], v[190:193], v[8:11], v[166:169]
	s_waitcnt vmcnt(5)
	v_mfma_f32_16x16x32_bf16 v[170:173], v[222:225], v[8:11], v[170:173]
	v_mfma_f32_16x16x32_bf16 v[166:169], v[194:197], v[12:15], v[166:169]
	s_waitcnt vmcnt(4)
	v_mfma_f32_16x16x32_bf16 v[170:173], v[226:229], v[12:15], v[170:173]
	v_mfma_f32_16x16x32_bf16 v[166:169], v[198:201], v[16:19], v[166:169]
	s_waitcnt vmcnt(3)
	v_mfma_f32_16x16x32_bf16 v[170:173], v[230:233], v[16:19], v[170:173]
	v_mfma_f32_16x16x32_bf16 v[166:169], v[202:205], v[20:23], v[166:169]
	s_waitcnt vmcnt(2)
	v_mfma_f32_16x16x32_bf16 v[170:173], v[234:237], v[20:23], v[170:173]
	v_mfma_f32_16x16x32_bf16 v[166:169], v[206:209], v[24:27], v[166:169]
	s_waitcnt vmcnt(1)
	v_mfma_f32_16x16x32_bf16 v[170:173], v[238:241], v[24:27], v[170:173]
	v_mfma_f32_16x16x32_bf16 v[166:169], v[210:213], v[28:31], v[166:169]
	s_waitcnt vmcnt(0)
	v_mfma_f32_16x16x32_bf16 v[170:173], v[242:245], v[28:31], v[170:173]
	s_nop 5
	v_mul_f32_e32 v73, 0x3db8aa3b, v166
	v_mul_f32_e32 v74, 0x3db8aa3b, v167
	v_mul_f32_e32 v75, 0x3db8aa3b, v168
	v_mul_f32_e32 v136, 0x3db8aa3b, v169
	v_max_f32_e32 v73, v73, v74
	v_mul_f32_e32 v162, 0x3db8aa3b, v170
	v_mul_f32_e32 v163, 0x3db8aa3b, v171
	v_max3_f32 v73, v73, v75, v136
	v_mul_f32_e32 v165, 0x3db8aa3b, v172
	v_mul_f32_e32 v174, 0x3db8aa3b, v173
	v_max3_f32 v73, v73, v162, v163
	v_max3_f32 v73, v73, v165, v174
	ds_bpermute_b32 v74, v159, v73
	v_add_u32_e32 v174, 0xfffffe80, v161
	s_waitcnt lgkmcnt(0)
	v_max_f32_e32 v74, v74, v74
	v_max_f32_e32 v73, v73, v74
	ds_bpermute_b32 v74, v160, v73
	s_waitcnt lgkmcnt(0)
	v_max3_f32 v163, v72, v73, v74
	v_fma_f32 v73, v166, s55, -v163
	v_fma_f32 v136, v168, s55, -v163
	v_sub_f32_e32 v72, v72, v163
	v_exp_f32_e32 v73, v73
	v_fma_f32 v74, v167, s55, -v163
	s_nop 1
	v_exp_f32_e32 v74, v74
	s_nop 0
	v_exp_f32_e32 v136, v136
	v_add_f32_e32 v75, v73, v74
	v_mov_b32_e32 v165, v136
	v_fma_f32 v136, v169, s55, -v163
	v_add_f32_e32 v75, v165, v75
	s_nop 0
	v_exp_f32_e32 v136, v136
	s_nop 0
	v_mov_b32_e32 v166, v136
	v_fma_f32 v136, v170, s55, -v163
	v_add_f32_e32 v75, v166, v75
	s_nop 0
	v_exp_f32_e32 v136, v136
	s_nop 0
	v_mov_b32_e32 v167, v136
	v_fma_f32 v136, v171, s55, -v163
	v_add_f32_e32 v75, v167, v75
	v_bfe_u32 v171, v166, 16, 1
	v_exp_f32_e32 v136, v136
	v_add3_u32 v166, v166, v171, s86
	v_mov_b32_e32 v168, v136
	v_fma_f32 v136, v172, s55, -v163
	v_add_f32_e32 v75, v168, v75
	v_bfe_u32 v172, v74, 16, 1
	v_exp_f32_e32 v136, v136
	v_add3_u32 v172, v74, v172, s86
	v_mov_b32_e32 v169, v136
	v_fma_f32 v136, v173, s55, -v163
	v_add_f32_e32 v75, v169, v75
	v_bfe_u32 v171, v169, 16, 1
	v_exp_f32_e32 v136, v136
	v_add3_u32 v169, v169, v171, s86
	v_mov_b32_e32 v170, v136
	v_exp_f32_e32 v72, v72
	v_add_f32_e32 v75, v170, v75
	v_mov_b32_e32 v136, v72
	ds_bpermute_b32 v72, v159, v75
	v_pk_mul_f32 v[98:99], v[98:99], v[136:137] op_sel_hi:[1,0]
	v_pk_mul_f32 v[96:97], v[96:97], v[136:137] op_sel_hi:[1,0]
	v_pk_mul_f32 v[78:79], v[78:79], v[136:137] op_sel_hi:[1,0]
	v_pk_mul_f32 v[76:77], v[76:77], v[136:137] op_sel_hi:[1,0]
	s_waitcnt lgkmcnt(0)
	v_add_f32_e32 v72, v75, v72
	ds_bpermute_b32 v75, v160, v72
	v_pk_mul_f32 v[70:71], v[70:71], v[136:137] op_sel_hi:[1,0]
	v_pk_mul_f32 v[68:69], v[68:69], v[136:137] op_sel_hi:[1,0]
	v_pk_mul_f32 v[46:47], v[46:47], v[136:137] op_sel_hi:[1,0]
	v_pk_mul_f32 v[44:45], v[44:45], v[136:137] op_sel_hi:[1,0]
	s_waitcnt lgkmcnt(0)
	v_add_f32_e32 v162, v72, v75
	v_bfe_u32 v72, v170, 16, 1
	v_bfe_u32 v75, v168, 16, 1
	v_add3_u32 v74, v168, v75, s86
	v_add3_u32 v72, v170, v72, s86
	v_bfe_u32 v75, v73, 16, 1
	v_bfe_u32 v168, v165, 16, 1
	v_bfe_u32 v170, v167, 16, 1
	v_add3_u32 v167, v167, v170, s86
	v_add3_u32 v165, v165, v168, s86
	v_add3_u32 v73, v73, v75, s86
	v_lshrrev_b32_e32 v168, 16, v73
	v_lshrrev_b32_e32 v73, 16, v165
	v_lshrrev_b32_e32 v165, 16, v167
	v_lshrrev_b32_e32 v75, 16, v169
	v_and_or_b32 v75, v72, s85, v75
	v_and_or_b32 v74, v74, s85, v165
	v_and_or_b32 v73, v166, s85, v73
	v_and_or_b32 v72, v172, s85, v168
	v_add_u32_e32 v165, 0xffffdd80, v161
	ds_read_b64_tr_b16 v[194:195], v165
	ds_read_b64_tr_b16 v[190:191], v165 offset:32
	ds_read_b64_tr_b16 v[170:171], v165 offset:64
	ds_read_b64_tr_b16 v[166:167], v165 offset:96
	ds_read_b64_tr_b16 v[196:197], v174
	ds_read_b64_tr_b16 v[192:193], v174 offset:32
	ds_read_b64_tr_b16 v[172:173], v174 offset:64
	ds_read_b64_tr_b16 v[168:169], v174 offset:96
	s_waitcnt lgkmcnt(0)
; __device__ __forceinline__ unsigned pk2(float lo, float hi) { return f2bf(lo) | (f2bf(hi) << 16); }
; __device__ __forceinline__ void cross_phase(const Ctx& C, const bf16* Q, const bf16* KV  , bf16* O) {
;     ...
; #pragma unroll
;                 for (int dt = 0; dt < DT; ++dt) oacc[dt] = oacc[dt] * sc;
;                 bf16x8 pb; { v4u t; t.x = pk2(pv[0], pv[1]); t.y = pk2(pv[2], pv[3]); t.z = pk2(pv[4], pv[5]); t.w = pk2(pv[6], pv[7]); pb = __builtin_bit_cast(bf16x8, t); }
; #pragma unroll
;                 for (int d4 = 0; d4 < DT; d4 += 4) { bf16x8 vf4[4]; read_vfrags4_trp<P>(vs + (32 * c) * P + 16 * d4, i, g, vf4);
; #pragma unroll
;                     for (int dt = 0; dt < 4; ++dt) oacc[d4 + dt] = __builtin_amdgcn_mfma_f32_16x16x32_bf16(vf4[dt], pb, oacc[d4 + dt], 0, 0, 0); }
;             }
;     ...
;             const float il = 1.0f / l_run;
;             bf16* op = O + (size_t)(b * SEQ + t0 + i) * DM + hd * 256 + 4 * g;
; #pragma unroll
;             for (int dt = 0; dt < DT; ++dt) { v2u w; w.x = pk2(oacc[dt].x * il, oacc[dt].y * il); w.y = pk2(oacc[dt].z * il, oacc[dt].w * il); *(v2u*)(op + 16 * dt) = w; }
	v_pk_mul_f32 v[50:51], v[50:51], v[136:137] op_sel_hi:[1,0]
	v_pk_mul_f32 v[48:49], v[48:49], v[136:137] op_sel_hi:[1,0]
	v_pk_mul_f32 v[42:43], v[42:43], v[136:137] op_sel_hi:[1,0]
	v_pk_mul_f32 v[40:41], v[40:41], v[136:137] op_sel_hi:[1,0]
	v_pk_mul_f32 v[38:39], v[38:39], v[136:137] op_sel_hi:[1,0]
	v_pk_mul_f32 v[36:37], v[36:37], v[136:137] op_sel_hi:[1,0]
	v_pk_mul_f32 v[34:35], v[34:35], v[136:137] op_sel_hi:[1,0]
	v_pk_mul_f32 v[32:33], v[32:33], v[136:137] op_sel_hi:[1,0]
	v_mfma_f32_16x16x32_bf16 v[96:99], v[194:197], v[72:75], v[96:99]
	v_add_u32_e32 v165, 0xffffde00, v161
	v_add_u32_e32 v174, 0xffffff00, v161
	v_pk_mul_f32 v[82:83], v[82:83], v[136:137] op_sel_hi:[1,0]
	v_mfma_f32_16x16x32_bf16 v[76:79], v[190:193], v[72:75], v[76:79]
	v_mul_f32_e64 v80, v80, v136
	v_mul_f32_e64 v81, v81, v136
	v_pk_mul_f32 v[86:87], v[86:87], v[136:137] op_sel_hi:[1,0]
	v_pk_mul_f32 v[84:85], v[84:85], v[136:137] op_sel_hi:[1,0]
	v_mfma_f32_16x16x32_bf16 v[68:71], v[170:173], v[72:75], v[68:71]
	v_mul_f32_e64 v90, v90, v136
	v_mul_f32_e64 v91, v91, v136
	v_pk_mul_f32 v[88:89], v[88:89], v[136:137] op_sel_hi:[1,0]
	v_pk_mul_f32 v[94:95], v[94:95], v[136:137] op_sel_hi:[1,0]
	v_mfma_f32_16x16x32_bf16 v[44:47], v[166:169], v[72:75], v[44:47]
	ds_read_b64_tr_b16 v[194:195], v165
	ds_read_b64_tr_b16 v[190:191], v165 offset:32
	ds_read_b64_tr_b16 v[170:171], v165 offset:64
	ds_read_b64_tr_b16 v[166:167], v165 offset:96
	ds_read_b64_tr_b16 v[196:197], v174
	ds_read_b64_tr_b16 v[192:193], v174 offset:32
	ds_read_b64_tr_b16 v[172:173], v174 offset:64
	ds_read_b64_tr_b16 v[168:169], v174 offset:96
	s_waitcnt lgkmcnt(0)
	v_mul_f32_e64 v92, v92, v136
	v_mul_f32_e64 v93, v93, v136
	v_pk_mul_f32 v[54:55], v[54:55], v[136:137] op_sel_hi:[1,0]
	v_pk_mul_f32 v[52:53], v[52:53], v[136:137] op_sel_hi:[1,0]
	v_pk_mul_f32 v[58:59], v[58:59], v[136:137] op_sel_hi:[1,0]
	v_pk_mul_f32 v[56:57], v[56:57], v[136:137] op_sel_hi:[1,0]
	v_pk_mul_f32 v[62:63], v[62:63], v[136:137] op_sel_hi:[1,0]
	v_pk_mul_f32 v[60:61], v[60:61], v[136:137] op_sel_hi:[1,0]
	v_pk_mul_f32 v[66:67], v[66:67], v[136:137] op_sel_hi:[1,0]
	v_pk_mul_f32 v[64:65], v[64:65], v[136:137] op_sel_hi:[1,0]
	v_mfma_f32_16x16x32_bf16 v[48:51], v[194:197], v[72:75], v[48:51]
	v_add_u32_e32 v165, 0xffffde80, v161
	v_add_u32_e32 v174, 0xffffff80, v161
	v_fmac_f32_e32 v162, v164, v136
	v_mfma_f32_16x16x32_bf16 v[40:43], v[190:193], v[72:75], v[40:43]
	v_mfma_f32_16x16x32_bf16 v[36:39], v[170:173], v[72:75], v[36:39]
	v_mfma_f32_16x16x32_bf16 v[32:35], v[166:169], v[72:75], v[32:35]
	ds_read_b64_tr_b16 v[194:195], v165
	ds_read_b64_tr_b16 v[190:191], v165 offset:32
	ds_read_b64_tr_b16 v[170:171], v165 offset:64
	ds_read_b64_tr_b16 v[166:167], v165 offset:96
	ds_read_b64_tr_b16 v[196:197], v174
	ds_read_b64_tr_b16 v[192:193], v174 offset:32
	ds_read_b64_tr_b16 v[172:173], v174 offset:64
	ds_read_b64_tr_b16 v[168:169], v174 offset:96
	s_waitcnt lgkmcnt(0)
	v_add_u32_e32 v165, 0xffffdf00, v161
	v_mfma_f32_16x16x32_bf16 v[80:83], v[194:197], v[72:75], v[80:83]
	v_mfma_f32_16x16x32_bf16 v[84:87], v[190:193], v[72:75], v[84:87]
	v_mfma_f32_16x16x32_bf16 v[88:91], v[170:173], v[72:75], v[88:91]
	v_mfma_f32_16x16x32_bf16 v[92:95], v[166:169], v[72:75], v[92:95]
	ds_read_b64_tr_b16 v[194:195], v165
	ds_read_b64_tr_b16 v[190:191], v165 offset:32
	ds_read_b64_tr_b16 v[170:171], v165 offset:64
	ds_read_b64_tr_b16 v[166:167], v165 offset:96
	ds_read_b64_tr_b16 v[196:197], v161
	ds_read_b64_tr_b16 v[192:193], v161 offset:32
	ds_read_b64_tr_b16 v[172:173], v161 offset:64
	ds_read_b64_tr_b16 v[168:169], v161 offset:96
	s_waitcnt lgkmcnt(0)
	v_add_u32_e32 v161, 0x4200, v161
	v_mfma_f32_16x16x32_bf16 v[52:55], v[194:197], v[72:75], v[52:55]
	v_mfma_f32_16x16x32_bf16 v[56:59], v[190:193], v[72:75], v[56:59]
	v_mfma_f32_16x16x32_bf16 v[60:63], v[170:173], v[72:75], v[60:63]
	v_mfma_f32_16x16x32_bf16 v[64:67], v[166:169], v[72:75], v[64:67]
	v_mov_b32_e32 v72, v163
	s_cbranch_scc1 .LBB0_293
	v_div_scale_f32 v1, s[8:9], v162, v162, 1.0
	v_rcp_f32_e32 v2, v1
	v_lshlrev_b32_e32 v0, 2, v133
	s_add_i32 s12, s12, 1
	s_cmp_eq_u32 s12, 8
	v_fma_f32 v3, -v1, v2, 1.0
	v_fmac_f32_e32 v2, v3, v2
	v_div_scale_f32 v3, vcc, 1.0, v162, 1.0
	v_mul_f32_e32 v4, v3, v2
	v_fma_f32 v5, -v1, v4, v3
	v_fmac_f32_e32 v4, v5, v2
	v_fma_f32 v1, -v1, v4, v3
	v_div_fmas_f32 v1, v1, v2, v4
	v_div_fixup_f32 v2, v1, v162, 1.0
	v_lshl_add_u64 v[4:5], v[134:135], 1, s[4:5]
	v_ashrrev_i32_e32 v1, 31, v0
	v_lshl_add_u64 v[0:1], v[0:1], 1, v[4:5]
	v_mov_b32_e32 v4, v96
	v_mov_b32_e32 v5, v98
	v_pk_mul_f32 v[4:5], v[4:5], v[2:3] op_sel_hi:[1,0]
	v_mov_b32_e32 v98, v97
	v_pk_mul_f32 v[6:7], v[98:99], v[2:3] op_sel_hi:[1,0]
	v_and_b32_sdwa v3, v5, v182 dst_sel:DWORD dst_unused:UNUSED_PAD src0_sel:WORD_1 src1_sel:DWORD
	v_and_b32_sdwa v8, v4, v182 dst_sel:DWORD dst_unused:UNUSED_PAD src0_sel:WORD_1 src1_sel:DWORD
	v_add3_u32 v4, v4, v8, s86
	v_add3_u32 v3, v5, v3, s86
	v_and_b32_sdwa v5, v7, v182 dst_sel:DWORD dst_unused:UNUSED_PAD src0_sel:WORD_1 src1_sel:DWORD
	v_and_b32_sdwa v8, v6, v182 dst_sel:DWORD dst_unused:UNUSED_PAD src0_sel:WORD_1 src1_sel:DWORD
	v_add3_u32 v5, v7, v5, s86
	v_add3_u32 v6, v6, v8, s86
	v_and_b32_e32 v5, 0xffff0000, v5
	v_and_b32_e32 v6, 0xffff0000, v6
	v_or_b32_sdwa v5, v5, v3 dst_sel:DWORD dst_unused:UNUSED_PAD src0_sel:DWORD src1_sel:WORD_1
	v_or_b32_sdwa v4, v6, v4 dst_sel:DWORD dst_unused:UNUSED_PAD src0_sel:DWORD src1_sel:WORD_1
	global_store_dwordx2 v[0:1], v[4:5], off
	v_mov_b32_e32 v4, v76
	v_mov_b32_e32 v5, v78
	v_pk_mul_f32 v[4:5], v[4:5], v[2:3] op_sel_hi:[1,0]
	v_mov_b32_e32 v78, v77
	v_pk_mul_f32 v[6:7], v[78:79], v[2:3] op_sel_hi:[1,0]
; __device__ __forceinline__ unsigned pk2(float lo, float hi) { return f2bf(lo) | (f2bf(hi) << 16); }
; __device__ __forceinline__ void cross_phase(const Ctx& C, const bf16* Q, const bf16* KV  , bf16* O) {
;     ...
;             const float il = 1.0f / l_run;
;             bf16* op = O + (size_t)(b * SEQ + t0 + i) * DM + hd * 256 + 4 * g;
; #pragma unroll
;             for (int dt = 0; dt < DT; ++dt) { v2u w; w.x = pk2(oacc[dt].x * il, oacc[dt].y * il); w.y = pk2(oacc[dt].z * il, oacc[dt].w * il); *(v2u*)(op + 16 * dt) = w; }
;         }
;         __syncthreads();
;     }
	v_and_b32_sdwa v3, v5, v182 dst_sel:DWORD dst_unused:UNUSED_PAD src0_sel:WORD_1 src1_sel:DWORD
	v_and_b32_sdwa v8, v4, v182 dst_sel:DWORD dst_unused:UNUSED_PAD src0_sel:WORD_1 src1_sel:DWORD
	v_add3_u32 v4, v4, v8, s86
	v_add3_u32 v3, v5, v3, s86
	v_and_b32_sdwa v5, v7, v182 dst_sel:DWORD dst_unused:UNUSED_PAD src0_sel:WORD_1 src1_sel:DWORD
	v_and_b32_sdwa v8, v6, v182 dst_sel:DWORD dst_unused:UNUSED_PAD src0_sel:WORD_1 src1_sel:DWORD
	v_add3_u32 v5, v7, v5, s86
	v_add3_u32 v6, v6, v8, s86
	v_and_b32_e32 v5, 0xffff0000, v5
	v_and_b32_e32 v6, 0xffff0000, v6
	v_or_b32_sdwa v5, v5, v3 dst_sel:DWORD dst_unused:UNUSED_PAD src0_sel:DWORD src1_sel:WORD_1
	v_or_b32_sdwa v4, v6, v4 dst_sel:DWORD dst_unused:UNUSED_PAD src0_sel:DWORD src1_sel:WORD_1
	global_store_dwordx2 v[0:1], v[4:5], off offset:32
	v_mov_b32_e32 v4, v68
	v_mov_b32_e32 v5, v70
	v_pk_mul_f32 v[4:5], v[4:5], v[2:3] op_sel_hi:[1,0]
	v_mov_b32_e32 v70, v69
	v_pk_mul_f32 v[6:7], v[70:71], v[2:3] op_sel_hi:[1,0]
	v_and_b32_sdwa v3, v5, v182 dst_sel:DWORD dst_unused:UNUSED_PAD src0_sel:WORD_1 src1_sel:DWORD
	v_and_b32_sdwa v8, v4, v182 dst_sel:DWORD dst_unused:UNUSED_PAD src0_sel:WORD_1 src1_sel:DWORD
	v_add3_u32 v4, v4, v8, s86
	v_add3_u32 v3, v5, v3, s86
	v_and_b32_sdwa v5, v7, v182 dst_sel:DWORD dst_unused:UNUSED_PAD src0_sel:WORD_1 src1_sel:DWORD
	v_and_b32_sdwa v8, v6, v182 dst_sel:DWORD dst_unused:UNUSED_PAD src0_sel:WORD_1 src1_sel:DWORD
	v_add3_u32 v5, v7, v5, s86
	v_add3_u32 v6, v6, v8, s86
	v_and_b32_e32 v5, 0xffff0000, v5
	v_and_b32_e32 v6, 0xffff0000, v6
	v_or_b32_sdwa v5, v5, v3 dst_sel:DWORD dst_unused:UNUSED_PAD src0_sel:DWORD src1_sel:WORD_1
	v_or_b32_sdwa v4, v6, v4 dst_sel:DWORD dst_unused:UNUSED_PAD src0_sel:DWORD src1_sel:WORD_1
	global_store_dwordx2 v[0:1], v[4:5], off offset:64
	v_mov_b32_e32 v4, v44
	v_mov_b32_e32 v5, v46
	v_pk_mul_f32 v[4:5], v[4:5], v[2:3] op_sel_hi:[1,0]
	v_mov_b32_e32 v46, v45
	v_pk_mul_f32 v[6:7], v[46:47], v[2:3] op_sel_hi:[1,0]
	v_and_b32_sdwa v3, v5, v182 dst_sel:DWORD dst_unused:UNUSED_PAD src0_sel:WORD_1 src1_sel:DWORD
	v_and_b32_sdwa v8, v4, v182 dst_sel:DWORD dst_unused:UNUSED_PAD src0_sel:WORD_1 src1_sel:DWORD
	v_add3_u32 v4, v4, v8, s86
	v_add3_u32 v3, v5, v3, s86
	v_and_b32_sdwa v5, v7, v182 dst_sel:DWORD dst_unused:UNUSED_PAD src0_sel:WORD_1 src1_sel:DWORD
	v_and_b32_sdwa v8, v6, v182 dst_sel:DWORD dst_unused:UNUSED_PAD src0_sel:WORD_1 src1_sel:DWORD
	v_add3_u32 v5, v7, v5, s86
	v_add3_u32 v6, v6, v8, s86
	v_and_b32_e32 v5, 0xffff0000, v5
	v_and_b32_e32 v6, 0xffff0000, v6
	v_or_b32_sdwa v5, v5, v3 dst_sel:DWORD dst_unused:UNUSED_PAD src0_sel:DWORD src1_sel:WORD_1
	v_or_b32_sdwa v4, v6, v4 dst_sel:DWORD dst_unused:UNUSED_PAD src0_sel:DWORD src1_sel:WORD_1
	global_store_dwordx2 v[0:1], v[4:5], off offset:96
	v_mov_b32_e32 v4, v48
	v_mov_b32_e32 v5, v50
	v_pk_mul_f32 v[4:5], v[4:5], v[2:3] op_sel_hi:[1,0]
	v_mov_b32_e32 v50, v49
	v_pk_mul_f32 v[6:7], v[50:51], v[2:3] op_sel_hi:[1,0]
	v_and_b32_sdwa v3, v5, v182 dst_sel:DWORD dst_unused:UNUSED_PAD src0_sel:WORD_1 src1_sel:DWORD
	v_and_b32_sdwa v8, v4, v182 dst_sel:DWORD dst_unused:UNUSED_PAD src0_sel:WORD_1 src1_sel:DWORD
	v_add3_u32 v4, v4, v8, s86
	v_add3_u32 v3, v5, v3, s86
	v_and_b32_sdwa v5, v7, v182 dst_sel:DWORD dst_unused:UNUSED_PAD src0_sel:WORD_1 src1_sel:DWORD
	v_and_b32_sdwa v8, v6, v182 dst_sel:DWORD dst_unused:UNUSED_PAD src0_sel:WORD_1 src1_sel:DWORD
	v_add3_u32 v5, v7, v5, s86
	v_add3_u32 v6, v6, v8, s86
	v_and_b32_e32 v5, 0xffff0000, v5
	v_and_b32_e32 v6, 0xffff0000, v6
	v_or_b32_sdwa v5, v5, v3 dst_sel:DWORD dst_unused:UNUSED_PAD src0_sel:DWORD src1_sel:WORD_1
	v_or_b32_sdwa v4, v6, v4 dst_sel:DWORD dst_unused:UNUSED_PAD src0_sel:DWORD src1_sel:WORD_1
	global_store_dwordx2 v[0:1], v[4:5], off offset:128
	v_mov_b32_e32 v4, v40
	v_mov_b32_e32 v5, v42
	v_pk_mul_f32 v[4:5], v[4:5], v[2:3] op_sel_hi:[1,0]
	v_mov_b32_e32 v42, v41
	v_pk_mul_f32 v[6:7], v[42:43], v[2:3] op_sel_hi:[1,0]
	v_and_b32_sdwa v3, v5, v182 dst_sel:DWORD dst_unused:UNUSED_PAD src0_sel:WORD_1 src1_sel:DWORD
	v_and_b32_sdwa v8, v4, v182 dst_sel:DWORD dst_unused:UNUSED_PAD src0_sel:WORD_1 src1_sel:DWORD
	v_add3_u32 v4, v4, v8, s86
	v_add3_u32 v3, v5, v3, s86
	v_and_b32_sdwa v5, v7, v182 dst_sel:DWORD dst_unused:UNUSED_PAD src0_sel:WORD_1 src1_sel:DWORD
	v_and_b32_sdwa v8, v6, v182 dst_sel:DWORD dst_unused:UNUSED_PAD src0_sel:WORD_1 src1_sel:DWORD
	v_add3_u32 v5, v7, v5, s86
	v_add3_u32 v6, v6, v8, s86
	v_and_b32_e32 v5, 0xffff0000, v5
	v_and_b32_e32 v6, 0xffff0000, v6
	v_or_b32_sdwa v5, v5, v3 dst_sel:DWORD dst_unused:UNUSED_PAD src0_sel:DWORD src1_sel:WORD_1
	v_or_b32_sdwa v4, v6, v4 dst_sel:DWORD dst_unused:UNUSED_PAD src0_sel:DWORD src1_sel:WORD_1
	global_store_dwordx2 v[0:1], v[4:5], off offset:160
	v_mov_b32_e32 v4, v36
	v_mov_b32_e32 v5, v38
	v_pk_mul_f32 v[4:5], v[4:5], v[2:3] op_sel_hi:[1,0]
	v_mov_b32_e32 v38, v37
	v_pk_mul_f32 v[6:7], v[38:39], v[2:3] op_sel_hi:[1,0]
	v_and_b32_sdwa v3, v5, v182 dst_sel:DWORD dst_unused:UNUSED_PAD src0_sel:WORD_1 src1_sel:DWORD
	v_and_b32_sdwa v8, v4, v182 dst_sel:DWORD dst_unused:UNUSED_PAD src0_sel:WORD_1 src1_sel:DWORD
	v_add3_u32 v4, v4, v8, s86
	v_add3_u32 v3, v5, v3, s86
	v_and_b32_sdwa v5, v7, v182 dst_sel:DWORD dst_unused:UNUSED_PAD src0_sel:WORD_1 src1_sel:DWORD
	v_and_b32_sdwa v8, v6, v182 dst_sel:DWORD dst_unused:UNUSED_PAD src0_sel:WORD_1 src1_sel:DWORD
	v_add3_u32 v5, v7, v5, s86
	v_add3_u32 v6, v6, v8, s86
	v_and_b32_e32 v5, 0xffff0000, v5
	v_and_b32_e32 v6, 0xffff0000, v6
	v_or_b32_sdwa v5, v5, v3 dst_sel:DWORD dst_unused:UNUSED_PAD src0_sel:DWORD src1_sel:WORD_1
	v_or_b32_sdwa v4, v6, v4 dst_sel:DWORD dst_unused:UNUSED_PAD src0_sel:DWORD src1_sel:WORD_1
; __device__ __forceinline__ unsigned pk2(float lo, float hi) { return f2bf(lo) | (f2bf(hi) << 16); }
; __device__ __forceinline__ void cross_phase(const Ctx& C, const bf16* Q, const bf16* KV  , bf16* O) {
;     ...
;             const float il = 1.0f / l_run;
;             bf16* op = O + (size_t)(b * SEQ + t0 + i) * DM + hd * 256 + 4 * g;
; #pragma unroll
;             for (int dt = 0; dt < DT; ++dt) { v2u w; w.x = pk2(oacc[dt].x * il, oacc[dt].y * il); w.y = pk2(oacc[dt].z * il, oacc[dt].w * il); *(v2u*)(op + 16 * dt) = w; }
;         }
;         __syncthreads();
;     }
	global_store_dwordx2 v[0:1], v[4:5], off offset:192
	v_mov_b32_e32 v4, v32
	v_mov_b32_e32 v5, v34
	v_pk_mul_f32 v[4:5], v[4:5], v[2:3] op_sel_hi:[1,0]
	v_mov_b32_e32 v34, v33
	v_pk_mul_f32 v[6:7], v[34:35], v[2:3] op_sel_hi:[1,0]
	v_and_b32_sdwa v3, v5, v182 dst_sel:DWORD dst_unused:UNUSED_PAD src0_sel:WORD_1 src1_sel:DWORD
	v_and_b32_sdwa v8, v4, v182 dst_sel:DWORD dst_unused:UNUSED_PAD src0_sel:WORD_1 src1_sel:DWORD
	v_add3_u32 v4, v4, v8, s86
	v_add3_u32 v3, v5, v3, s86
	v_and_b32_sdwa v5, v7, v182 dst_sel:DWORD dst_unused:UNUSED_PAD src0_sel:WORD_1 src1_sel:DWORD
	v_and_b32_sdwa v8, v6, v182 dst_sel:DWORD dst_unused:UNUSED_PAD src0_sel:WORD_1 src1_sel:DWORD
	v_add3_u32 v5, v7, v5, s86
	v_add3_u32 v6, v6, v8, s86
	v_and_b32_e32 v5, 0xffff0000, v5
	v_and_b32_e32 v6, 0xffff0000, v6
	v_or_b32_sdwa v5, v5, v3 dst_sel:DWORD dst_unused:UNUSED_PAD src0_sel:DWORD src1_sel:WORD_1
	v_or_b32_sdwa v4, v6, v4 dst_sel:DWORD dst_unused:UNUSED_PAD src0_sel:DWORD src1_sel:WORD_1
	global_store_dwordx2 v[0:1], v[4:5], off offset:224
	v_mov_b32_e32 v4, v80
	v_mov_b32_e32 v5, v82
	v_pk_mul_f32 v[4:5], v[4:5], v[2:3] op_sel_hi:[1,0]
	v_mov_b32_e32 v82, v81
	v_pk_mul_f32 v[6:7], v[82:83], v[2:3] op_sel_hi:[1,0]
	v_and_b32_sdwa v3, v5, v182 dst_sel:DWORD dst_unused:UNUSED_PAD src0_sel:WORD_1 src1_sel:DWORD
	v_and_b32_sdwa v8, v4, v182 dst_sel:DWORD dst_unused:UNUSED_PAD src0_sel:WORD_1 src1_sel:DWORD
	v_add3_u32 v4, v4, v8, s86
	v_add3_u32 v3, v5, v3, s86
	v_and_b32_sdwa v5, v7, v182 dst_sel:DWORD dst_unused:UNUSED_PAD src0_sel:WORD_1 src1_sel:DWORD
	v_and_b32_sdwa v8, v6, v182 dst_sel:DWORD dst_unused:UNUSED_PAD src0_sel:WORD_1 src1_sel:DWORD
	v_add3_u32 v5, v7, v5, s86
	v_add3_u32 v6, v6, v8, s86
	v_and_b32_e32 v5, 0xffff0000, v5
	v_and_b32_e32 v6, 0xffff0000, v6
	v_or_b32_sdwa v5, v5, v3 dst_sel:DWORD dst_unused:UNUSED_PAD src0_sel:DWORD src1_sel:WORD_1
	v_or_b32_sdwa v4, v6, v4 dst_sel:DWORD dst_unused:UNUSED_PAD src0_sel:DWORD src1_sel:WORD_1
	global_store_dwordx2 v[0:1], v[4:5], off offset:256
	v_mov_b32_e32 v4, v84
	v_mov_b32_e32 v5, v86
	v_pk_mul_f32 v[4:5], v[4:5], v[2:3] op_sel_hi:[1,0]
	v_mov_b32_e32 v86, v85
	v_pk_mul_f32 v[6:7], v[86:87], v[2:3] op_sel_hi:[1,0]
	v_and_b32_sdwa v3, v5, v182 dst_sel:DWORD dst_unused:UNUSED_PAD src0_sel:WORD_1 src1_sel:DWORD
	v_and_b32_sdwa v8, v4, v182 dst_sel:DWORD dst_unused:UNUSED_PAD src0_sel:WORD_1 src1_sel:DWORD
	v_add3_u32 v4, v4, v8, s86
	v_add3_u32 v3, v5, v3, s86
	v_and_b32_sdwa v5, v7, v182 dst_sel:DWORD dst_unused:UNUSED_PAD src0_sel:WORD_1 src1_sel:DWORD
	v_and_b32_sdwa v8, v6, v182 dst_sel:DWORD dst_unused:UNUSED_PAD src0_sel:WORD_1 src1_sel:DWORD
	v_add3_u32 v5, v7, v5, s86
	v_add3_u32 v6, v6, v8, s86
	v_and_b32_e32 v5, 0xffff0000, v5
	v_and_b32_e32 v6, 0xffff0000, v6
	v_or_b32_sdwa v5, v5, v3 dst_sel:DWORD dst_unused:UNUSED_PAD src0_sel:DWORD src1_sel:WORD_1
	v_or_b32_sdwa v4, v6, v4 dst_sel:DWORD dst_unused:UNUSED_PAD src0_sel:DWORD src1_sel:WORD_1
	global_store_dwordx2 v[0:1], v[4:5], off offset:288
	v_mov_b32_e32 v4, v88
	v_mov_b32_e32 v5, v90
	v_pk_mul_f32 v[4:5], v[4:5], v[2:3] op_sel_hi:[1,0]
	v_mov_b32_e32 v90, v89
	v_pk_mul_f32 v[6:7], v[90:91], v[2:3] op_sel_hi:[1,0]
	v_and_b32_sdwa v3, v5, v182 dst_sel:DWORD dst_unused:UNUSED_PAD src0_sel:WORD_1 src1_sel:DWORD
	v_and_b32_sdwa v8, v4, v182 dst_sel:DWORD dst_unused:UNUSED_PAD src0_sel:WORD_1 src1_sel:DWORD
	v_add3_u32 v4, v4, v8, s86
	v_add3_u32 v3, v5, v3, s86
	v_and_b32_sdwa v5, v7, v182 dst_sel:DWORD dst_unused:UNUSED_PAD src0_sel:WORD_1 src1_sel:DWORD
	v_and_b32_sdwa v8, v6, v182 dst_sel:DWORD dst_unused:UNUSED_PAD src0_sel:WORD_1 src1_sel:DWORD
	v_add3_u32 v5, v7, v5, s86
	v_add3_u32 v6, v6, v8, s86
	v_and_b32_e32 v5, 0xffff0000, v5
	v_and_b32_e32 v6, 0xffff0000, v6
	v_or_b32_sdwa v5, v5, v3 dst_sel:DWORD dst_unused:UNUSED_PAD src0_sel:DWORD src1_sel:WORD_1
	v_or_b32_sdwa v4, v6, v4 dst_sel:DWORD dst_unused:UNUSED_PAD src0_sel:DWORD src1_sel:WORD_1
	global_store_dwordx2 v[0:1], v[4:5], off offset:320
	v_mov_b32_e32 v4, v92
	v_mov_b32_e32 v5, v94
	v_pk_mul_f32 v[4:5], v[4:5], v[2:3] op_sel_hi:[1,0]
	v_mov_b32_e32 v94, v93
	v_pk_mul_f32 v[6:7], v[94:95], v[2:3] op_sel_hi:[1,0]
	v_and_b32_sdwa v3, v5, v182 dst_sel:DWORD dst_unused:UNUSED_PAD src0_sel:WORD_1 src1_sel:DWORD
	v_and_b32_sdwa v8, v4, v182 dst_sel:DWORD dst_unused:UNUSED_PAD src0_sel:WORD_1 src1_sel:DWORD
	v_add3_u32 v4, v4, v8, s86
	v_add3_u32 v3, v5, v3, s86
	v_and_b32_sdwa v5, v7, v182 dst_sel:DWORD dst_unused:UNUSED_PAD src0_sel:WORD_1 src1_sel:DWORD
; __device__ __forceinline__ unsigned pk2(float lo, float hi) { return f2bf(lo) | (f2bf(hi) << 16); }
; __device__ __forceinline__ void cross_phase(const Ctx& C, const bf16* Q, const bf16* KV  , bf16* O) {
;     ...
;             const float il = 1.0f / l_run;
;             bf16* op = O + (size_t)(b * SEQ + t0 + i) * DM + hd * 256 + 4 * g;
; #pragma unroll
;             for (int dt = 0; dt < DT; ++dt) { v2u w; w.x = pk2(oacc[dt].x * il, oacc[dt].y * il); w.y = pk2(oacc[dt].z * il, oacc[dt].w * il); *(v2u*)(op + 16 * dt) = w; }
;         }
;         __syncthreads();
;     }
	v_and_b32_sdwa v8, v6, v182 dst_sel:DWORD dst_unused:UNUSED_PAD src0_sel:WORD_1 src1_sel:DWORD
	v_add3_u32 v5, v7, v5, s86
	v_add3_u32 v6, v6, v8, s86
	v_and_b32_e32 v5, 0xffff0000, v5
	v_and_b32_e32 v6, 0xffff0000, v6
	v_or_b32_sdwa v5, v5, v3 dst_sel:DWORD dst_unused:UNUSED_PAD src0_sel:DWORD src1_sel:WORD_1
	v_or_b32_sdwa v4, v6, v4 dst_sel:DWORD dst_unused:UNUSED_PAD src0_sel:DWORD src1_sel:WORD_1
	global_store_dwordx2 v[0:1], v[4:5], off offset:352
	v_mov_b32_e32 v4, v52
	v_mov_b32_e32 v5, v54
	v_pk_mul_f32 v[4:5], v[4:5], v[2:3] op_sel_hi:[1,0]
	v_mov_b32_e32 v54, v53
	v_pk_mul_f32 v[6:7], v[54:55], v[2:3] op_sel_hi:[1,0]
	v_and_b32_sdwa v3, v5, v182 dst_sel:DWORD dst_unused:UNUSED_PAD src0_sel:WORD_1 src1_sel:DWORD
	v_and_b32_sdwa v8, v4, v182 dst_sel:DWORD dst_unused:UNUSED_PAD src0_sel:WORD_1 src1_sel:DWORD
	v_add3_u32 v4, v4, v8, s86
	v_add3_u32 v3, v5, v3, s86
	v_and_b32_sdwa v5, v7, v182 dst_sel:DWORD dst_unused:UNUSED_PAD src0_sel:WORD_1 src1_sel:DWORD
	v_and_b32_sdwa v8, v6, v182 dst_sel:DWORD dst_unused:UNUSED_PAD src0_sel:WORD_1 src1_sel:DWORD
	v_add3_u32 v5, v7, v5, s86
	v_add3_u32 v6, v6, v8, s86
	v_and_b32_e32 v5, 0xffff0000, v5
	v_and_b32_e32 v6, 0xffff0000, v6
	v_or_b32_sdwa v5, v5, v3 dst_sel:DWORD dst_unused:UNUSED_PAD src0_sel:DWORD src1_sel:WORD_1
	v_or_b32_sdwa v4, v6, v4 dst_sel:DWORD dst_unused:UNUSED_PAD src0_sel:DWORD src1_sel:WORD_1
	global_store_dwordx2 v[0:1], v[4:5], off offset:384
	v_mov_b32_e32 v4, v56
	v_mov_b32_e32 v5, v58
	v_pk_mul_f32 v[4:5], v[2:3], v[4:5] op_sel_hi:[0,1]
	v_mov_b32_e32 v58, v57
	v_pk_mul_f32 v[6:7], v[2:3], v[58:59] op_sel_hi:[0,1]
	v_and_b32_sdwa v3, v5, v182 dst_sel:DWORD dst_unused:UNUSED_PAD src0_sel:WORD_1 src1_sel:DWORD
	v_and_b32_sdwa v8, v4, v182 dst_sel:DWORD dst_unused:UNUSED_PAD src0_sel:WORD_1 src1_sel:DWORD
	v_add3_u32 v4, v4, v8, s86
	v_add3_u32 v3, v5, v3, s86
	v_and_b32_sdwa v5, v7, v182 dst_sel:DWORD dst_unused:UNUSED_PAD src0_sel:WORD_1 src1_sel:DWORD
	v_and_b32_sdwa v8, v6, v182 dst_sel:DWORD dst_unused:UNUSED_PAD src0_sel:WORD_1 src1_sel:DWORD
	v_add3_u32 v5, v7, v5, s86
	v_add3_u32 v6, v6, v8, s86
	v_and_b32_e32 v5, 0xffff0000, v5
	v_and_b32_e32 v6, 0xffff0000, v6
	v_or_b32_sdwa v5, v5, v3 dst_sel:DWORD dst_unused:UNUSED_PAD src0_sel:DWORD src1_sel:WORD_1
	v_or_b32_sdwa v4, v6, v4 dst_sel:DWORD dst_unused:UNUSED_PAD src0_sel:DWORD src1_sel:WORD_1
	global_store_dwordx2 v[0:1], v[4:5], off offset:416
	v_mov_b32_e32 v4, v60
	v_mov_b32_e32 v5, v62
	v_pk_mul_f32 v[4:5], v[2:3], v[4:5] op_sel_hi:[0,1]
	v_mov_b32_e32 v62, v61
	v_pk_mul_f32 v[6:7], v[2:3], v[62:63] op_sel_hi:[0,1]
	v_and_b32_sdwa v3, v5, v182 dst_sel:DWORD dst_unused:UNUSED_PAD src0_sel:WORD_1 src1_sel:DWORD
	v_and_b32_sdwa v8, v4, v182 dst_sel:DWORD dst_unused:UNUSED_PAD src0_sel:WORD_1 src1_sel:DWORD
	v_add3_u32 v4, v4, v8, s86
	v_add3_u32 v3, v5, v3, s86
	v_and_b32_sdwa v5, v7, v182 dst_sel:DWORD dst_unused:UNUSED_PAD src0_sel:WORD_1 src1_sel:DWORD
	v_and_b32_sdwa v8, v6, v182 dst_sel:DWORD dst_unused:UNUSED_PAD src0_sel:WORD_1 src1_sel:DWORD
	v_add3_u32 v5, v7, v5, s86
	v_add3_u32 v6, v6, v8, s86
	v_and_b32_e32 v5, 0xffff0000, v5
	v_and_b32_e32 v6, 0xffff0000, v6
	v_or_b32_sdwa v5, v5, v3 dst_sel:DWORD dst_unused:UNUSED_PAD src0_sel:DWORD src1_sel:WORD_1
	v_or_b32_sdwa v4, v6, v4 dst_sel:DWORD dst_unused:UNUSED_PAD src0_sel:DWORD src1_sel:WORD_1
	global_store_dwordx2 v[0:1], v[4:5], off offset:448
	v_mov_b32_e32 v4, v64
	v_mov_b32_e32 v5, v66
	v_pk_mul_f32 v[4:5], v[2:3], v[4:5] op_sel_hi:[0,1]
	v_mov_b32_e32 v66, v65
	v_pk_mul_f32 v[2:3], v[2:3], v[66:67] op_sel_hi:[0,1]
	v_and_b32_sdwa v6, v5, v182 dst_sel:DWORD dst_unused:UNUSED_PAD src0_sel:WORD_1 src1_sel:DWORD
	v_and_b32_sdwa v7, v4, v182 dst_sel:DWORD dst_unused:UNUSED_PAD src0_sel:WORD_1 src1_sel:DWORD
	v_add3_u32 v4, v4, v7, s86
	v_add3_u32 v5, v5, v6, s86
	v_and_b32_sdwa v6, v3, v182 dst_sel:DWORD dst_unused:UNUSED_PAD src0_sel:WORD_1 src1_sel:DWORD
	v_and_b32_sdwa v7, v2, v182 dst_sel:DWORD dst_unused:UNUSED_PAD src0_sel:WORD_1 src1_sel:DWORD
	v_add3_u32 v3, v3, v6, s86
	v_add3_u32 v2, v2, v7, s86
	v_and_b32_e32 v3, 0xffff0000, v3
	v_and_b32_e32 v2, 0xffff0000, v2
	v_or_b32_sdwa v3, v3, v5 dst_sel:DWORD dst_unused:UNUSED_PAD src0_sel:DWORD src1_sel:WORD_1
	v_or_b32_sdwa v2, v2, v4 dst_sel:DWORD dst_unused:UNUSED_PAD src0_sel:DWORD src1_sel:WORD_1
	global_store_dwordx2 v[0:1], v[2:3], off offset:480
	s_cbranch_scc0 .LBB0_292
	s_add_i32 s10, s10, s96
	s_add_i32 s2, s2, s83
	s_cmpk_gt_i32 s10, 0xff
	s_barrier
	s_cbranch_scc0 .LBB0_291

; __device__ __forceinline__ void ret_out_phase(const Ctx& C, const bf16* PROJ, const bf16* ST, bf16* MIX, const float* decay_logit, const float* ret_gain) {
;     ...
;     for (int wt = C.gw; wt < NB * 8 * 128; wt += C.ngw) {
;         const int b = wt >> 10, h = (wt >> 7) & 7, t0 = (wt & 127) * 16, n = t0 >> 7, c = (t0 & 127) + i;
;         const bf16* base = PROJ + (size_t)b * SEQ * INW + h * 64;
;         const float zf = decay_logit[h], zb = decay_logit[8 + h];
;         const float lgf = -log1pf(expf(-zf)) * LOG2E, lgb = -log1pf(expf(-zb)) * LOG2E;
;         RetSpec sp{base, base + 512, base + 1024, t0, n * 128, lgf, lgb};
.LBB0_300:
	s_ashr_i32 s11, s7, 10
	s_bfe_u32 s8, s7, 0x30007
	s_and_b32 s10, s6, 0x7f0
	s_bfe_u32 s12, s6, 0x40007
	s_and_b32 s0, s6, 0x70
	s_ashr_i32 s9, s11, 31
	s_mul_i32 s1, s11, 0xe00000
	v_or_b32_e32 v101, s0, v72
	s_mul_hi_i32 s0, s11, 0xe00000
	s_add_u32 s1, s20, s1
	s_addc_u32 s13, s21, s0
	s_lshl_b32 s2, s8, 7
	s_add_u32 s0, s1, s2
	s_addc_u32 s1, s13, 0
	s_lshl_b32 s13, s8, 2
	v_mov_b32_e32 v0, s13
	global_load_dword v1, v0, s[4:5]
	global_load_dword v16, v0, s[4:5] offset:32
	s_and_b32 s13, s6, 0x780
	v_or_b32_e32 v42, s10, v72
	v_mul_u32_u24_e32 v136, 0x1c00, v42
	s_mov_b32 s14, 0x1c000
	v_mov_b64_e32 v[68:69], s[0:1]
	v_add_u32_e32 v20, s13, v92
	v_add_u32_e32 v24, s13, v93
	v_add_u32_e32 v28, s13, v94
	s_add_i32 s7, s7, s98
	s_add_i32 s6, s6, s83
	s_waitcnt vmcnt(0)
	v_mul_f32_e32 v0, 0xbfb8aa3b, v1
	v_fma_f32 v2, v1, s22, -v0
	v_rndne_f32_e32 v3, v0
	v_fmac_f32_e32 v2, 0xb2a5705f, v1
	v_sub_f32_e32 v0, v0, v3
	v_add_f32_e32 v0, v0, v2
	v_exp_f32_e32 v0, v0
	v_cvt_i32_f32_e32 v2, v3
	v_cmp_nlt_f32_e32 vcc, s23, v1
	v_ldexp_f32 v0, v0, v2
	s_nop 0
	v_cndmask_b32_e32 v0, 0, v0, vcc
	v_cmp_ngt_f32_e32 vcc, s24, v1
	s_nop 1
	v_cndmask_b32_e32 v17, v185, v0, vcc
	v_add_f32_e32 v2, 1.0, v17
	v_add_f32_e32 v0, -1.0, v2
	v_sub_f32_e32 v1, v0, v2
	v_add_f32_e32 v1, 1.0, v1
	v_sub_f32_e32 v0, v17, v0
	v_add_f32_e32 v3, v0, v1
	v_frexp_mant_f32_e32 v0, v2
	v_cmp_gt_f32_e32 vcc, s26, v0
	v_cvt_f64_f32_e32 v[0:1], v2
	v_frexp_exp_i32_f64_e32 v0, v[0:1]
	v_subbrev_co_u32_e32 v8, vcc, 0, v0, vcc
	v_sub_u32_e32 v0, 0, v8
	v_ldexp_f32 v1, v2, v0
	v_add_f32_e32 v2, -1.0, v1
	v_add_f32_e32 v4, 1.0, v1
	v_ldexp_f32 v0, v3, v0
	v_add_f32_e32 v3, 1.0, v2
	v_add_f32_e32 v5, -1.0, v4
	v_sub_f32_e32 v3, v1, v3
	v_sub_f32_e32 v1, v1, v5
	v_add_f32_e32 v3, v0, v3
	v_add_f32_e32 v0, v0, v1
	v_add_f32_e32 v9, v4, v0
	v_rcp_f32_e32 v11, v9
	v_sub_f32_e32 v1, v4, v9
	v_add_f32_e32 v10, v0, v1
	v_add_f32_e32 v1, v2, v3
	v_mul_f32_e32 v13, v1, v11
	v_sub_f32_e32 v0, v2, v1
	v_mul_f32_e32 v2, v9, v13
	v_fma_f32 v4, v13, v9, -v2
	v_fmac_f32_e32 v4, v13, v10
	v_add_f32_e32 v12, v3, v0
	v_add_f32_e32 v0, v2, v4
	v_sub_f32_e32 v3, v1, v0
	v_pk_add_f32 v[6:7], v[0:1], v[2:3] neg_lo:[0,1] neg_hi:[0,1]
	v_mov_b32_e32 v5, v0
	v_pk_add_f32 v[0:1], v[6:7], v[4:5] neg_lo:[0,1] neg_hi:[0,1]
	v_cmp_neq_f32_e32 vcc, s25, v17
	v_add_f32_e32 v1, v12, v1
	v_add_f32_e32 v0, v0, v1
	v_add_f32_e32 v1, v3, v0
	v_mul_f32_e32 v12, v11, v1
	v_mul_f32_e32 v2, v9, v12
	v_fma_f32 v4, v12, v9, -v2
	v_fmac_f32_e32 v4, v12, v10
	v_sub_f32_e32 v3, v3, v1
	v_add_f32_e32 v9, v0, v3
	v_add_f32_e32 v0, v2, v4
	v_sub_f32_e32 v3, v1, v0
	v_pk_add_f32 v[6:7], v[0:1], v[2:3] neg_lo:[0,1] neg_hi:[0,1]
	v_mov_b32_e32 v5, v0
	v_pk_add_f32 v[0:1], v[6:7], v[4:5] neg_lo:[0,1] neg_hi:[0,1]
	s_nop 0
	v_add_f32_e32 v1, v9, v1
	v_add_f32_e32 v0, v0, v1
	v_add_f32_e32 v1, v13, v12
	v_add_f32_e32 v0, v3, v0
	v_sub_f32_e32 v2, v1, v13
	v_mul_f32_e32 v0, v11, v0
	v_sub_f32_e32 v2, v12, v2
	v_add_f32_e32 v2, v2, v0
	v_add_f32_e32 v4, v1, v2
	v_mul_f32_e32 v5, v4, v4
	v_fmamk_f32 v0, v5, 0x3e9b6dac, v180
	v_fmaak_f32 v139, v5, v0, 0x3f2aaada
	v_cvt_f32_i32_e32 v0, v8
	v_sub_f32_e32 v1, v4, v1
	v_sub_f32_e32 v1, v2, v1
	v_ldexp_f32 v6, v1, 1
	v_mul_f32_e32 v1, v4, v5
	v_ldexp_f32 v3, v4, 1
	v_pk_mul_f32 v[4:5], v[0:1], v[138:139]
	s_nop 0
	v_fma_f32 v2, v0, s27, -v4
	v_fmac_f32_e32 v2, 0xb102e308, v0
	v_pk_add_f32 v[0:1], v[4:5], v[2:3]
	s_nop 0
	v_sub_f32_e32 v3, v1, v3
	v_sub_f32_e32 v3, v5, v3
	v_add_f32_e32 v7, v6, v3
	v_mov_b32_e32 v6, v4
	v_pk_add_f32 v[4:5], v[0:1], v[4:5] neg_lo:[0,1] neg_hi:[0,1]
	v_pk_add_f32 v[8:9], v[0:1], v[6:7]
	v_mov_b32_e32 v3, v0
	v_mov_b32_e32 v5, v9
	v_pk_add_f32 v[10:11], v[2:3], v[4:5] neg_lo:[0,1] neg_hi:[0,1]
	v_pk_add_f32 v[2:3], v[2:3], v[4:5]
	v_mov_b32_e32 v14, v1
	v_pk_add_f32 v[4:5], v[2:3], v[0:1] op_sel:[1,0] op_sel_hi:[0,1] neg_lo:[0,1] neg_hi:[0,1]
	v_pk_add_f32 v[12:13], v[8:9], v[4:5] op_sel_hi:[1,0] neg_lo:[0,1] neg_hi:[0,1]
	v_mov_b32_e32 v8, v9
	v_mov_b32_e32 v9, v3
	v_mov_b32_e32 v15, v4
	v_pk_add_f32 v[4:5], v[8:9], v[14:15] neg_lo:[0,1] neg_hi:[0,1]
	v_mov_b32_e32 v6, v7
	v_mov_b32_e32 v7, v0
	v_pk_add_f32 v[0:1], v[6:7], v[4:5] neg_lo:[0,1] neg_hi:[0,1]
	v_mov_b32_e32 v12, v10
	v_pk_add_f32 v[4:5], v[12:13], v[0:1]
	v_mov_b32_e32 v11, v3
	v_pk_add_f32 v[6:7], v[4:5], v[4:5] op_sel:[0,1] op_sel_hi:[1,0]
	s_nop 0
	v_pk_add_f32 v[2:3], v[2:3], v[6:7] op_sel:[1,0] op_sel_hi:[0,1]
	v_mov_b32_e32 v5, v2
	v_pk_add_f32 v[8:9], v[4:5], v[10:11] neg_lo:[0,1] neg_hi:[0,1]
	v_mov_b32_e32 v1, v6
	v_sub_f32_e32 v3, v4, v8
	v_pk_add_f32 v[0:1], v[0:1], v[8:9] neg_lo:[0,1] neg_hi:[0,1]
	v_sub_f32_e32 v3, v10, v3
	v_add_f32_e32 v0, v0, v3
	v_add_f32_e32 v0, v0, v1
	v_add_f32_e32 v0, v2, v0
	v_cndmask_b32_e32 v0, v185, v0, vcc
	v_cmp_lt_f32_e64 vcc, |v17|, s28
	s_nop 1
	v_cndmask_b32_e32 v0, v0, v17, vcc
	v_mul_f32_e32 v102, 0xbfb8aa3b, v0
	v_mul_f32_e32 v0, 0xbfb8aa3b, v16
	v_fma_f32 v1, v16, s22, -v0
	v_rndne_f32_e32 v2, v0
	v_fmac_f32_e32 v1, 0xb2a5705f, v16
	v_sub_f32_e32 v0, v0, v2
	v_add_f32_e32 v0, v0, v1
	v_exp_f32_e32 v0, v0
	v_cvt_i32_f32_e32 v1, v2
	v_cmp_nlt_f32_e32 vcc, s23, v16
	v_ldexp_f32 v0, v0, v1
	s_nop 0
	v_cndmask_b32_e32 v0, 0, v0, vcc
	v_cmp_ngt_f32_e32 vcc, s24, v16
	s_nop 1
	v_cndmask_b32_e32 v16, v185, v0, vcc
	v_add_f32_e32 v2, 1.0, v16
	v_add_f32_e32 v0, -1.0, v2
	v_sub_f32_e32 v1, v0, v2
	v_add_f32_e32 v1, 1.0, v1
	v_sub_f32_e32 v0, v16, v0
	v_add_f32_e32 v3, v0, v1
	v_frexp_mant_f32_e32 v0, v2
	v_cmp_gt_f32_e32 vcc, s26, v0
	v_cvt_f64_f32_e32 v[0:1], v2
	v_frexp_exp_i32_f64_e32 v0, v[0:1]
	v_subbrev_co_u32_e32 v8, vcc, 0, v0, vcc
; #define LAS __attribute__((address_space(3)))
; template <int DH, bool SOFTMAX, bool PREFETCH, class Spec>
; __device__ __forceinline__ void wave_attn(const Spec& sp, int nch, LAS bf16* vl, int lane, f32x4 (&oacc)[DH / 16], float& m_run, float& l_run) {
;     ...
;         WA_LOAD(0);
;         for (int c = 0; c < nch; ++c) {
;             bf16x8 kf[2][KS];
; #pragma unroll
;             for (int kt = 0; kt < 2; ++kt)
; #pragma unroll
;                 for (int ks = 0; ks < KS; ++ks) kf[kt][ks] = kn[kt][ks];
; #pragma unroll
;             for (int r = 0; r < NP; ++r) { const int p = lane + 64 * r, key = p / PPR, pc = p % PPR; *(LAS v4u*)(vl + key * P + pc * 8) = vn[r]; }
;             if (c + 1 < nch) WA_LOAD(c + 1);
;             f32x4 st[2];
; #pragma unroll
;             for (int kt = 0; kt < 2; ++kt) { st[kt] = (f32x4){0.f, 0.f, 0.f, 0.f};
; #pragma unroll
;                 for (int ks = 0; ks < KS; ++ks) st[kt] = __builtin_amdgcn_mfma_f32_16x16x32_bf16(kf[kt][ks], qf[ks], st[kt], 0, 0, 0); }
; __device__ __forceinline__ void ret_out_phase(const Ctx& C, const bf16* PROJ, const bf16* ST, bf16* MIX, const float* decay_logit, const float* ret_gain) {
;     ...
;         const float lgf = -log1pf(expf(-zf)) * LOG2E, lgb = -log1pf(expf(-zb)) * LOG2E;
;         RetSpec sp{base, base + 512, base + 1024, t0, n * 128, lgf, lgb};
;         f32x4 o[4]; float m, l;
;         wave_attn<64, false, true>(sp, 4, vl, lane, o, m, l);
	v_sub_u32_e32 v0, 0, v8
	v_ldexp_f32 v1, v2, v0
	v_add_f32_e32 v2, -1.0, v1
	v_add_f32_e32 v4, 1.0, v1
	v_ldexp_f32 v0, v3, v0
	v_add_f32_e32 v3, 1.0, v2
	v_add_f32_e32 v5, -1.0, v4
	v_sub_f32_e32 v3, v1, v3
	v_sub_f32_e32 v1, v1, v5
	v_add_f32_e32 v3, v0, v3
	v_add_f32_e32 v0, v0, v1
	v_add_f32_e32 v9, v4, v0
	v_rcp_f32_e32 v11, v9
	v_sub_f32_e32 v1, v4, v9
	v_add_f32_e32 v10, v0, v1
	v_add_f32_e32 v1, v2, v3
	v_mul_f32_e32 v13, v1, v11
	v_sub_f32_e32 v0, v2, v1
	v_mul_f32_e32 v2, v9, v13
	v_fma_f32 v4, v13, v9, -v2
	v_fmac_f32_e32 v4, v13, v10
	v_add_f32_e32 v12, v3, v0
	v_add_f32_e32 v0, v2, v4
	v_sub_f32_e32 v3, v1, v0
	v_pk_add_f32 v[6:7], v[0:1], v[2:3] neg_lo:[0,1] neg_hi:[0,1]
	v_mov_b32_e32 v5, v0
	v_pk_add_f32 v[0:1], v[6:7], v[4:5] neg_lo:[0,1] neg_hi:[0,1]
	v_cmp_neq_f32_e32 vcc, s25, v16
	v_add_f32_e32 v1, v12, v1
	v_add_f32_e32 v0, v0, v1
	v_add_f32_e32 v1, v3, v0
	v_mul_f32_e32 v12, v11, v1
	v_mul_f32_e32 v2, v9, v12
	v_fma_f32 v4, v12, v9, -v2
	v_fmac_f32_e32 v4, v12, v10
	v_sub_f32_e32 v3, v3, v1
	v_add_f32_e32 v9, v0, v3
	v_add_f32_e32 v0, v2, v4
	v_sub_f32_e32 v3, v1, v0
	v_pk_add_f32 v[6:7], v[0:1], v[2:3] neg_lo:[0,1] neg_hi:[0,1]
	v_mov_b32_e32 v5, v0
	v_pk_add_f32 v[0:1], v[6:7], v[4:5] neg_lo:[0,1] neg_hi:[0,1]
	s_nop 0
	v_add_f32_e32 v1, v9, v1
	v_add_f32_e32 v0, v0, v1
	v_add_f32_e32 v1, v13, v12
	v_add_f32_e32 v0, v3, v0
	v_sub_f32_e32 v2, v1, v13
	v_mul_f32_e32 v0, v11, v0
	v_sub_f32_e32 v2, v12, v2
	v_add_f32_e32 v2, v2, v0
	v_add_f32_e32 v4, v1, v2
	v_mul_f32_e32 v5, v4, v4
	v_fmamk_f32 v0, v5, 0x3e9b6dac, v180
	v_fmaak_f32 v139, v5, v0, 0x3f2aaada
	v_cvt_f32_i32_e32 v0, v8
	v_sub_f32_e32 v1, v4, v1
	v_sub_f32_e32 v1, v2, v1
	v_ldexp_f32 v6, v1, 1
	v_mul_f32_e32 v1, v4, v5
	v_ldexp_f32 v3, v4, 1
	v_pk_mul_f32 v[4:5], v[0:1], v[138:139]
	s_nop 0
	v_fma_f32 v2, v0, s27, -v4
	v_fmac_f32_e32 v2, 0xb102e308, v0
	v_pk_add_f32 v[0:1], v[4:5], v[2:3]
	s_nop 0
	v_sub_f32_e32 v3, v1, v3
	v_sub_f32_e32 v3, v5, v3
	v_add_f32_e32 v7, v6, v3
	v_mov_b32_e32 v6, v4
	v_pk_add_f32 v[4:5], v[0:1], v[4:5] neg_lo:[0,1] neg_hi:[0,1]
	v_pk_add_f32 v[8:9], v[0:1], v[6:7]
	v_mov_b32_e32 v3, v0
	v_mov_b32_e32 v5, v9
	v_pk_add_f32 v[10:11], v[2:3], v[4:5] neg_lo:[0,1] neg_hi:[0,1]
	v_pk_add_f32 v[2:3], v[2:3], v[4:5]
	v_mov_b32_e32 v14, v1
	v_pk_add_f32 v[4:5], v[2:3], v[0:1] op_sel:[1,0] op_sel_hi:[0,1] neg_lo:[0,1] neg_hi:[0,1]
	v_pk_add_f32 v[12:13], v[8:9], v[4:5] op_sel_hi:[1,0] neg_lo:[0,1] neg_hi:[0,1]
	v_mov_b32_e32 v8, v9
	v_mov_b32_e32 v9, v3
	v_mov_b32_e32 v15, v4
	v_pk_add_f32 v[4:5], v[8:9], v[14:15] neg_lo:[0,1] neg_hi:[0,1]
	v_mov_b32_e32 v6, v7
	v_mov_b32_e32 v7, v0
	v_pk_add_f32 v[0:1], v[6:7], v[4:5] neg_lo:[0,1] neg_hi:[0,1]
	v_mov_b32_e32 v12, v10
	v_pk_add_f32 v[4:5], v[12:13], v[0:1]
	v_mov_b32_e32 v11, v3
	v_pk_add_f32 v[6:7], v[4:5], v[4:5] op_sel:[0,1] op_sel_hi:[1,0]
	s_nop 0
	v_pk_add_f32 v[2:3], v[2:3], v[6:7] op_sel:[1,0] op_sel_hi:[0,1]
	v_mov_b32_e32 v5, v2
	v_pk_add_f32 v[8:9], v[4:5], v[10:11] neg_lo:[0,1] neg_hi:[0,1]
	v_mov_b32_e32 v1, v6
	v_sub_f32_e32 v3, v4, v8
	v_pk_add_f32 v[0:1], v[0:1], v[8:9] neg_lo:[0,1] neg_hi:[0,1]
	v_sub_f32_e32 v3, v10, v3
	v_add_f32_e32 v0, v0, v3
	v_add_f32_e32 v0, v0, v1
	v_add_f32_e32 v0, v2, v0
	v_cndmask_b32_e32 v0, v185, v0, vcc
	v_cmp_lt_f32_e64 vcc, |v16|, s28
	v_or_b32_e32 v10, s13, v72
	v_lshl_add_u64 v[8:9], s[0:1], 0, v[80:81]
	v_cndmask_b32_e32 v0, v0, v16, vcc
	v_mul_f32_e32 v103, 0xbfb8aa3b, v0
	v_lshl_add_u64 v[0:1], s[0:1], 0, v[136:137]
	v_mul_u32_u24_e32 v136, 0x1c00, v10
	v_lshl_add_u64 v[90:91], v[0:1], 0, v[80:81]
	v_lshl_add_u64 v[56:57], v[8:9], 0, v[136:137]
	global_load_dwordx4 v[0:3], v[90:91], off
	global_load_dwordx4 v[4:7], v[90:91], off offset:64
	global_load_dwordx4 v[8:11], v[56:57], off offset:1024
	global_load_dwordx4 v[12:15], v[56:57], off offset:1088
	v_add_co_u32_e32 v16, vcc, s14, v56
	v_mad_i64_i32 v[20:21], s[0:1], v20, s90, v[68:69]
	s_nop 0
	v_addc_co_u32_e32 v17, vcc, 0, v57, vcc
	global_load_dwordx4 v[32:35], v[16:17], off offset:1024
	global_load_dwordx4 v[36:39], v[16:17], off offset:1088
	v_add_u32_e32 v16, s13, v73
	v_mad_i64_i32 v[16:17], s[0:1], v16, s90, v[68:69]
	v_lshl_add_u64 v[16:17], v[16:17], 0, v[82:83]
	global_load_dwordx4 v[16:19], v[16:17], off offset:2048
	v_lshl_add_u64 v[20:21], v[20:21], 0, v[84:85]
	v_mad_i64_i32 v[24:25], s[0:1], v24, s90, v[68:69]
	global_load_dwordx4 v[20:23], v[20:21], off offset:2048
	v_lshl_add_u64 v[24:25], v[24:25], 0, v[86:87]
	v_mad_i64_i32 v[28:29], s[0:1], v28, s90, v[68:69]
	global_load_dwordx4 v[24:27], v[24:25], off offset:2048
	v_lshl_add_u64 v[28:29], v[28:29], 0, v[88:89]
	global_load_dwordx4 v[28:31], v[28:29], off offset:2048
	s_waitcnt vmcnt(7)
	v_mfma_f32_16x16x32_bf16 v[8:11], v[8:11], v[0:3], 0
	s_waitcnt vmcnt(3)
	ds_write_b128 v97, v[16:19]
	s_waitcnt vmcnt(2)
	ds_write_b128 v98, v[20:23]
	s_waitcnt vmcnt(1)
	ds_write_b128 v99, v[24:27]
	s_waitcnt vmcnt(0)
; template <int DH, bool SOFTMAX, bool PREFETCH, class Spec>
; __device__ __forceinline__ void wave_attn(const Spec& sp, int nch, LAS bf16* vl, int lane, f32x4 (&oacc)[DH / 16], float& m_run, float& l_run) {
;     ...
;             for (int r = 0; r < NP; ++r) { const int p = lane + 64 * r, key = p / PPR, pc = p % PPR; *(LAS v4u*)(vl + key * P + pc * 8) = vn[r]; }
;             if (c + 1 < nch) WA_LOAD(c + 1);
;             f32x4 st[2];
; #pragma unroll
;             for (int kt = 0; kt < 2; ++kt) { st[kt] = (f32x4){0.f, 0.f, 0.f, 0.f};
; #pragma unroll
;                 for (int ks = 0; ks < KS; ++ks) st[kt] = __builtin_amdgcn_mfma_f32_16x16x32_bf16(kf[kt][ks], qf[ks], st[kt], 0, 0, 0); }
;             float pv[8];
; #pragma unroll
;             for (int kt = 0; kt < 2; ++kt)
; #pragma unroll
;                 for (int j = 0; j < 4; ++j) pv[kt * 4 + j] = sp.score(st[kt][j], i, 32 * c + 16 * kt + 4 * g + j);
;             if constexpr (SOFTMAX) {
;                 float cm = pv[0];
; #pragma unroll
;                 for (int r = 1; r < 8; ++r) cm = fmaxf(cm, pv[r]);
;                 cm = fmaxf(cm, __shfl_xor(cm, 16)); cm = fmaxf(cm, __shfl_xor(cm, 32));
;                 const float mn = fmaxf(m_run, cm), sc = exp2f(m_run - mn);
;                 float ls = 0.f;
; #pragma unroll
;                 for (int r = 0; r < 8; ++r) { pv[r] = exp2f(pv[r] - mn); ls += pv[r]; }
;                 ls += __shfl_xor(ls, 16); ls += __shfl_xor(ls, 32);
;                 l_run = l_run * sc + ls; m_run = mn;
; #pragma unroll
;                 for (int dt = 0; dt < DT; ++dt) oacc[dt] = oacc[dt] * sc;
;             }
;             bf16x8 pb; { v4u t; t.x = pk2(pv[0], pv[1]); t.y = pk2(pv[2], pv[3]); t.z = pk2(pv[4], pv[5]); t.w = pk2(pv[6], pv[7]); pb = __builtin_bit_cast(bf16x8, t); }
;             if constexpr (USE_TR) {
; #pragma unroll
;                 for (int d4 = 0; d4 < DT; d4 += 4) { bf16x8 vf4[4]; read_vfrags4_trp<P>(vl + 16 * d4, i, g, vf4);
; #pragma unroll
;                     for (int dt = 0; dt < 4; ++dt) oacc[d4 + dt] = __builtin_amdgcn_mfma_f32_16x16x32_bf16(vf4[dt], pb, oacc[d4 + dt], 0, 0, 0); }
;     __device__ __forceinline__ float score(float s, int i, int j) const {
;         const int rel = (t0 + i) - (kofs + j); const float e = rel >= 0 ? lgf * (float)rel : lgb * (float)(-rel);
;         return s * 0.125f * exp2f(e);
;     }
	ds_write_b128 v100, v[28:31]
	v_mfma_f32_16x16x32_bf16 v[8:11], v[12:15], v[4:7], v[8:11]
	v_add_co_u32_e32 v20, vcc, s53, v56
	s_mov_b32 s0, 0x54000
	v_mfma_f32_16x16x32_bf16 v[12:15], v[32:35], v[0:3], 0
	v_add_u32_e32 v35, s13, v74
	v_sub_u32_e32 v104, v42, v35
	v_sub_u32_e32 v32, 0, v104
	v_addc_co_u32_e32 v21, vcc, 0, v57, vcc
	v_max_i32_e32 v32, v104, v32
	v_add_co_u32_e32 v28, vcc, s0, v56
	v_cvt_f32_u32_e32 v32, v32
	s_nop 0
	v_addc_co_u32_e32 v29, vcc, 0, v57, vcc
	v_cmp_gt_i32_e32 vcc, 0, v104
	v_mfma_f32_16x16x32_bf16 v[12:15], v[36:39], v[4:7], v[12:15]
	global_load_dwordx4 v[16:19], v[20:21], off offset:1024
	s_nop 0
	global_load_dwordx4 v[20:23], v[20:21], off offset:1088
	v_cndmask_b32_e32 v33, v102, v103, vcc
	v_mul_f32_e32 v34, v33, v32
	global_load_dwordx4 v[24:27], v[28:29], off offset:1024
	s_nop 0
	global_load_dwordx4 v[28:31], v[28:29], off offset:1088
	v_exp_f32_e32 v32, v34
	s_or_b32 s14, s13, 32
	v_add_u32_e32 v40, s14, v94
	v_xad_u32 v33, v35, -1, v42
	v_sub_u32_e32 v34, 0, v33
	v_max_i32_e32 v34, v33, v34
	v_cvt_f32_u32_e32 v34, v34
	v_cmp_gt_i32_e32 vcc, 0, v33
	v_mad_i64_i32 v[40:41], s[0:1], v40, s90, v[68:69]
	s_nop 0
	v_cndmask_b32_e32 v33, v102, v103, vcc
	v_mul_f32_e32 v36, v33, v34
	v_lshl_add_u64 v[40:41], v[40:41], 0, v[88:89]
	global_load_dwordx4 v[58:61], v[40:41], off offset:2048
	v_exp_f32_e32 v33, v36
	v_add_u32_e32 v40, s14, v93
	v_mad_i64_i32 v[40:41], s[0:1], v40, s90, v[68:69]
	v_mov_b32_e32 v34, v33
	v_or_b32_e32 v33, 2, v35
	v_sub_u32_e32 v33, v42, v33
	v_sub_u32_e32 v36, 0, v33
	v_max_i32_e32 v36, v33, v36
	v_cvt_f32_u32_e32 v36, v36
	v_cmp_gt_i32_e32 vcc, 0, v33
	v_or_b32_e32 v35, 3, v35
	v_sub_u32_e32 v35, v42, v35
	v_cndmask_b32_e32 v33, v102, v103, vcc
	v_mul_f32_e32 v37, v33, v36
	v_lshl_add_u64 v[40:41], v[40:41], 0, v[86:87]
	global_load_dwordx4 v[62:65], v[40:41], off offset:2048
	v_exp_f32_e32 v33, v37
	v_cmp_gt_i32_e32 vcc, 0, v35
	v_add_u32_e32 v40, s14, v92
	v_sub_u32_e32 v36, 0, v35
	v_max_i32_e32 v36, v35, v36
	v_cvt_f32_u32_e32 v36, v36
	v_cndmask_b32_e32 v35, v102, v103, vcc
	v_mad_i64_i32 v[40:41], s[0:1], v40, s90, v[68:69]
	v_mul_f32_e32 v37, v35, v36
	v_lshl_add_u64 v[40:41], v[40:41], 0, v[84:85]
	global_load_dwordx4 v[106:109], v[40:41], off offset:2048
	v_exp_f32_e32 v35, v37
	v_sub_u32_e32 v37, 16, v104
	v_cmp_gt_i32_e32 vcc, 16, v104
	v_add_u32_e32 v36, -16, v104
	v_max_i32_e32 v36, v36, v37
	v_cvt_f32_u32_e32 v36, v36
	v_cndmask_b32_e32 v37, v102, v103, vcc
	v_add_u32_e32 v40, s14, v73
	v_mad_i64_i32 v[40:41], s[0:1], v40, s90, v[68:69]
	v_mul_f32_e32 v38, v37, v36
	v_lshl_add_u64 v[40:41], v[40:41], 0, v[82:83]
	global_load_dwordx4 v[110:113], v[40:41], off offset:2048
	v_exp_f32_e32 v36, v38
	v_sub_u32_e32 v38, 17, v104
	v_cmp_gt_i32_e32 vcc, 17, v104
	v_subrev_u32_e32 v37, 17, v104
	v_max_i32_e32 v37, v37, v38
	v_cvt_f32_u32_e32 v37, v37
	v_cndmask_b32_e32 v38, v102, v103, vcc
	s_waitcnt vmcnt(7)
	v_mfma_f32_16x16x32_bf16 v[16:19], v[16:19], v[0:3], 0
	s_mov_b32 s0, 0x8c000
	v_mul_f32_e32 v39, v38, v37
	s_waitcnt vmcnt(6)
	v_mfma_f32_16x16x32_bf16 v[16:19], v[20:23], v[4:7], v[16:19]
	s_or_b32 s14, s13, 64
	v_exp_f32_e32 v37, v39
	v_sub_u32_e32 v39, 18, v104
	v_cmp_gt_i32_e32 vcc, 18, v104
	v_mov_b32_e32 v38, v37
	v_subrev_u32_e32 v37, 18, v104
	v_max_i32_e32 v37, v37, v39
	v_cvt_f32_u32_e32 v37, v37
	v_cndmask_b32_e32 v39, v102, v103, vcc
	s_waitcnt vmcnt(5)
	v_mfma_f32_16x16x32_bf16 v[20:23], v[24:27], v[0:3], 0
	v_subrev_u32_e32 v24, 32, v104
	v_mul_f32_e32 v40, v39, v37
	v_sub_u32_e32 v25, 32, v104
	v_max_i32_e32 v24, v24, v25
	v_exp_f32_e32 v37, v40
	v_sub_u32_e32 v40, 19, v104
	v_cmp_gt_i32_e32 vcc, 19, v104
	v_subrev_u32_e32 v39, 19, v104
	v_max_i32_e32 v39, v39, v40
	v_cvt_f32_u32_e32 v39, v39
	v_cndmask_b32_e32 v40, v102, v103, vcc
	v_cvt_f32_u32_e32 v24, v24
	s_waitcnt vmcnt(4)
	v_mfma_f32_16x16x32_bf16 v[20:23], v[28:31], v[4:7], v[20:23]
	v_mul_f32_e32 v41, v40, v39
	v_add_u32_e32 v66, s14, v92
	s_or_b32 s13, s13, 0x60
	v_exp_f32_e32 v39, v41
	v_mov_b32_e32 v41, v10
	v_mov_b32_e32 v10, v9
	v_mov_b32_e32 v40, v8
	v_pk_mul_f32 v[8:9], v[10:11], s[76:77] op_sel_hi:[1,0]
	v_mov_b32_e32 v11, v14
	v_mov_b32_e32 v14, v13
	v_mov_b32_e32 v10, v12
	v_pk_mul_f32 v[12:13], v[14:15], s[76:77] op_sel_hi:[1,0]
	v_pk_mul_f32 v[40:41], v[40:41], s[76:77] op_sel_hi:[1,0]
	v_pk_mul_f32 v[8:9], v[8:9], v[34:35]
	v_pk_mul_f32 v[10:11], v[10:11], s[76:77] op_sel_hi:[1,0]
	v_pk_mul_f32 v[12:13], v[12:13], v[38:39]
	v_pk_mul_f32 v[32:33], v[40:41], v[32:33]
	v_pk_mul_f32 v[10:11], v[10:11], v[36:37]
	v_bfe_u32 v14, v13, 16, 1
	v_bfe_u32 v15, v12, 16, 1
	v_bfe_u32 v34, v9, 16, 1
	v_bfe_u32 v35, v8, 16, 1
	v_add3_u32 v8, v8, v35, s86
	v_add3_u32 v9, v9, v34, s86
	v_add3_u32 v12, v12, v15, s86
	v_add3_u32 v13, v13, v14, s86
	v_bfe_u32 v14, v32, 16, 1
	v_bfe_u32 v15, v33, 16, 1
	v_bfe_u32 v34, v10, 16, 1
	v_bfe_u32 v35, v11, 16, 1
	v_add3_u32 v11, v11, v35, s86
	v_add3_u32 v10, v10, v34, s86
	v_add3_u32 v15, v33, v15, s86
	v_add3_u32 v14, v32, v14, s86
	v_lshrrev_b32_e32 v14, 16, v14
	v_lshrrev_b32_e32 v15, 16, v15
	v_lshrrev_b32_e32 v10, 16, v10
	v_lshrrev_b32_e32 v11, 16, v11
	v_and_or_b32 v11, v13, s85, v11
	v_and_or_b32 v10, v12, s85, v10
	v_and_or_b32 v9, v9, s85, v15
	v_and_or_b32 v8, v8, s85, v14
	ds_read_b64_tr_b16 v[40:41], v95
	ds_read_b64_tr_b16 v[36:37], v95 offset:32
	ds_read_b64_tr_b16 v[32:33], v95 offset:64
	ds_read_b64_tr_b16 v[12:13], v95 offset:96
	ds_read_b64_tr_b16 v[42:43], v96
	ds_read_b64_tr_b16 v[38:39], v96 offset:32
	ds_read_b64_tr_b16 v[34:35], v96 offset:64
	ds_read_b64_tr_b16 v[14:15], v96 offset:96
	s_waitcnt lgkmcnt(0)
	s_waitcnt vmcnt(0)
; template <int DH, bool SOFTMAX, bool PREFETCH, class Spec>
; __device__ __forceinline__ void wave_attn(const Spec& sp, int nch, LAS bf16* vl, int lane, f32x4 (&oacc)[DH / 16], float& m_run, float& l_run) {
;     ...
;             for (int r = 0; r < NP; ++r) { const int p = lane + 64 * r, key = p / PPR, pc = p % PPR; *(LAS v4u*)(vl + key * P + pc * 8) = vn[r]; }
;             if (c + 1 < nch) WA_LOAD(c + 1);
;             f32x4 st[2];
; #pragma unroll
;             for (int kt = 0; kt < 2; ++kt) { st[kt] = (f32x4){0.f, 0.f, 0.f, 0.f};
; #pragma unroll
;                 for (int ks = 0; ks < KS; ++ks) st[kt] = __builtin_amdgcn_mfma_f32_16x16x32_bf16(kf[kt][ks], qf[ks], st[kt], 0, 0, 0); }
;             float pv[8];
; #pragma unroll
;             for (int kt = 0; kt < 2; ++kt)
; #pragma unroll
;                 for (int j = 0; j < 4; ++j) pv[kt * 4 + j] = sp.score(st[kt][j], i, 32 * c + 16 * kt + 4 * g + j);
;             if constexpr (SOFTMAX) {
;                 float cm = pv[0];
; #pragma unroll
;                 for (int r = 1; r < 8; ++r) cm = fmaxf(cm, pv[r]);
;                 cm = fmaxf(cm, __shfl_xor(cm, 16)); cm = fmaxf(cm, __shfl_xor(cm, 32));
;                 const float mn = fmaxf(m_run, cm), sc = exp2f(m_run - mn);
;                 float ls = 0.f;
; #pragma unroll
;                 for (int r = 0; r < 8; ++r) { pv[r] = exp2f(pv[r] - mn); ls += pv[r]; }
;                 ls += __shfl_xor(ls, 16); ls += __shfl_xor(ls, 32);
;                 l_run = l_run * sc + ls; m_run = mn;
; #pragma unroll
;                 for (int dt = 0; dt < DT; ++dt) oacc[dt] = oacc[dt] * sc;
;             }
;             bf16x8 pb; { v4u t; t.x = pk2(pv[0], pv[1]); t.y = pk2(pv[2], pv[3]); t.z = pk2(pv[4], pv[5]); t.w = pk2(pv[6], pv[7]); pb = __builtin_bit_cast(bf16x8, t); }
;             if constexpr (USE_TR) {
; #pragma unroll
;                 for (int d4 = 0; d4 < DT; d4 += 4) { bf16x8 vf4[4]; read_vfrags4_trp<P>(vl + 16 * d4, i, g, vf4);
; #pragma unroll
;                     for (int dt = 0; dt < 4; ++dt) oacc[d4 + dt] = __builtin_amdgcn_mfma_f32_16x16x32_bf16(vf4[dt], pb, oacc[d4 + dt], 0, 0, 0); }
;     __device__ __forceinline__ float score(float s, int i, int j) const {
;         const int rel = (t0 + i) - (kofs + j); const float e = rel >= 0 ? lgf * (float)rel : lgb * (float)(-rel);
;         return s * 0.125f * exp2f(e);
;     }
	ds_write_b128 v97, v[110:113]
	ds_write_b128 v98, v[106:109]
	ds_write_b128 v99, v[62:65]
	ds_write_b128 v100, v[58:61]
	v_bfi_b32 v14, s87, v14, v14
	v_bfi_b32 v38, s87, v38, v38
	v_bfi_b32 v42, s87, v42, v42
	s_waitcnt lgkmcnt(9)
	v_mfma_f32_16x16x32_bf16 v[52:55], v[12:15], v[8:11], 0
	v_add_co_u32_e32 v12, vcc, s52, v56
	v_bfi_b32 v34, s87, v34, v34
	s_nop 0
	v_addc_co_u32_e32 v13, vcc, 0, v57, vcc
	v_mfma_f32_16x16x32_bf16 v[44:47], v[36:39], v[8:11], 0
	v_add_co_u32_e32 v36, vcc, s0, v56
	v_mad_i64_i32 v[66:67], s[0:1], v66, s90, v[68:69]
	s_nop 0
	v_addc_co_u32_e32 v37, vcc, 0, v57, vcc
	v_cmp_gt_i32_e32 vcc, 32, v104
	v_mfma_f32_16x16x32_bf16 v[40:43], v[40:43], v[8:11], 0
	v_lshl_add_u64 v[66:67], v[66:67], 0, v[84:85]
	v_cndmask_b32_e32 v25, v102, v103, vcc
	v_mul_f32_e32 v26, v25, v24
	s_waitcnt lgkmcnt(8)
	v_mfma_f32_16x16x32_bf16 v[48:51], v[32:35], v[8:11], 0
	global_load_dwordx4 v[8:11], v[12:13], off offset:1024
	s_nop 0
	global_load_dwordx4 v[12:15], v[12:13], off offset:1088
	v_exp_f32_e32 v24, v26
	v_sub_u32_e32 v26, 33, v104
	v_cmp_gt_i32_e32 vcc, 33, v104
	v_subrev_u32_e32 v25, 33, v104
	v_max_i32_e32 v25, v25, v26
	v_cvt_f32_u32_e32 v25, v25
	v_cndmask_b32_e32 v26, v102, v103, vcc
	global_load_dwordx4 v[32:35], v[36:37], off offset:1024
	s_nop 0
	global_load_dwordx4 v[36:39], v[36:37], off offset:1088
	v_add_u32_e32 v58, s14, v94
	v_mul_f32_e32 v27, v26, v25
	global_load_dwordx4 v[106:109], v[66:67], off offset:2048
	v_add_u32_e32 v66, s14, v73
	v_exp_f32_e32 v25, v27
	v_sub_u32_e32 v27, 34, v104
	v_cmp_gt_i32_e32 vcc, 34, v104
	v_mov_b32_e32 v26, v25
	v_subrev_u32_e32 v25, 34, v104
	v_max_i32_e32 v25, v25, v27
	v_cvt_f32_u32_e32 v25, v25
	v_cndmask_b32_e32 v27, v102, v103, vcc
	v_mad_i64_i32 v[66:67], s[0:1], v66, s90, v[68:69]
	v_mul_f32_e32 v28, v27, v25
	v_add_u32_e32 v62, s14, v93
	v_lshl_add_u64 v[66:67], v[66:67], 0, v[82:83]
	v_exp_f32_e32 v25, v28
	v_sub_u32_e32 v28, 35, v104
	v_cmp_gt_i32_e32 vcc, 35, v104
	v_subrev_u32_e32 v27, 35, v104
	v_max_i32_e32 v27, v27, v28
	v_cvt_f32_u32_e32 v27, v27
	v_cndmask_b32_e32 v28, v102, v103, vcc
	v_mad_i64_i32 v[58:59], s[0:1], v58, s90, v[68:69]
	v_mul_f32_e32 v29, v28, v27
	v_mad_i64_i32 v[62:63], s[0:1], v62, s90, v[68:69]
	s_nop 0
	v_exp_f32_e32 v27, v29
	v_sub_u32_e32 v29, 48, v104
	v_cmp_gt_i32_e32 vcc, 48, v104
	v_subrev_u32_e32 v28, 48, v104
	v_max_i32_e32 v28, v28, v29
	v_cvt_f32_u32_e32 v28, v28
	v_cndmask_b32_e32 v29, v102, v103, vcc
	global_load_dwordx4 v[110:113], v[66:67], off offset:2048
	v_lshl_add_u64 v[58:59], v[58:59], 0, v[88:89]
	v_mul_f32_e32 v30, v29, v28
	v_lshl_add_u64 v[62:63], v[62:63], 0, v[86:87]
	global_load_dwordx4 v[58:61], v[58:59], off offset:2048
	v_exp_f32_e32 v28, v30
	v_sub_u32_e32 v30, 49, v104
	v_cmp_gt_i32_e32 vcc, 49, v104
	v_subrev_u32_e32 v29, 49, v104
	v_max_i32_e32 v29, v29, v30
	v_cvt_f32_u32_e32 v29, v29
	v_cndmask_b32_e32 v30, v102, v103, vcc
	global_load_dwordx4 v[62:65], v[62:63], off offset:2048
	s_waitcnt vmcnt(7)
	v_mfma_f32_16x16x32_bf16 v[8:11], v[8:11], v[0:3], 0
	v_mul_f32_e32 v31, v30, v29
	s_mov_b32 s0, 0xa8000
	s_waitcnt vmcnt(6)
	v_mfma_f32_16x16x32_bf16 v[8:11], v[12:15], v[4:7], v[8:11]
	v_exp_f32_e32 v29, v31
	v_sub_u32_e32 v31, 50, v104
	v_cmp_gt_i32_e32 vcc, 50, v104
	v_mov_b32_e32 v30, v29
	v_subrev_u32_e32 v29, 50, v104
	v_max_i32_e32 v29, v29, v31
	v_cvt_f32_u32_e32 v29, v29
	v_cndmask_b32_e32 v31, v102, v103, vcc
	s_waitcnt vmcnt(5)
	v_mfma_f32_16x16x32_bf16 v[12:15], v[32:35], v[0:3], 0
	v_subrev_u32_e32 v32, 64, v104
	v_mul_f32_e32 v66, v31, v29
	v_sub_u32_e32 v33, 64, v104
	v_max_i32_e32 v32, v32, v33
	v_exp_f32_e32 v29, v66
	v_sub_u32_e32 v66, 51, v104
	v_cmp_gt_i32_e32 vcc, 51, v104
	v_subrev_u32_e32 v31, 51, v104
	v_max_i32_e32 v31, v31, v66
	v_cvt_f32_u32_e32 v31, v31
	v_cndmask_b32_e32 v66, v102, v103, vcc
	v_cvt_f32_u32_e32 v32, v32
	v_add_u32_e32 v70, s13, v73
	v_mul_f32_e32 v67, v66, v31
	s_waitcnt vmcnt(4)
	v_mfma_f32_16x16x32_bf16 v[12:15], v[36:39], v[4:7], v[12:15]
	v_exp_f32_e32 v31, v67
	v_mov_b32_e32 v67, v18
	v_mov_b32_e32 v18, v17
	v_mov_b32_e32 v66, v16
	v_pk_mul_f32 v[16:17], v[18:19], s[76:77] op_sel_hi:[1,0]
	v_mov_b32_e32 v19, v22
	v_mov_b32_e32 v22, v21
	v_mov_b32_e32 v18, v20
	v_pk_mul_f32 v[20:21], v[22:23], s[76:77] op_sel_hi:[1,0]
	v_pk_mul_f32 v[66:67], v[66:67], s[76:77] op_sel_hi:[1,0]
	v_pk_mul_f32 v[16:17], v[16:17], v[26:27]
	v_pk_mul_f32 v[18:19], v[18:19], s[76:77] op_sel_hi:[1,0]
	v_pk_mul_f32 v[20:21], v[20:21], v[30:31]
	v_pk_mul_f32 v[24:25], v[66:67], v[24:25]
	v_pk_mul_f32 v[18:19], v[18:19], v[28:29]
	v_bfe_u32 v22, v21, 16, 1
	v_bfe_u32 v23, v20, 16, 1
	v_bfe_u32 v26, v17, 16, 1
	v_bfe_u32 v27, v16, 16, 1
	v_add3_u32 v16, v16, v27, s86
	v_add3_u32 v17, v17, v26, s86
	v_add3_u32 v20, v20, v23, s86
	v_add3_u32 v21, v21, v22, s86
	v_bfe_u32 v22, v24, 16, 1
	v_bfe_u32 v23, v25, 16, 1
	v_bfe_u32 v26, v18, 16, 1
	v_bfe_u32 v27, v19, 16, 1
	v_add3_u32 v19, v19, v27, s86
	v_add3_u32 v18, v18, v26, s86
	v_add3_u32 v23, v25, v23, s86
	v_add3_u32 v22, v24, v22, s86
	v_lshrrev_b32_e32 v22, 16, v22
	v_lshrrev_b32_e32 v23, 16, v23
	v_lshrrev_b32_e32 v18, 16, v18
	v_lshrrev_b32_e32 v19, 16, v19
	v_and_or_b32 v31, v21, s85, v19
	v_and_or_b32 v30, v20, s85, v18
	v_and_or_b32 v29, v17, s85, v23
	v_and_or_b32 v28, v16, s85, v22
	ds_read_b64_tr_b16 v[16:17], v95
	ds_read_b64_tr_b16 v[20:21], v95 offset:32
	ds_read_b64_tr_b16 v[24:25], v95 offset:64
	ds_read_b64_tr_b16 v[114:115], v95 offset:96
	ds_read_b64_tr_b16 v[18:19], v96
	ds_read_b64_tr_b16 v[22:23], v96 offset:32
	ds_read_b64_tr_b16 v[26:27], v96 offset:64
	ds_read_b64_tr_b16 v[116:117], v96 offset:96
	s_waitcnt lgkmcnt(0)
; template <int DH, bool SOFTMAX, bool PREFETCH, class Spec>
; __device__ __forceinline__ void wave_attn(const Spec& sp, int nch, LAS bf16* vl, int lane, f32x4 (&oacc)[DH / 16], float& m_run, float& l_run) {
;     ...
;             for (int r = 0; r < NP; ++r) { const int p = lane + 64 * r, key = p / PPR, pc = p % PPR; *(LAS v4u*)(vl + key * P + pc * 8) = vn[r]; }
;             if (c + 1 < nch) WA_LOAD(c + 1);
;             f32x4 st[2];
; #pragma unroll
;             for (int kt = 0; kt < 2; ++kt) { st[kt] = (f32x4){0.f, 0.f, 0.f, 0.f};
; #pragma unroll
;                 for (int ks = 0; ks < KS; ++ks) st[kt] = __builtin_amdgcn_mfma_f32_16x16x32_bf16(kf[kt][ks], qf[ks], st[kt], 0, 0, 0); }
;             float pv[8];
; #pragma unroll
;             for (int kt = 0; kt < 2; ++kt)
; #pragma unroll
;                 for (int j = 0; j < 4; ++j) pv[kt * 4 + j] = sp.score(st[kt][j], i, 32 * c + 16 * kt + 4 * g + j);
;             if constexpr (SOFTMAX) {
;                 float cm = pv[0];
; #pragma unroll
;                 for (int r = 1; r < 8; ++r) cm = fmaxf(cm, pv[r]);
;                 cm = fmaxf(cm, __shfl_xor(cm, 16)); cm = fmaxf(cm, __shfl_xor(cm, 32));
;                 const float mn = fmaxf(m_run, cm), sc = exp2f(m_run - mn);
;                 float ls = 0.f;
; #pragma unroll
;                 for (int r = 0; r < 8; ++r) { pv[r] = exp2f(pv[r] - mn); ls += pv[r]; }
;                 ls += __shfl_xor(ls, 16); ls += __shfl_xor(ls, 32);
;                 l_run = l_run * sc + ls; m_run = mn;
; #pragma unroll
;                 for (int dt = 0; dt < DT; ++dt) oacc[dt] = oacc[dt] * sc;
;             }
;             bf16x8 pb; { v4u t; t.x = pk2(pv[0], pv[1]); t.y = pk2(pv[2], pv[3]); t.z = pk2(pv[4], pv[5]); t.w = pk2(pv[6], pv[7]); pb = __builtin_bit_cast(bf16x8, t); }
;             if constexpr (USE_TR) {
; #pragma unroll
;                 for (int d4 = 0; d4 < DT; d4 += 4) { bf16x8 vf4[4]; read_vfrags4_trp<P>(vl + 16 * d4, i, g, vf4);
; #pragma unroll
;                     for (int dt = 0; dt < 4; ++dt) oacc[d4 + dt] = __builtin_amdgcn_mfma_f32_16x16x32_bf16(vf4[dt], pb, oacc[d4 + dt], 0, 0, 0); }
;     __device__ __forceinline__ float score(float s, int i, int j) const {
;         const int rel = (t0 + i) - (kofs + j); const float e = rel >= 0 ? lgf * (float)rel : lgb * (float)(-rel);
;         return s * 0.125f * exp2f(e);
;     }
	s_waitcnt vmcnt(2)
	ds_write_b128 v97, v[110:113]
	ds_write_b128 v98, v[106:109]
	s_waitcnt vmcnt(0)
	ds_write_b128 v99, v[62:65]
	ds_write_b128 v100, v[58:61]
	v_bfi_b32 v22, s87, v22, v22
	v_bfi_b32 v18, s87, v18, v18
	v_bfi_b32 v26, s87, v26, v26
	v_bfi_b32 v116, s87, v116, v116
	v_mfma_f32_16x16x32_bf16 v[20:23], v[20:23], v[28:31], v[44:47]
	v_add_u32_e32 v60, s13, v93
	v_add_u32_e32 v64, s13, v92
	s_nop 0
	v_add_co_u32_e32 v44, vcc, s0, v56
	s_mov_b32 s0, 0xc4000
	s_nop 0
	v_addc_co_u32_e32 v45, vcc, 0, v57, vcc
	v_mfma_f32_16x16x32_bf16 v[16:19], v[16:19], v[28:31], v[40:43]
	s_nop 2
	global_load_dwordx4 v[40:43], v[44:45], off offset:1024
	s_nop 0
	global_load_dwordx4 v[44:47], v[44:45], off offset:1088
	v_mov_b32_e32 v107, v10
	v_mov_b32_e32 v10, v9
	v_mfma_f32_16x16x32_bf16 v[24:27], v[24:27], v[28:31], v[48:51]
	v_mfma_f32_16x16x32_bf16 v[28:31], v[114:117], v[28:31], v[52:55]
	s_nop 2
	v_add_co_u32_e32 v52, vcc, s0, v56
	v_add_u32_e32 v56, s13, v94
	s_nop 0
	v_addc_co_u32_e32 v53, vcc, 0, v57, vcc
	v_cmp_gt_i32_e32 vcc, 64, v104
	v_mad_i64_i32 v[56:57], s[0:1], v56, s90, v[68:69]
	s_nop 0
	v_cndmask_b32_e32 v33, v102, v103, vcc
	v_mul_f32_e32 v34, v33, v32
	v_mad_i64_i32 v[60:61], s[0:1], v60, s90, v[68:69]
	s_nop 0
	v_exp_f32_e32 v32, v34
	v_sub_u32_e32 v34, 0x41, v104
	v_cmp_gt_i32_e32 vcc, s88, v104
	v_add_u32_e32 v33, 0xffffffbf, v104
	v_max_i32_e32 v33, v33, v34
	v_cvt_f32_u32_e32 v33, v33
	v_cndmask_b32_e32 v34, v102, v103, vcc
	v_mad_i64_i32 v[64:65], s[0:1], v64, s90, v[68:69]
	v_mul_f32_e32 v35, v34, v33
	v_mad_i64_i32 v[68:69], s[0:1], v70, s90, v[68:69]
	s_nop 0
	v_exp_f32_e32 v33, v35
	v_sub_u32_e32 v35, 0x42, v104
	s_movk_i32 s0, 0x42
	v_mov_b32_e32 v34, v33
	v_add_u32_e32 v33, 0xffffffbe, v104
	v_max_i32_e32 v33, v33, v35
	v_cvt_f32_u32_e32 v33, v33
	v_cmp_gt_i32_e32 vcc, s0, v104
	global_load_dwordx4 v[48:51], v[52:53], off offset:1024
	s_nop 0
	global_load_dwordx4 v[52:55], v[52:53], off offset:1088
	v_cndmask_b32_e32 v35, v102, v103, vcc
	v_mul_f32_e32 v36, v35, v33
	s_movk_i32 s0, 0x43
	v_lshl_add_u64 v[56:57], v[56:57], 0, v[88:89]
	v_exp_f32_e32 v33, v36
	v_sub_u32_e32 v36, 0x43, v104
	v_cmp_gt_i32_e32 vcc, s0, v104
	v_add_u32_e32 v35, 0xffffffbd, v104
	v_max_i32_e32 v35, v35, v36
	v_cvt_f32_u32_e32 v35, v35
	v_cndmask_b32_e32 v36, v102, v103, vcc
	s_movk_i32 s0, 0x50
	v_lshl_add_u64 v[60:61], v[60:61], 0, v[86:87]
	v_mul_f32_e32 v37, v36, v35
	v_lshl_add_u64 v[64:65], v[64:65], 0, v[84:85]
	v_lshl_add_u64 v[68:69], v[68:69], 0, v[82:83]
	v_exp_f32_e32 v35, v37
	v_sub_u32_e32 v37, 0x50, v104
	v_cmp_gt_i32_e32 vcc, s0, v104
	v_add_u32_e32 v36, 0xffffffb0, v104
	v_max_i32_e32 v36, v36, v37
	v_cvt_f32_u32_e32 v36, v36
	v_cndmask_b32_e32 v37, v102, v103, vcc
	s_movk_i32 s0, 0x51
	global_load_dwordx4 v[56:59], v[56:57], off offset:2048
	v_mul_f32_e32 v38, v37, v36
	global_load_dwordx4 v[60:63], v[60:61], off offset:2048
	s_lshl_b32 s1, s8, 5
	v_exp_f32_e32 v36, v38
	v_sub_u32_e32 v38, 0x51, v104
	v_cmp_gt_i32_e32 vcc, s0, v104
	v_add_u32_e32 v37, 0xffffffaf, v104
	v_max_i32_e32 v37, v37, v38
	v_cvt_f32_u32_e32 v37, v37
	v_cndmask_b32_e32 v38, v102, v103, vcc
	s_movk_i32 s0, 0x52
	global_load_dwordx4 v[64:67], v[64:65], off offset:2048
	v_mul_f32_e32 v39, v38, v37
	global_load_dwordx4 v[68:71], v[68:69], off offset:2048
	s_nop 0
	v_exp_f32_e32 v37, v39
	v_sub_u32_e32 v39, 0x52, v104
	v_cmp_gt_i32_e32 vcc, s0, v104
	v_mov_b32_e32 v38, v37
	v_add_u32_e32 v37, 0xffffffae, v104
	v_max_i32_e32 v37, v37, v39
	v_cvt_f32_u32_e32 v37, v37
	v_cndmask_b32_e32 v39, v102, v103, vcc
	s_movk_i32 s0, 0x53
	v_mul_f32_e32 v105, v39, v37
	s_nop 1
	v_exp_f32_e32 v37, v105
	v_sub_u32_e32 v105, 0x53, v104
	v_cmp_gt_i32_e32 vcc, s0, v104
	v_add_u32_e32 v39, 0xffffffad, v104
	v_max_i32_e32 v39, v39, v105
	v_cvt_f32_u32_e32 v39, v39
	v_cndmask_b32_e32 v105, v102, v103, vcc
	s_movk_i32 s0, 0x60
	v_mul_f32_e32 v106, v105, v39
	s_nop 1
	v_exp_f32_e32 v39, v106
	v_mov_b32_e32 v106, v8
	v_pk_mul_f32 v[8:9], v[10:11], s[76:77] op_sel_hi:[1,0]
	v_mov_b32_e32 v11, v14
	v_mov_b32_e32 v14, v13
	v_mov_b32_e32 v10, v12
	v_pk_mul_f32 v[12:13], v[14:15], s[76:77] op_sel_hi:[1,0]
	v_pk_mul_f32 v[106:107], v[106:107], s[76:77] op_sel_hi:[1,0]
	v_pk_mul_f32 v[8:9], v[34:35], v[8:9]
	v_pk_mul_f32 v[10:11], v[10:11], s[76:77] op_sel_hi:[1,0]
	v_pk_mul_f32 v[12:13], v[38:39], v[12:13]
	v_pk_mul_f32 v[32:33], v[32:33], v[106:107]
	v_pk_mul_f32 v[10:11], v[36:37], v[10:11]
	v_bfe_u32 v14, v13, 16, 1
	v_bfe_u32 v15, v12, 16, 1
	v_bfe_u32 v34, v9, 16, 1
	v_bfe_u32 v35, v8, 16, 1
	v_add3_u32 v8, v8, v35, s86
	v_add3_u32 v9, v9, v34, s86
	v_add3_u32 v12, v12, v15, s86
	v_add3_u32 v13, v13, v14, s86
	v_bfe_u32 v14, v32, 16, 1
	v_bfe_u32 v15, v33, 16, 1
	v_bfe_u32 v34, v10, 16, 1
	v_bfe_u32 v35, v11, 16, 1
	v_add3_u32 v11, v11, v35, s86
	v_add3_u32 v10, v10, v34, s86
	v_add3_u32 v15, v33, v15, s86
	v_add3_u32 v14, v32, v14, s86
	v_lshrrev_b32_e32 v14, 16, v14
	v_lshrrev_b32_e32 v15, 16, v15
	v_lshrrev_b32_e32 v10, 16, v10
	v_lshrrev_b32_e32 v11, 16, v11
	v_and_or_b32 v35, v13, s85, v11
	v_and_or_b32 v34, v12, s85, v10
	v_and_or_b32 v33, v9, s85, v15
	v_and_or_b32 v32, v8, s85, v14
	ds_read_b64_tr_b16 v[8:9], v95
	ds_read_b64_tr_b16 v[12:13], v95 offset:32
	ds_read_b64_tr_b16 v[106:107], v95 offset:64
	ds_read_b64_tr_b16 v[36:37], v95 offset:96
	ds_read_b64_tr_b16 v[10:11], v96
	ds_read_b64_tr_b16 v[14:15], v96 offset:32
	ds_read_b64_tr_b16 v[108:109], v96 offset:64
	ds_read_b64_tr_b16 v[38:39], v96 offset:96
	s_waitcnt lgkmcnt(0)
	v_cmp_gt_i32_e32 vcc, s0, v104
	v_bfi_b32 v10, s87, v10, v10
	v_bfi_b32 v108, s87, v108, v108
	s_movk_i32 s0, 0x61
	v_mfma_f32_16x16x32_bf16 v[8:11], v[8:11], v[32:35], v[16:19]
	v_bfi_b32 v14, s87, v14, v14
	v_bfi_b32 v38, s87, v38, v38
	s_waitcnt vmcnt(0)
; template <int DH, bool SOFTMAX, bool PREFETCH, class Spec>
; __device__ __forceinline__ void wave_attn(const Spec& sp, int nch, LAS bf16* vl, int lane, f32x4 (&oacc)[DH / 16], float& m_run, float& l_run) {
;     ...
;             for (int kt = 0; kt < 2; ++kt)
; #pragma unroll
;                 for (int j = 0; j < 4; ++j) pv[kt * 4 + j] = sp.score(st[kt][j], i, 32 * c + 16 * kt + 4 * g + j);
;             if constexpr (SOFTMAX) {
;                 float cm = pv[0];
; #pragma unroll
;                 for (int r = 1; r < 8; ++r) cm = fmaxf(cm, pv[r]);
;                 cm = fmaxf(cm, __shfl_xor(cm, 16)); cm = fmaxf(cm, __shfl_xor(cm, 32));
;                 const float mn = fmaxf(m_run, cm), sc = exp2f(m_run - mn);
;                 float ls = 0.f;
; #pragma unroll
;                 for (int r = 0; r < 8; ++r) { pv[r] = exp2f(pv[r] - mn); ls += pv[r]; }
;                 ls += __shfl_xor(ls, 16); ls += __shfl_xor(ls, 32);
;                 l_run = l_run * sc + ls; m_run = mn;
; #pragma unroll
;                 for (int dt = 0; dt < DT; ++dt) oacc[dt] = oacc[dt] * sc;
;             }
;             bf16x8 pb; { v4u t; t.x = pk2(pv[0], pv[1]); t.y = pk2(pv[2], pv[3]); t.z = pk2(pv[4], pv[5]); t.w = pk2(pv[6], pv[7]); pb = __builtin_bit_cast(bf16x8, t); }
;             if constexpr (USE_TR) {
; #pragma unroll
;                 for (int d4 = 0; d4 < DT; d4 += 4) { bf16x8 vf4[4]; read_vfrags4_trp<P>(vl + 16 * d4, i, g, vf4);
; #pragma unroll
;                     for (int dt = 0; dt < 4; ++dt) oacc[d4 + dt] = __builtin_amdgcn_mfma_f32_16x16x32_bf16(vf4[dt], pb, oacc[d4 + dt], 0, 0, 0); }
; __device__ __forceinline__ void ret_out_phase(const Ctx& C, const bf16* PROJ, const bf16* ST, bf16* MIX, const float* decay_logit, const float* ret_gain) {
;     ...
;         for (int dir = 0; dir < 2; ++dir) {
;             const bf16* stn = ST + (size_t)((((b * 8 + h) * 2 + dir) * 16) + n) * 4096 + (size_t)i * 64 + 8 * g;
;             const float xi = 0.125f * (dir == 0 ? exp2f(lgf * (float)(c + 1)) : exp2f(lgb * (float)(128 - c)));
; #pragma unroll
;             for (int dt = 0; dt < 4; ++dt) { f32x4 as = (f32x4){0.f, 0.f, 0.f, 0.f};
; #pragma unroll
;                 for (int ks = 0; ks < 2; ++ks) { const bf16x8 sf = *(const bf16x8*)(stn + (size_t)(16 * dt) * 64 + 32 * ks); as = __builtin_amdgcn_mfma_f32_16x16x32_bf16(sf, qf[ks], as, 0, 0, 0); }
;                 o[dt] = o[dt] + as * xi; }
	ds_write_b128 v97, v[68:71]
	ds_write_b128 v98, v[64:67]
	ds_write_b128 v99, v[60:63]
	ds_write_b128 v100, v[56:59]
	v_mfma_f32_16x16x32_bf16 v[16:19], v[106:109], v[32:35], v[24:27]
	v_mfma_f32_16x16x32_bf16 v[24:27], v[40:43], v[0:3], 0
	v_mfma_f32_16x16x32_bf16 v[0:3], v[48:51], v[0:3], 0
	v_mfma_f32_16x16x32_bf16 v[24:27], v[44:47], v[4:7], v[24:27]
	v_mfma_f32_16x16x32_bf16 v[0:3], v[52:55], v[4:7], v[0:3]
	v_add_u32_e32 v4, 0xffffffa0, v104
	v_sub_u32_e32 v5, 0x60, v104
	v_max_i32_e32 v4, v4, v5
	v_cvt_f32_u32_e32 v4, v4
	v_cndmask_b32_e32 v5, v102, v103, vcc
	v_mfma_f32_16x16x32_bf16 v[12:15], v[12:15], v[32:35], v[20:23]
	v_mul_f32_e32 v6, v5, v4
	v_mfma_f32_16x16x32_bf16 v[20:23], v[36:39], v[32:35], v[28:31]
	s_nop 0
	v_exp_f32_e32 v4, v6
	v_sub_u32_e32 v6, 0x61, v104
	v_cmp_gt_i32_e32 vcc, s0, v104
	v_add_u32_e32 v5, 0xffffff9f, v104
	v_max_i32_e32 v5, v5, v6
	v_cvt_f32_u32_e32 v5, v5
	v_cndmask_b32_e32 v6, v102, v103, vcc
	s_movk_i32 s0, 0x62
	v_mul_f32_e32 v7, v6, v5
	s_nop 1
	v_exp_f32_e32 v5, v7
	v_sub_u32_e32 v7, 0x62, v104
	v_cmp_gt_i32_e32 vcc, s0, v104
	v_mov_b32_e32 v6, v5
	v_add_u32_e32 v5, 0xffffff9e, v104
	v_max_i32_e32 v5, v5, v7
	v_cvt_f32_u32_e32 v5, v5
	v_cndmask_b32_e32 v7, v102, v103, vcc
	s_movk_i32 s0, 0x63
	v_mul_f32_e32 v28, v7, v5
	s_nop 1
	v_exp_f32_e32 v5, v28
	v_sub_u32_e32 v28, 0x63, v104
	v_cmp_gt_i32_e32 vcc, s0, v104
	v_add_u32_e32 v7, 0xffffff9d, v104
	v_max_i32_e32 v7, v7, v28
	v_cvt_f32_u32_e32 v7, v7
	v_cndmask_b32_e32 v28, v102, v103, vcc
	s_movk_i32 s0, 0x70
	v_mul_f32_e32 v29, v28, v7
	s_nop 1
	v_exp_f32_e32 v7, v29
	v_sub_u32_e32 v29, 0x70, v104
	v_cmp_gt_i32_e32 vcc, s0, v104
	v_add_u32_e32 v28, 0xffffff90, v104
	v_max_i32_e32 v28, v28, v29
	v_cvt_f32_u32_e32 v28, v28
	v_cndmask_b32_e32 v29, v102, v103, vcc
	s_movk_i32 s0, 0x71
	v_mul_f32_e32 v30, v29, v28
	s_nop 1
	v_exp_f32_e32 v28, v30
	v_sub_u32_e32 v30, 0x71, v104
	v_cmp_gt_i32_e32 vcc, s0, v104
	v_add_u32_e32 v29, 0xffffff8f, v104
	v_max_i32_e32 v29, v29, v30
	v_cvt_f32_u32_e32 v29, v29
	v_cndmask_b32_e32 v30, v102, v103, vcc
	s_movk_i32 s0, 0x72
	v_mul_f32_e32 v31, v30, v29
	s_nop 1
	v_exp_f32_e32 v29, v31
	v_sub_u32_e32 v31, 0x72, v104
	v_cmp_gt_i32_e32 vcc, s0, v104
	v_mov_b32_e32 v30, v29
	v_add_u32_e32 v29, 0xffffff8e, v104
	v_max_i32_e32 v29, v29, v31
	v_cvt_f32_u32_e32 v29, v29
	v_cndmask_b32_e32 v31, v102, v103, vcc
	s_movk_i32 s0, 0x73
	v_mul_f32_e32 v32, v31, v29
	s_nop 1
	v_exp_f32_e32 v29, v32
	v_sub_u32_e32 v32, 0x73, v104
	v_cmp_gt_i32_e32 vcc, s0, v104
	v_add_u32_e32 v31, 0xffffff8d, v104
	v_max_i32_e32 v31, v31, v32
	v_cvt_f32_u32_e32 v31, v31
	v_cndmask_b32_e32 v32, v102, v103, vcc
	s_lshl_b32 s0, s11, 8
	s_or_b32 s0, s1, s0
	v_mul_f32_e32 v33, v32, v31
	s_or_b32 s0, s0, s12
	s_ashr_i32 s1, s0, 31
	v_exp_f32_e32 v31, v33
	v_mov_b32_e32 v33, v26
	v_mov_b32_e32 v26, v25
	v_mov_b32_e32 v32, v24
	v_pk_mul_f32 v[24:25], v[26:27], s[76:77] op_sel_hi:[1,0]
	v_pk_mul_f32 v[32:33], v[32:33], s[76:77] op_sel_hi:[1,0]
	v_pk_mul_f32 v[6:7], v[6:7], v[24:25]
	v_mov_b32_e32 v25, v2
	v_mov_b32_e32 v2, v1
	v_mov_b32_e32 v24, v0
	v_pk_mul_f32 v[0:1], v[2:3], s[76:77] op_sel_hi:[1,0]
	v_pk_mul_f32 v[24:25], v[24:25], s[76:77] op_sel_hi:[1,0]
	v_pk_mul_f32 v[0:1], v[30:31], v[0:1]
	v_pk_mul_f32 v[4:5], v[4:5], v[32:33]
	v_pk_mul_f32 v[24:25], v[28:29], v[24:25]
	v_bfe_u32 v2, v1, 16, 1
	v_bfe_u32 v3, v0, 16, 1
	v_bfe_u32 v26, v7, 16, 1
	v_bfe_u32 v27, v6, 16, 1
	v_add3_u32 v6, v6, v27, s86
	v_add3_u32 v7, v7, v26, s86
	v_add3_u32 v0, v0, v3, s86
	v_add3_u32 v1, v1, v2, s86
	v_bfe_u32 v2, v4, 16, 1
	v_bfe_u32 v3, v5, 16, 1
	v_bfe_u32 v26, v24, 16, 1
	v_bfe_u32 v27, v25, 16, 1
	v_add3_u32 v25, v25, v27, s86
	v_add3_u32 v24, v24, v26, s86
	v_add3_u32 v3, v5, v3, s86
	v_add3_u32 v2, v4, v2, s86
	v_lshrrev_b32_e32 v4, 16, v2
	v_lshrrev_b32_e32 v5, 16, v3
	v_lshrrev_b32_e32 v2, 16, v24
	v_lshrrev_b32_e32 v3, 16, v25
	v_and_or_b32 v3, v1, s85, v3
	v_and_or_b32 v2, v0, s85, v2
	v_and_or_b32 v1, v7, s85, v5
	v_and_or_b32 v0, v6, s85, v4
	ds_read_b64_tr_b16 v[32:33], v95
	ds_read_b64_tr_b16 v[28:29], v95 offset:32
	ds_read_b64_tr_b16 v[24:25], v95 offset:64
	ds_read_b64_tr_b16 v[4:5], v95 offset:96
	ds_read_b64_tr_b16 v[34:35], v96
	ds_read_b64_tr_b16 v[30:31], v96 offset:32
	ds_read_b64_tr_b16 v[26:27], v96 offset:64
	ds_read_b64_tr_b16 v[6:7], v96 offset:96
	s_waitcnt lgkmcnt(0)
	s_lshl_b64 s[12:13], s[0:1], 13
	v_bfi_b32 v34, s87, v34, v34
	v_bfi_b32 v30, s87, v30, v30
	v_bfi_b32 v26, s87, v26, v26
	v_bfi_b32 v6, s87, v6, v6
	v_mfma_f32_16x16x32_bf16 v[8:11], v[32:35], v[0:3], v[8:11]
	v_lshl_add_u64 v[32:33], v[76:77], 0, s[12:13]
	s_or_b32 s0, s0, 16
	s_ashr_i32 s1, s0, 31
	v_mfma_f32_16x16x32_bf16 v[12:15], v[28:31], v[0:3], v[12:15]
	s_lshl_b64 s[0:1], s[0:1], 13
	v_lshl_add_u64 v[40:41], v[76:77], 0, s[0:1]
	s_lshl_b32 s11, s11, 11
	v_mfma_f32_16x16x32_bf16 v[16:19], v[24:27], v[0:3], v[16:19]
	v_mfma_f32_16x16x32_bf16 v[0:3], v[4:7], v[0:3], v[20:23]
	v_sub_u32_e32 v4, 0x80, v101
	v_cvt_f32_ubyte0_e32 v4, v4
	v_mul_f32_e32 v5, v103, v4
	global_load_dwordx4 v[20:23], v[90:91], off
	global_load_dwordx4 v[24:27], v[90:91], off offset:64
	v_exp_f32_e32 v4, v5
	global_load_dwordx4 v[28:31], v[32:33], off offset:64
	v_mov_b32_e32 v42, v4
	v_add_u32_e32 v4, 1, v101
	v_cvt_f32_ubyte0_e32 v4, v4
	v_mul_f32_e32 v5, v102, v4
	v_mul_f32_e32 v42, 0x3e000000, v42
	s_nop 0
	v_exp_f32_e32 v4, v5
	s_nop 0
	v_mul_f32_e32 v34, 0x3e000000, v4
	global_load_dwordx4 v[4:7], v[32:33], off
	s_waitcnt vmcnt(0)
; __device__ __forceinline__ void ret_out_phase(const Ctx& C, const bf16* PROJ, const bf16* ST, bf16* MIX, const float* decay_logit, const float* ret_gain) {
;     ...
;         for (int dir = 0; dir < 2; ++dir) {
;             const bf16* stn = ST + (size_t)((((b * 8 + h) * 2 + dir) * 16) + n) * 4096 + (size_t)i * 64 + 8 * g;
;             const float xi = 0.125f * (dir == 0 ? exp2f(lgf * (float)(c + 1)) : exp2f(lgb * (float)(128 - c)));
; #pragma unroll
;             for (int dt = 0; dt < 4; ++dt) { f32x4 as = (f32x4){0.f, 0.f, 0.f, 0.f};
; #pragma unroll
;                 for (int ks = 0; ks < 2; ++ks) { const bf16x8 sf = *(const bf16x8*)(stn + (size_t)(16 * dt) * 64 + 32 * ks); as = __builtin_amdgcn_mfma_f32_16x16x32_bf16(sf, qf[ks], as, 0, 0, 0); }
;                 o[dt] = o[dt] + as * xi; }
;         }
;         float ss = 0.f;
; #pragma unroll
;         for (int dt = 0; dt < 4; ++dt) ss += (o[dt].x * o[dt].x + o[dt].y * o[dt].y) + (o[dt].z * o[dt].z + o[dt].w * o[dt].w);
;         ss += __shfl_xor(ss, 16); ss += __shfl_xor(ss, 32);
	v_mfma_f32_16x16x32_bf16 v[4:7], v[4:7], v[20:23], 0
	v_mfma_f32_16x16x32_bf16 v[4:7], v[28:31], v[24:27], v[4:7]
	s_nop 7
	v_pk_fma_f32 v[28:29], v[34:35], v[6:7], v[10:11] op_sel_hi:[0,1,1]
	v_pk_fma_f32 v[30:31], v[34:35], v[4:5], v[8:9] op_sel_hi:[0,1,1]
	global_load_dwordx4 v[4:7], v[32:33], off offset:2048
	global_load_dwordx4 v[8:11], v[32:33], off offset:2112
	s_waitcnt vmcnt(1)
	v_mfma_f32_16x16x32_bf16 v[4:7], v[4:7], v[20:23], 0
	s_waitcnt vmcnt(0)
	v_mfma_f32_16x16x32_bf16 v[4:7], v[8:11], v[24:27], v[4:7]
	s_nop 7
	v_pk_fma_f32 v[38:39], v[34:35], v[4:5], v[12:13] op_sel_hi:[0,1,1]
	v_add_co_u32_e32 v12, vcc, s54, v32
	v_pk_fma_f32 v[36:37], v[34:35], v[6:7], v[14:15] op_sel_hi:[0,1,1]
	s_nop 0
	v_addc_co_u32_e32 v13, vcc, 0, v33, vcc
	global_load_dwordx4 v[4:7], v[12:13], off
	global_load_dwordx4 v[8:11], v[12:13], off offset:64
	s_waitcnt vmcnt(1)
	v_mfma_f32_16x16x32_bf16 v[4:7], v[4:7], v[20:23], 0
	s_waitcnt vmcnt(0)
	v_mfma_f32_16x16x32_bf16 v[4:7], v[8:11], v[24:27], v[4:7]
	global_load_dwordx4 v[8:11], v[12:13], off offset:2112
	s_nop 6
	v_pk_fma_f32 v[18:19], v[34:35], v[6:7], v[18:19] op_sel_hi:[0,1,1]
	v_pk_fma_f32 v[16:17], v[34:35], v[4:5], v[16:17] op_sel_hi:[0,1,1]
	global_load_dwordx4 v[4:7], v[12:13], off offset:2048
	s_waitcnt vmcnt(0)
	v_mfma_f32_16x16x32_bf16 v[4:7], v[4:7], v[20:23], 0
	v_mfma_f32_16x16x32_bf16 v[4:7], v[8:11], v[24:27], v[4:7]
	s_nop 7
	v_pk_fma_f32 v[32:33], v[34:35], v[6:7], v[2:3] op_sel_hi:[0,1,1]
	v_pk_fma_f32 v[34:35], v[34:35], v[4:5], v[0:1] op_sel_hi:[0,1,1]
	global_load_dwordx4 v[0:3], v[40:41], off
	global_load_dwordx4 v[4:7], v[40:41], off offset:64
	s_waitcnt vmcnt(1)
	v_mfma_f32_16x16x32_bf16 v[0:3], v[0:3], v[20:23], 0
	s_waitcnt vmcnt(0)
	v_mfma_f32_16x16x32_bf16 v[0:3], v[4:7], v[24:27], v[0:3]
	global_load_dwordx4 v[4:7], v[40:41], off offset:2112
	s_nop 6
	v_pk_fma_f32 v[12:13], v[42:43], v[2:3], v[28:29] op_sel_hi:[0,1,1]
	v_pk_fma_f32 v[14:15], v[42:43], v[0:1], v[30:31] op_sel_hi:[0,1,1]
	global_load_dwordx4 v[0:3], v[40:41], off offset:2048
	s_waitcnt vmcnt(0)
	v_mfma_f32_16x16x32_bf16 v[0:3], v[0:3], v[20:23], 0
	v_add_co_u32_e32 v28, vcc, s54, v40
	v_mfma_f32_16x16x32_bf16 v[0:3], v[4:7], v[24:27], v[0:3]
	s_nop 0
	v_addc_co_u32_e32 v29, vcc, 0, v41, vcc
	global_load_dwordx4 v[4:7], v[28:29], off offset:64
	s_nop 4
	v_pk_fma_f32 v[8:9], v[42:43], v[2:3], v[36:37] op_sel_hi:[0,1,1]
	v_pk_fma_f32 v[10:11], v[42:43], v[0:1], v[38:39] op_sel_hi:[0,1,1]
	global_load_dwordx4 v[0:3], v[28:29], off
	s_waitcnt vmcnt(0)
	v_mfma_f32_16x16x32_bf16 v[0:3], v[0:3], v[20:23], 0
	v_mfma_f32_16x16x32_bf16 v[0:3], v[4:7], v[24:27], v[0:3]
	s_nop 7
	v_pk_fma_f32 v[4:5], v[42:43], v[2:3], v[18:19] op_sel_hi:[0,1,1]
	v_pk_fma_f32 v[6:7], v[42:43], v[0:1], v[16:17] op_sel_hi:[0,1,1]
	global_load_dwordx4 v[0:3], v[28:29], off offset:2048
	global_load_dwordx4 v[16:19], v[28:29], off offset:2112
	s_waitcnt vmcnt(1)
	v_mfma_f32_16x16x32_bf16 v[0:3], v[0:3], v[20:23], 0
	s_waitcnt vmcnt(0)
	v_mfma_f32_16x16x32_bf16 v[16:19], v[16:19], v[24:27], v[0:3]
	s_nop 7
	v_pk_fma_f32 v[0:1], v[42:43], v[18:19], v[32:33] op_sel_hi:[0,1,1]
	v_pk_fma_f32 v[2:3], v[42:43], v[16:17], v[34:35] op_sel_hi:[0,1,1]
	v_pk_mul_f32 v[16:17], v[12:13], v[12:13]
	v_pk_mul_f32 v[18:19], v[14:15], v[14:15]
	s_nop 0
	v_pk_mov_b32 v[20:21], v[18:19], v[16:17] op_sel:[1,0]
	v_mov_b32_e32 v19, v17
	v_pk_add_f32 v[16:17], v[20:21], v[18:19]
	v_pk_mul_f32 v[18:19], v[8:9], v[8:9]
	v_pk_mul_f32 v[20:21], v[10:11], v[10:11]
	v_pk_add_f32 v[16:17], v[16:17], v[16:17] op_sel:[0,1] op_sel_hi:[1,0]
	v_pk_mov_b32 v[22:23], v[20:21], v[18:19] op_sel:[1,0]
	v_mov_b32_e32 v21, v19
	v_pk_add_f32 v[18:19], v[22:23], v[20:21]
	v_mul_f32_e32 v20, v2, v2
	v_mul_f32_e32 v21, v3, v3
	v_pk_add_f32 v[18:19], v[18:19], v[18:19] op_sel:[0,1] op_sel_hi:[1,0]
	v_mov_b32_e32 v17, v20
	v_mov_b32_e32 v19, v21
	v_pk_add_f32 v[16:17], v[16:17], v[18:19]
	v_mul_f32_e32 v18, v7, v7
	v_mul_f32_e32 v20, v5, v5
	v_mul_f32_e32 v22, v0, v0
	v_mul_f32_e32 v23, v1, v1
	v_pk_fma_f32 v[18:19], v[6:7], v[6:7], v[18:19] op_sel_hi:[1,1,0]
	v_pk_fma_f32 v[20:21], v[4:5], v[4:5], v[20:21] op_sel_hi:[1,1,0]
	v_mov_b32_e32 v19, v22
	v_mov_b32_e32 v21, v23
	v_pk_add_f32 v[18:19], v[18:19], v[20:21]
	v_lshlrev_b64 v[22:23], 1, v[74:75]
	v_pk_add_f32 v[16:17], v[16:17], v[18:19]
	v_and_b32_e32 v18, 64, v181
	v_add_f32_e32 v16, v16, v17
	v_xor_b32_e32 v17, 16, v181
	v_add_u32_e32 v18, 64, v18
	v_cmp_lt_i32_e32 vcc, v17, v18
	s_nop 1
	v_cndmask_b32_e32 v17, v181, v17, vcc
	v_lshlrev_b32_e32 v17, 2, v17
	ds_bpermute_b32 v17, v17, v16
	s_waitcnt lgkmcnt(0)
	v_add_f32_e32 v16, v16, v17
	v_xor_b32_e32 v17, 32, v181
	v_cmp_lt_i32_e32 vcc, v17, v18
	s_nop 1
	v_cndmask_b32_e32 v17, v181, v17, vcc
	v_lshlrev_b32_e32 v17, 2, v17
	ds_bpermute_b32 v17, v17, v16
	s_waitcnt lgkmcnt(0)
; __device__ __forceinline__ unsigned pk2(float lo, float hi) { return f2bf(lo) | (f2bf(hi) << 16); }
; __device__ __forceinline__ void ret_out_phase(const Ctx& C, const bf16* PROJ, const bf16* ST, bf16* MIX, const float* decay_logit, const float* ret_gain) {
;     ...
;         const float rstd = 1.0f / sqrtf(ss * (1.f / 64.f) + RMS_EPS);
;         const size_t tok = (size_t)b * SEQ + t0 + i;
;         const bf16* rg = PROJ + tok * INW + 1536 + h * 64 + 4 * g;
;         bf16* mo = MIX + tok * DM + h * 64 + 4 * g;
; #pragma unroll
;         for (int dt = 0; dt < 4; ++dt) { const f32x4 gn = *(const f32x4*)(ret_gain + h * 64 + 16 * dt + 4 * g);
;             const v2u gw = *(const v2u*)(rg + 16 * dt);
;             float z[4] = {bflo(gw[0]), bfhi(gw[0]), bflo(gw[1]), bfhi(gw[1])}, y[4];
; #pragma unroll
;             for (int j = 0; j < 4; ++j) { const float sil = z[j] / (1.0f + __expf(-z[j])); y[j] = o[dt][j] * rstd * gn[j] * sil; }
;             v2u w; w.x = pk2(y[0], y[1]); w.y = pk2(y[2], y[3]);
;             *(v2u*)(mo + 16 * dt) = w; }
	v_add_f32_e32 v16, v16, v17
	v_fmamk_f32 v16, v16, 0x3c800000, v178
	v_cmp_gt_f32_e32 vcc, s91, v16
	v_mul_f32_e32 v17, 0x4f800000, v16
	s_nop 0
	v_cndmask_b32_e32 v16, v16, v17, vcc
	v_sqrt_f32_e32 v17, v16
	s_nop 0
	v_add_u32_e32 v18, -1, v17
	v_fma_f32 v19, -v18, v17, v16
	v_cmp_ge_f32_e64 s[0:1], 0, v19
	v_add_u32_e32 v19, 1, v17
	s_nop 0
	v_cndmask_b32_e64 v18, v17, v18, s[0:1]
	v_fma_f32 v17, -v19, v17, v16
	v_cmp_lt_f32_e64 s[0:1], 0, v17
	s_nop 1
	v_cndmask_b32_e64 v17, v18, v19, s[0:1]
	v_mul_f32_e32 v18, 0x37800000, v17
	v_cndmask_b32_e32 v17, v17, v18, vcc
	v_cmp_class_f32_e32 vcc, v16, v179
	s_nop 1
	v_cndmask_b32_e32 v16, v17, v16, vcc
	v_div_scale_f32 v17, s[0:1], v16, v16, 1.0
	v_rcp_f32_e32 v18, v17
	s_or_b32 s0, s11, s10
	v_fma_f32 v19, -v17, v18, 1.0
	v_fmac_f32_e32 v18, v19, v18
	v_div_scale_f32 v19, vcc, 1.0, v16, 1.0
	v_mul_f32_e32 v20, v19, v18
	v_fma_f32 v21, -v17, v20, v19
	v_fmac_f32_e32 v20, v21, v18
	v_fma_f32 v17, -v17, v20, v19
	v_div_fmas_f32 v17, v17, v18, v20
	v_mov_b32_e32 v19, s9
	v_or_b32_e32 v18, s0, v72
	v_mov_b64_e32 v[20:21], s[20:21]
	v_mad_u64_u32 v[20:21], s[0:1], v18, s90, v[20:21]
	v_lshlrev_b64 v[18:19], 11, v[18:19]
	v_mad_i32_i24 v21, s9, v186, v21
	v_lshl_add_u64 v[18:19], s[34:35], 0, v[18:19]
	v_lshl_add_u64 v[20:21], v[20:21], 0, s[2:3]
	v_lshl_add_u64 v[18:19], v[18:19], 0, s[2:3]
	s_lshl_b32 s2, s8, 8
	v_lshl_add_u64 v[20:21], v[20:21], 0, v[22:23]
	v_lshl_add_u64 v[18:19], v[18:19], 0, v[22:23]
	v_lshl_add_u64 v[22:23], v[78:79], 0, s[2:3]
	global_load_dwordx4 v[24:27], v[22:23], off
	global_load_dwordx2 v[28:29], v[20:21], off offset:3072
	v_div_fixup_f32 v16, v17, v16, 1.0
	s_cmpk_gt_i32 s7, 0x7fff
	s_waitcnt vmcnt(0)
	v_and_b32_e32 v37, 0xffff0000, v28
	v_lshlrev_b32_e32 v17, 16, v29
	v_lshlrev_b32_e32 v31, 16, v28
	v_and_b32_e32 v36, 0xffff0000, v29
	v_mul_f32_e32 v29, 0xbfb8aa3b, v37
	v_mul_f32_e32 v28, 0xbfb8aa3b, v31
	v_exp_f32_e32 v30, v29
	v_mul_f32_e32 v29, 0xbfb8aa3b, v17
	v_exp_f32_e32 v28, v28
	v_exp_f32_e32 v29, v29
	s_nop 0
	v_pk_add_f32 v[28:29], v[28:29], 1.0 op_sel_hi:[1,0]
	s_nop 0
	v_div_scale_f32 v32, s[0:1], v29, v29, v17
	v_rcp_f32_e32 v33, v32
	s_nop 0
	v_fma_f32 v34, -v32, v33, 1.0
	v_fmac_f32_e32 v33, v34, v33
	v_div_scale_f32 v34, vcc, v17, v29, v17
	v_mul_f32_e32 v35, v34, v33
	v_fma_f32 v38, -v32, v35, v34
	v_fmac_f32_e32 v35, v38, v33
	v_fma_f32 v32, -v32, v35, v34
	v_div_fmas_f32 v32, v32, v33, v35
	v_div_fixup_f32 v29, v32, v29, v17
	v_div_scale_f32 v17, s[0:1], v28, v28, v31
	v_rcp_f32_e32 v32, v17
	s_nop 0
	v_fma_f32 v33, -v17, v32, 1.0
	v_fmac_f32_e32 v32, v33, v32
	v_div_scale_f32 v33, vcc, v31, v28, v31
	v_mul_f32_e32 v34, v33, v32
	v_fma_f32 v35, -v17, v34, v33
	v_fmac_f32_e32 v34, v35, v32
	v_fma_f32 v17, -v17, v34, v33
	v_div_fmas_f32 v17, v17, v32, v34
	v_mov_b32_e32 v33, v12
	v_mul_f32_e32 v12, 0xbfb8aa3b, v36
	v_div_fixup_f32 v28, v17, v28, v31
	v_exp_f32_e32 v31, v12
	v_mov_b32_e32 v32, v14
	v_pk_mul_f32 v[32:33], v[32:33], v[16:17] op_sel_hi:[1,0]
	v_mov_b32_e32 v34, v24
	v_pk_add_f32 v[30:31], v[30:31], 1.0 op_sel_hi:[1,0]
	v_mov_b32_e32 v35, v26
	v_div_scale_f32 v12, s[0:1], v31, v31, v36
	v_rcp_f32_e32 v14, v12
	v_pk_mul_f32 v[32:33], v[34:35], v[32:33]
	v_fma_f32 v17, -v12, v14, 1.0
	v_fmac_f32_e32 v14, v17, v14
	v_div_scale_f32 v17, vcc, v36, v31, v36
	v_mul_f32_e32 v24, v17, v14
	v_fma_f32 v26, -v12, v24, v17
	v_fmac_f32_e32 v24, v26, v14
	v_fma_f32 v12, -v12, v24, v17
	v_div_fmas_f32 v12, v12, v14, v24
	v_div_fixup_f32 v31, v12, v31, v36
	v_div_scale_f32 v12, s[0:1], v30, v30, v37
	v_rcp_f32_e32 v14, v12
	v_pk_mul_f32 v[28:29], v[28:29], v[32:33]
	v_fma_f32 v17, -v12, v14, 1.0
	v_fmac_f32_e32 v14, v17, v14
	v_div_scale_f32 v17, vcc, v37, v30, v37
	v_mul_f32_e32 v24, v17, v14
	v_fma_f32 v26, -v12, v24, v17
	v_fmac_f32_e32 v24, v26, v14
	v_fma_f32 v12, -v12, v24, v17
	v_div_fmas_f32 v12, v12, v14, v24
	v_div_fixup_f32 v30, v12, v30, v37
	v_mov_b32_e32 v12, v15
	v_pk_mul_f32 v[12:13], v[12:13], v[16:17] op_sel_hi:[1,0]
	v_mov_b32_e32 v26, v25
	v_pk_mul_f32 v[12:13], v[26:27], v[12:13]
	v_and_b32_sdwa v14, v29, v182 dst_sel:DWORD dst_unused:UNUSED_PAD src0_sel:WORD_1 src1_sel:DWORD
	v_pk_mul_f32 v[12:13], v[30:31], v[12:13]
	v_and_b32_sdwa v15, v28, v182 dst_sel:DWORD dst_unused:UNUSED_PAD src0_sel:WORD_1 src1_sel:DWORD
	v_and_b32_sdwa v17, v13, v182 dst_sel:DWORD dst_unused:UNUSED_PAD src0_sel:WORD_1 src1_sel:DWORD
	v_and_b32_sdwa v24, v12, v182 dst_sel:DWORD dst_unused:UNUSED_PAD src0_sel:WORD_1 src1_sel:DWORD
	v_add3_u32 v13, v13, v17, s86
	v_add3_u32 v12, v12, v24, s86
	v_add3_u32 v15, v28, v15, s86
	v_add3_u32 v14, v29, v14, s86
	v_and_b32_e32 v13, 0xffff0000, v13
	v_and_b32_e32 v12, 0xffff0000, v12
	v_or_b32_sdwa v13, v13, v14 dst_sel:DWORD dst_unused:UNUSED_PAD src0_sel:DWORD src1_sel:WORD_1
	v_or_b32_sdwa v12, v12, v15 dst_sel:DWORD dst_unused:UNUSED_PAD src0_sel:DWORD src1_sel:WORD_1
	global_store_dwordx2 v[18:19], v[12:13], off
	global_load_dwordx4 v[12:15], v[22:23], off offset:64
	s_nop 0
	global_load_dwordx2 v[24:25], v[20:21], off offset:3104
	s_waitcnt vmcnt(0)
; __device__ __forceinline__ unsigned pk2(float lo, float hi) { return f2bf(lo) | (f2bf(hi) << 16); }
; __device__ __forceinline__ void ret_out_phase(const Ctx& C, const bf16* PROJ, const bf16* ST, bf16* MIX, const float* decay_logit, const float* ret_gain) {
;     ...
;         for (int dt = 0; dt < 4; ++dt) { const f32x4 gn = *(const f32x4*)(ret_gain + h * 64 + 16 * dt + 4 * g);
;             const v2u gw = *(const v2u*)(rg + 16 * dt);
;             float z[4] = {bflo(gw[0]), bfhi(gw[0]), bflo(gw[1]), bfhi(gw[1])}, y[4];
; #pragma unroll
;             for (int j = 0; j < 4; ++j) { const float sil = z[j] / (1.0f + __expf(-z[j])); y[j] = o[dt][j] * rstd * gn[j] * sil; }
;             v2u w; w.x = pk2(y[0], y[1]); w.y = pk2(y[2], y[3]);
;             *(v2u*)(mo + 16 * dt) = w; }
	v_and_b32_e32 v33, 0xffff0000, v24
	v_lshlrev_b32_e32 v17, 16, v25
	v_lshlrev_b32_e32 v27, 16, v24
	v_and_b32_e32 v32, 0xffff0000, v25
	v_mul_f32_e32 v25, 0xbfb8aa3b, v33
	v_mul_f32_e32 v24, 0xbfb8aa3b, v27
	v_exp_f32_e32 v26, v25
	v_mul_f32_e32 v25, 0xbfb8aa3b, v17
	v_exp_f32_e32 v24, v24
	v_exp_f32_e32 v25, v25
	s_nop 0
	v_pk_add_f32 v[24:25], v[24:25], 1.0 op_sel_hi:[1,0]
	s_nop 0
	v_div_scale_f32 v28, s[0:1], v25, v25, v17
	v_rcp_f32_e32 v29, v28
	s_nop 0
	v_fma_f32 v30, -v28, v29, 1.0
	v_fmac_f32_e32 v29, v30, v29
	v_div_scale_f32 v30, vcc, v17, v25, v17
	v_mul_f32_e32 v31, v30, v29
	v_fma_f32 v34, -v28, v31, v30
	v_fmac_f32_e32 v31, v34, v29
	v_fma_f32 v28, -v28, v31, v30
	v_div_fmas_f32 v28, v28, v29, v31
	v_div_fixup_f32 v25, v28, v25, v17
	v_div_scale_f32 v17, s[0:1], v24, v24, v27
	v_rcp_f32_e32 v28, v17
	s_nop 0
	v_fma_f32 v29, -v17, v28, 1.0
	v_fmac_f32_e32 v28, v29, v28
	v_div_scale_f32 v29, vcc, v27, v24, v27
	v_mul_f32_e32 v30, v29, v28
	v_fma_f32 v31, -v17, v30, v29
	v_fmac_f32_e32 v30, v31, v28
	v_fma_f32 v17, -v17, v30, v29
	v_div_fmas_f32 v17, v17, v28, v30
	v_mov_b32_e32 v29, v8
	v_mul_f32_e32 v8, 0xbfb8aa3b, v32
	v_div_fixup_f32 v24, v17, v24, v27
	v_exp_f32_e32 v27, v8
	v_mov_b32_e32 v28, v10
	v_mov_b32_e32 v30, v12
	v_mov_b32_e32 v31, v14
	v_pk_add_f32 v[26:27], v[26:27], 1.0 op_sel_hi:[1,0]
	v_pk_mul_f32 v[28:29], v[28:29], v[16:17] op_sel_hi:[1,0]
	v_div_scale_f32 v8, s[0:1], v27, v27, v32
	v_rcp_f32_e32 v10, v8
	v_pk_mul_f32 v[28:29], v[30:31], v[28:29]
	v_fma_f32 v12, -v8, v10, 1.0
	v_fmac_f32_e32 v10, v12, v10
	v_div_scale_f32 v12, vcc, v32, v27, v32
	v_mul_f32_e32 v14, v12, v10
	v_fma_f32 v17, -v8, v14, v12
	v_fmac_f32_e32 v14, v17, v10
	v_fma_f32 v8, -v8, v14, v12
	v_div_fmas_f32 v8, v8, v10, v14
	v_div_fixup_f32 v27, v8, v27, v32
	v_div_scale_f32 v8, s[0:1], v26, v26, v33
	v_rcp_f32_e32 v10, v8
	v_pk_mul_f32 v[24:25], v[28:29], v[24:25]
	v_fma_f32 v12, -v8, v10, 1.0
	v_fmac_f32_e32 v10, v12, v10
	v_div_scale_f32 v12, vcc, v33, v26, v33
	v_mul_f32_e32 v14, v12, v10
	v_fma_f32 v17, -v8, v14, v12
	v_fmac_f32_e32 v14, v17, v10
	v_fma_f32 v8, -v8, v14, v12
	v_div_fmas_f32 v8, v8, v10, v14
	v_div_fixup_f32 v26, v8, v26, v33
	v_mov_b32_e32 v8, v11
	v_pk_mul_f32 v[8:9], v[8:9], v[16:17] op_sel_hi:[1,0]
	v_mov_b32_e32 v14, v13
	v_pk_mul_f32 v[8:9], v[14:15], v[8:9]
	v_and_b32_sdwa v10, v25, v182 dst_sel:DWORD dst_unused:UNUSED_PAD src0_sel:WORD_1 src1_sel:DWORD
	v_pk_mul_f32 v[8:9], v[8:9], v[26:27]
	v_and_b32_sdwa v11, v24, v182 dst_sel:DWORD dst_unused:UNUSED_PAD src0_sel:WORD_1 src1_sel:DWORD
	v_and_b32_sdwa v12, v9, v182 dst_sel:DWORD dst_unused:UNUSED_PAD src0_sel:WORD_1 src1_sel:DWORD
	v_and_b32_sdwa v13, v8, v182 dst_sel:DWORD dst_unused:UNUSED_PAD src0_sel:WORD_1 src1_sel:DWORD
	v_add3_u32 v9, v9, v12, s86
	v_add3_u32 v8, v8, v13, s86
	v_add3_u32 v11, v24, v11, s86
	v_add3_u32 v10, v25, v10, s86
	v_and_b32_e32 v9, 0xffff0000, v9
	v_and_b32_e32 v8, 0xffff0000, v8
	v_or_b32_sdwa v9, v9, v10 dst_sel:DWORD dst_unused:UNUSED_PAD src0_sel:DWORD src1_sel:WORD_1
	v_or_b32_sdwa v8, v8, v11 dst_sel:DWORD dst_unused:UNUSED_PAD src0_sel:DWORD src1_sel:WORD_1
	global_store_dwordx2 v[18:19], v[8:9], off offset:32
	global_load_dwordx4 v[8:11], v[22:23], off offset:128
	s_nop 0
	global_load_dwordx2 v[12:13], v[20:21], off offset:3136
	s_waitcnt vmcnt(0)
; __device__ __forceinline__ unsigned pk2(float lo, float hi) { return f2bf(lo) | (f2bf(hi) << 16); }
; __device__ __forceinline__ void ret_out_phase(const Ctx& C, const bf16* PROJ, const bf16* ST, bf16* MIX, const float* decay_logit, const float* ret_gain) {
;     ...
;         for (int dt = 0; dt < 4; ++dt) { const f32x4 gn = *(const f32x4*)(ret_gain + h * 64 + 16 * dt + 4 * g);
;             const v2u gw = *(const v2u*)(rg + 16 * dt);
;             float z[4] = {bflo(gw[0]), bfhi(gw[0]), bflo(gw[1]), bfhi(gw[1])}, y[4];
; #pragma unroll
;             for (int j = 0; j < 4; ++j) { const float sil = z[j] / (1.0f + __expf(-z[j])); y[j] = o[dt][j] * rstd * gn[j] * sil; }
;             v2u w; w.x = pk2(y[0], y[1]); w.y = pk2(y[2], y[3]);
;             *(v2u*)(mo + 16 * dt) = w; }
	v_and_b32_e32 v29, 0xffff0000, v12
	v_lshlrev_b32_e32 v15, 16, v13
	v_lshlrev_b32_e32 v17, 16, v12
	v_and_b32_e32 v28, 0xffff0000, v13
	v_mul_f32_e32 v13, 0xbfb8aa3b, v29
	v_mul_f32_e32 v12, 0xbfb8aa3b, v17
	v_exp_f32_e32 v14, v13
	v_mul_f32_e32 v13, 0xbfb8aa3b, v15
	v_exp_f32_e32 v12, v12
	v_exp_f32_e32 v13, v13
	s_nop 0
	v_pk_add_f32 v[12:13], v[12:13], 1.0 op_sel_hi:[1,0]
	s_nop 0
	v_div_scale_f32 v24, s[0:1], v13, v13, v15
	v_rcp_f32_e32 v25, v24
	s_nop 0
	v_fma_f32 v26, -v24, v25, 1.0
	v_fmac_f32_e32 v25, v26, v25
	v_div_scale_f32 v26, vcc, v15, v13, v15
	v_mul_f32_e32 v27, v26, v25
	v_fma_f32 v30, -v24, v27, v26
	v_fmac_f32_e32 v27, v30, v25
	v_fma_f32 v24, -v24, v27, v26
	v_div_fmas_f32 v24, v24, v25, v27
	v_div_fixup_f32 v13, v24, v13, v15
	v_div_scale_f32 v15, s[0:1], v12, v12, v17
	v_rcp_f32_e32 v24, v15
	s_nop 0
	v_fma_f32 v25, -v15, v24, 1.0
	v_fmac_f32_e32 v24, v25, v24
	v_div_scale_f32 v25, vcc, v17, v12, v17
	v_mul_f32_e32 v26, v25, v24
	v_fma_f32 v27, -v15, v26, v25
	v_fmac_f32_e32 v26, v27, v24
	v_fma_f32 v15, -v15, v26, v25
	v_div_fmas_f32 v15, v15, v24, v26
	v_mov_b32_e32 v25, v4
	v_mul_f32_e32 v4, 0xbfb8aa3b, v28
	v_div_fixup_f32 v12, v15, v12, v17
	v_exp_f32_e32 v15, v4
	v_mov_b32_e32 v24, v6
	v_mov_b32_e32 v26, v8
	v_mov_b32_e32 v27, v10
	v_pk_add_f32 v[14:15], v[14:15], 1.0 op_sel_hi:[1,0]
	v_pk_mul_f32 v[24:25], v[24:25], v[16:17] op_sel_hi:[1,0]
	v_div_scale_f32 v4, s[0:1], v15, v15, v28
	v_rcp_f32_e32 v6, v4
	v_pk_mul_f32 v[24:25], v[26:27], v[24:25]
	v_fma_f32 v8, -v4, v6, 1.0
	v_fmac_f32_e32 v6, v8, v6
	v_div_scale_f32 v8, vcc, v28, v15, v28
	v_mul_f32_e32 v10, v8, v6
	v_fma_f32 v17, -v4, v10, v8
	v_fmac_f32_e32 v10, v17, v6
	v_fma_f32 v4, -v4, v10, v8
	v_div_fmas_f32 v4, v4, v6, v10
	v_div_fixup_f32 v15, v4, v15, v28
	v_div_scale_f32 v4, s[0:1], v14, v14, v29
	v_rcp_f32_e32 v6, v4
	v_pk_mul_f32 v[12:13], v[24:25], v[12:13]
	v_fma_f32 v8, -v4, v6, 1.0
	v_fmac_f32_e32 v6, v8, v6
	v_div_scale_f32 v8, vcc, v29, v14, v29
	v_mul_f32_e32 v10, v8, v6
	v_fma_f32 v17, -v4, v10, v8
	v_fmac_f32_e32 v10, v17, v6
	v_fma_f32 v4, -v4, v10, v8
	v_div_fmas_f32 v4, v4, v6, v10
	v_div_fixup_f32 v14, v4, v14, v29
	v_mov_b32_e32 v4, v7
	v_pk_mul_f32 v[4:5], v[4:5], v[16:17] op_sel_hi:[1,0]
	v_mov_b32_e32 v10, v9
	v_pk_mul_f32 v[4:5], v[10:11], v[4:5]
	v_and_b32_sdwa v6, v13, v182 dst_sel:DWORD dst_unused:UNUSED_PAD src0_sel:WORD_1 src1_sel:DWORD
	v_pk_mul_f32 v[4:5], v[4:5], v[14:15]
	v_and_b32_sdwa v7, v12, v182 dst_sel:DWORD dst_unused:UNUSED_PAD src0_sel:WORD_1 src1_sel:DWORD
	v_and_b32_sdwa v8, v5, v182 dst_sel:DWORD dst_unused:UNUSED_PAD src0_sel:WORD_1 src1_sel:DWORD
	v_and_b32_sdwa v9, v4, v182 dst_sel:DWORD dst_unused:UNUSED_PAD src0_sel:WORD_1 src1_sel:DWORD
	v_add3_u32 v5, v5, v8, s86
	v_add3_u32 v4, v4, v9, s86
	v_add3_u32 v7, v12, v7, s86
	v_add3_u32 v6, v13, v6, s86
	v_and_b32_e32 v5, 0xffff0000, v5
	v_and_b32_e32 v4, 0xffff0000, v4
	v_or_b32_sdwa v5, v5, v6 dst_sel:DWORD dst_unused:UNUSED_PAD src0_sel:DWORD src1_sel:WORD_1
	v_or_b32_sdwa v4, v4, v7 dst_sel:DWORD dst_unused:UNUSED_PAD src0_sel:DWORD src1_sel:WORD_1
	global_store_dwordx2 v[18:19], v[4:5], off offset:64
	global_load_dwordx4 v[4:7], v[22:23], off offset:192
	s_nop 0
	global_load_dwordx2 v[8:9], v[20:21], off offset:3168
	s_waitcnt vmcnt(0)
	v_and_b32_e32 v20, 0xffff0000, v8
	v_lshlrev_b32_e32 v11, 16, v9
	v_lshlrev_b32_e32 v12, 16, v8
	v_and_b32_e32 v17, 0xffff0000, v9
	v_mul_f32_e32 v9, 0xbfb8aa3b, v20
	v_mul_f32_e32 v8, 0xbfb8aa3b, v12
	v_exp_f32_e32 v10, v9
	v_mul_f32_e32 v9, 0xbfb8aa3b, v11
	v_exp_f32_e32 v8, v8
	v_exp_f32_e32 v9, v9
	s_nop 0
	v_pk_add_f32 v[8:9], v[8:9], 1.0 op_sel_hi:[1,0]
	s_nop 0
	v_div_scale_f32 v13, s[0:1], v9, v9, v11
	v_rcp_f32_e32 v14, v13
	s_nop 0
	v_fma_f32 v15, -v13, v14, 1.0
	v_fmac_f32_e32 v14, v15, v14
	v_div_scale_f32 v15, vcc, v11, v9, v11
	v_mul_f32_e32 v21, v15, v14
	v_fma_f32 v22, -v13, v21, v15
	v_fmac_f32_e32 v21, v22, v14
	v_fma_f32 v13, -v13, v21, v15
	v_div_fmas_f32 v13, v13, v14, v21
	v_div_fixup_f32 v9, v13, v9, v11
	v_div_scale_f32 v11, s[0:1], v8, v8, v12
	v_rcp_f32_e32 v13, v11
	s_nop 0
	v_fma_f32 v14, -v11, v13, 1.0
	v_fmac_f32_e32 v13, v14, v13
	v_div_scale_f32 v14, vcc, v12, v8, v12
	v_mul_f32_e32 v15, v14, v13
	v_fma_f32 v21, -v11, v15, v14
	v_fmac_f32_e32 v15, v21, v13
	v_fma_f32 v11, -v11, v15, v14
	v_div_fmas_f32 v11, v11, v13, v15
	v_mov_b32_e32 v13, v0
	v_mul_f32_e32 v0, 0xbfb8aa3b, v17
	v_div_fixup_f32 v8, v11, v8, v12
	v_exp_f32_e32 v11, v0
	v_mov_b32_e32 v12, v2
	v_mov_b32_e32 v14, v4
	v_pk_mul_f32 v[12:13], v[12:13], v[16:17] op_sel_hi:[1,0]
	v_pk_add_f32 v[10:11], v[10:11], 1.0 op_sel_hi:[1,0]
	v_mov_b32_e32 v15, v6
	v_div_scale_f32 v0, s[0:1], v11, v11, v17
	v_rcp_f32_e32 v2, v0
	v_pk_mul_f32 v[12:13], v[14:15], v[12:13]
	v_fma_f32 v4, -v0, v2, 1.0
	v_fmac_f32_e32 v2, v4, v2
	v_div_scale_f32 v4, vcc, v17, v11, v17
	v_mul_f32_e32 v6, v4, v2
	v_pk_mul_f32 v[8:9], v[12:13], v[8:9]
	v_fma_f32 v12, -v0, v6, v4
	v_fmac_f32_e32 v6, v12, v2
	v_fma_f32 v0, -v0, v6, v4
	v_div_fmas_f32 v0, v0, v2, v6
	v_div_fixup_f32 v11, v0, v11, v17
	v_div_scale_f32 v0, s[0:1], v10, v10, v20
	v_rcp_f32_e32 v2, v0
	s_nop 0
	v_fma_f32 v4, -v0, v2, 1.0
	v_fmac_f32_e32 v2, v4, v2
	v_div_scale_f32 v4, vcc, v20, v10, v20
	v_mul_f32_e32 v6, v4, v2
	v_fma_f32 v12, -v0, v6, v4
	v_fmac_f32_e32 v6, v12, v2
	v_fma_f32 v0, -v0, v6, v4
	v_div_fmas_f32 v0, v0, v2, v6
	v_div_fixup_f32 v10, v0, v10, v20
	v_mov_b32_e32 v0, v3
	v_pk_mul_f32 v[0:1], v[0:1], v[16:17] op_sel_hi:[1,0]
	v_mov_b32_e32 v6, v5
	v_pk_mul_f32 v[0:1], v[6:7], v[0:1]
	v_and_b32_sdwa v2, v9, v182 dst_sel:DWORD dst_unused:UNUSED_PAD src0_sel:WORD_1 src1_sel:DWORD
	v_pk_mul_f32 v[0:1], v[0:1], v[10:11]
	v_and_b32_sdwa v3, v8, v182 dst_sel:DWORD dst_unused:UNUSED_PAD src0_sel:WORD_1 src1_sel:DWORD
	v_and_b32_sdwa v4, v1, v182 dst_sel:DWORD dst_unused:UNUSED_PAD src0_sel:WORD_1 src1_sel:DWORD
	v_and_b32_sdwa v5, v0, v182 dst_sel:DWORD dst_unused:UNUSED_PAD src0_sel:WORD_1 src1_sel:DWORD
	v_add3_u32 v1, v1, v4, s86
	v_add3_u32 v0, v0, v5, s86
	v_add3_u32 v3, v8, v3, s86
	v_add3_u32 v2, v9, v2, s86
	v_and_b32_e32 v1, 0xffff0000, v1
	v_and_b32_e32 v0, 0xffff0000, v0
	v_or_b32_sdwa v1, v1, v2 dst_sel:DWORD dst_unused:UNUSED_PAD src0_sel:DWORD src1_sel:WORD_1
	v_or_b32_sdwa v0, v0, v3 dst_sel:DWORD dst_unused:UNUSED_PAD src0_sel:DWORD src1_sel:WORD_1
	global_store_dwordx2 v[18:19], v[0:1], off offset:96
	s_cbranch_scc0 .LBB0_300

; #define LAS __attribute__((address_space(3)))
; template <int DH, bool SOFTMAX, bool PREFETCH, class Spec>
; __device__ __forceinline__ void wave_attn(const Spec& sp, int nch, LAS bf16* vl, int lane, f32x4 (&oacc)[DH / 16], float& m_run, float& l_run) {
;     ...
;         WA_LOAD(0);
;         for (int c = 0; c < nch; ++c) {
;             bf16x8 kf[2][KS];
; #pragma unroll
;             for (int kt = 0; kt < 2; ++kt)
; #pragma unroll
;                 for (int ks = 0; ks < KS; ++ks) kf[kt][ks] = kn[kt][ks];
; #pragma unroll
;             for (int r = 0; r < NP; ++r) { const int p = lane + 64 * r, key = p / PPR, pc = p % PPR; *(LAS v4u*)(vl + key * P + pc * 8) = vn[r]; }
;             if (c + 1 < nch) WA_LOAD(c + 1);
;             f32x4 st[2];
; #pragma unroll
;             for (int kt = 0; kt < 2; ++kt) { st[kt] = (f32x4){0.f, 0.f, 0.f, 0.f};
; #pragma unroll
;                 for (int ks = 0; ks < KS; ++ks) st[kt] = __builtin_amdgcn_mfma_f32_16x16x32_bf16(kf[kt][ks], qf[ks], st[kt], 0, 0, 0); }
;             float pv[8];
; #pragma unroll
;             for (int kt = 0; kt < 2; ++kt)
; #pragma unroll
;                 for (int j = 0; j < 4; ++j) pv[kt * 4 + j] = sp.score(st[kt][j], i, 32 * c + 16 * kt + 4 * g + j);
;             if constexpr (SOFTMAX) {
;                 float cm = pv[0];
; #pragma unroll
;                 for (int r = 1; r < 8; ++r) cm = fmaxf(cm, pv[r]);
;                 cm = fmaxf(cm, __shfl_xor(cm, 16)); cm = fmaxf(cm, __shfl_xor(cm, 32));
;     __device__ __forceinline__ const bf16* krow(int j) const { return kb + (size_t)kpos(j) * INW; }
;     __device__ __forceinline__ const bf16* vrow(int j) const { return vb + (size_t)kpos(j) * INW; }
.LBB0_323:
	s_waitcnt vmcnt(4)
	v_mov_b64_e32 v[170:171], v[34:35]
	v_mov_b64_e32 v[162:163], v[26:27]
	v_mov_b64_e32 v[168:169], v[32:33]
	v_add_u32_e32 v32, s10, v88
	v_mov_b64_e32 v[160:161], v[24:25]
	v_subrev_u32_e32 v24, 32, v32
	v_mov_b64_e32 v[158:159], v[30:31]
	v_lshlrev_b32_e32 v24, s2, v24
	v_mov_b64_e32 v[156:157], v[28:29]
	s_waitcnt vmcnt(3)
	ds_write_b128 v122, v[40:43]
	s_waitcnt vmcnt(2)
	ds_write_b128 v123, v[44:47]
	s_waitcnt vmcnt(1)
	ds_write_b128 v124, v[48:51]
	s_waitcnt vmcnt(0)
	ds_write_b128 v125, v[52:55]
	v_add_u32_e32 v24, s18, v24
	v_add_lshl_u32 v32, v32, -16, s2
	v_add_u32_e32 v40, s10, v121
	v_med3_i32 v24, v24, 0, v187
	v_add_u32_e32 v32, s18, v32
	v_lshlrev_b32_e32 v40, s2, v40
	v_add_u32_e32 v44, s10, v120
	v_mov_b32_e32 v173, v136
	v_mul_u32_u24_e32 v136, 0x1c00, v24
	v_med3_i32 v32, v32, 0, v187
	v_add_u32_e32 v40, s18, v40
	v_lshlrev_b32_e32 v44, s2, v44
	v_add_u32_e32 v48, s10, v119
	v_mov_b64_e32 v[166:167], v[38:39]
	v_lshl_add_u64 v[24:25], v[74:75], 0, v[136:137]
	v_mul_u32_u24_e32 v136, 0x1c00, v32
	v_med3_i32 v40, v40, 0, v187
	v_add_u32_e32 v44, s18, v44
	v_lshlrev_b32_e32 v48, s2, v48
	v_add_u32_e32 v52, s10, v118
	v_mov_b64_e32 v[164:165], v[36:37]
	v_lshl_add_u64 v[32:33], v[74:75], 0, v[136:137]
	v_mul_u32_u24_e32 v136, 0x1c00, v40
	v_med3_i32 v44, v44, 0, v187
	v_add_u32_e32 v48, s18, v48
	v_lshlrev_b32_e32 v52, s2, v52
	v_lshl_add_u64 v[40:41], v[76:77], 0, v[136:137]
	v_mul_u32_u24_e32 v136, 0x1c00, v44
	v_med3_i32 v48, v48, 0, v187
	v_add_u32_e32 v52, s18, v52
	v_mfma_f32_16x16x32_bf16 v[156:159], v[156:159], v[16:19], 0
	v_lshl_add_u64 v[44:45], v[78:79], 0, v[136:137]
	v_mul_u32_u24_e32 v136, 0x1c00, v48
	v_med3_i32 v52, v52, 0, v187
	v_lshl_add_u64 v[48:49], v[80:81], 0, v[136:137]
	v_mul_u32_u24_e32 v136, 0x1c00, v52
	v_lshl_add_u64 v[52:53], v[82:83], 0, v[136:137]
	v_add_u32_e32 v136, s10, v95
	v_mov_b32_e32 v172, v70
	v_mfma_f32_16x16x32_bf16 v[156:159], v[160:163], v[20:23], v[156:159]
	v_subrev_u32_e32 v70, 64, v136
	v_lshlrev_b32_e32 v70, s2, v70
	v_add_u32_e32 v70, s18, v70
	v_mfma_f32_16x16x32_bf16 v[160:163], v[164:167], v[16:19], 0
	v_add_u32_e32 v166, s10, v117
	v_subrev_u32_e32 v141, 64, v166
	v_sub_u32_e32 v164, 64, v166
	v_max_i32_e32 v141, v141, v164
	v_cmp_gt_u32_e64 s[0:1], s84, v70
	v_lshlrev_b32_e32 v70, s2, v141
	v_cmp_gt_u32_e32 vcc, s88, v141
	v_cvt_f32_i32_e32 v141, v70
	v_mov_b32_e32 v70, v156
	s_and_b64 vcc, s[0:1], vcc
	v_sub_u32_e32 v156, 63, v166
	v_pk_mul_f32 v[164:165], v[70:71], v[140:141]
	v_subrev_u32_e32 v141, 63, v166
	v_sub_f32_e32 v70, v164, v165
	v_mul_f32_e32 v70, 0x3fb8aa3b, v70
	v_cndmask_b32_e32 v164, v188, v70, vcc
	v_subrev_u32_e32 v70, 63, v136
	v_lshlrev_b32_e32 v70, s2, v70
	v_max_i32_e32 v141, v141, v156
	v_add_u32_e32 v70, s18, v70
	v_cmp_gt_u32_e64 s[0:1], s84, v70
	v_lshlrev_b32_e32 v70, s2, v141
	v_cmp_gt_u32_e32 vcc, s88, v141
	v_cvt_f32_i32_e32 v141, v70
	v_mov_b32_e32 v70, v157
	s_and_b64 vcc, vcc, s[0:1]
	v_mfma_f32_16x16x32_bf16 v[160:163], v[168:171], v[20:23], v[160:163]
	v_mul_f32_e64 v156, v70, v140
	v_mul_f32_e64 v157, v71, v141
	v_subrev_u32_e32 v141, 62, v166
	v_sub_f32_e32 v70, v156, v157
	v_mul_f32_e32 v70, 0x3fb8aa3b, v70
	v_cndmask_b32_e32 v165, v188, v70, vcc
	v_subrev_u32_e32 v70, 62, v136
	v_sub_u32_e32 v156, 62, v166
	v_lshlrev_b32_e32 v70, s2, v70
	v_max_i32_e32 v141, v141, v156
	v_add_u32_e32 v70, s18, v70
	v_cmp_gt_u32_e64 s[0:1], s84, v70
	v_lshlrev_b32_e32 v70, s2, v141
	v_cmp_gt_u32_e32 vcc, s88, v141
	v_cvt_f32_i32_e32 v141, v70
	v_mov_b32_e32 v70, v158
	s_and_b64 vcc, vcc, s[0:1]
	global_load_dwordx4 v[28:31], v[24:25], off
	s_nop 0
	global_load_dwordx4 v[24:27], v[24:25], off offset:64
	v_pk_mul_f32 v[156:157], v[70:71], v[140:141]
	v_subrev_u32_e32 v141, 61, v166
	v_sub_f32_e32 v70, v156, v157
	v_mul_f32_e32 v70, 0x3fb8aa3b, v70
	v_cndmask_b32_e32 v158, v188, v70, vcc
	v_subrev_u32_e32 v70, 61, v136
	v_sub_u32_e32 v156, 61, v166
	v_lshlrev_b32_e32 v70, s2, v70
	v_max_i32_e32 v141, v141, v156
	v_add_u32_e32 v70, s18, v70
	v_cmp_gt_u32_e64 s[0:1], s84, v70
	v_lshlrev_b32_e32 v70, s2, v141
	v_cmp_gt_u32_e32 vcc, s88, v141
	v_cvt_f32_i32_e32 v141, v70
	v_mov_b32_e32 v70, v159
	s_and_b64 vcc, vcc, s[0:1]
	global_load_dwordx4 v[36:39], v[32:33], off
	s_nop 0
	global_load_dwordx4 v[32:35], v[32:33], off offset:64
	v_pk_mul_f32 v[156:157], v[70:71], v[140:141]
	v_subrev_u32_e32 v141, 48, v166
	v_sub_f32_e32 v70, v156, v157
	v_mul_f32_e32 v70, 0x3fb8aa3b, v70
	v_cndmask_b32_e32 v159, v188, v70, vcc
	v_subrev_u32_e32 v70, 48, v136
	v_sub_u32_e32 v156, 48, v166
	v_lshlrev_b32_e32 v70, s2, v70
	v_max_i32_e32 v141, v141, v156
	v_add_u32_e32 v70, s18, v70
	v_cmp_gt_u32_e64 s[0:1], s84, v70
	v_lshlrev_b32_e32 v70, s2, v141
	v_cmp_gt_u32_e32 vcc, s88, v141
	v_cvt_f32_i32_e32 v141, v70
	v_mov_b32_e32 v70, v160
	s_and_b64 vcc, vcc, s[0:1]
	global_load_dwordx4 v[40:43], v[40:41], off
	v_pk_mul_f32 v[156:157], v[70:71], v[140:141]
	v_subrev_u32_e32 v141, 47, v166
	v_sub_f32_e32 v70, v156, v157
	v_mul_f32_e32 v70, 0x3fb8aa3b, v70
	v_cndmask_b32_e32 v160, v188, v70, vcc
	v_subrev_u32_e32 v70, 47, v136
	v_sub_u32_e32 v156, 47, v166
	v_lshlrev_b32_e32 v70, s2, v70
	v_max_i32_e32 v141, v141, v156
	v_add_u32_e32 v70, s18, v70
	v_cmp_gt_u32_e64 s[0:1], s84, v70
	v_lshlrev_b32_e32 v70, s2, v141
	v_cmp_gt_u32_e32 vcc, s88, v141
	v_cvt_f32_i32_e32 v141, v70
	v_mov_b32_e32 v70, v161
	s_and_b64 vcc, vcc, s[0:1]
	global_load_dwordx4 v[44:47], v[44:45], off
	v_pk_mul_f32 v[156:157], v[70:71], v[140:141]
	v_subrev_u32_e32 v141, 46, v166
	v_sub_f32_e32 v70, v156, v157
	v_mul_f32_e32 v70, 0x3fb8aa3b, v70
	v_cndmask_b32_e32 v161, v188, v70, vcc
	v_subrev_u32_e32 v70, 46, v136
	v_sub_u32_e32 v156, 46, v166
	v_lshlrev_b32_e32 v70, s2, v70
	v_max_i32_e32 v141, v141, v156
	v_add_u32_e32 v70, s18, v70
	v_cmp_gt_u32_e64 s[0:1], s84, v70
	v_lshlrev_b32_e32 v70, s2, v141
	v_cmp_gt_u32_e32 vcc, s88, v141
	v_cvt_f32_i32_e32 v141, v70
	v_mov_b32_e32 v70, v162
	s_and_b64 vcc, vcc, s[0:1]
	global_load_dwordx4 v[48:51], v[48:49], off
	v_pk_mul_f32 v[156:157], v[70:71], v[140:141]
	v_sub_u32_e32 v141, 45, v166
	v_sub_f32_e32 v70, v156, v157
	v_mul_f32_e32 v70, 0x3fb8aa3b, v70
	v_cndmask_b32_e32 v162, v188, v70, vcc
	v_subrev_u32_e32 v70, 45, v136
	v_subrev_u32_e32 v136, 45, v166
	v_lshlrev_b32_e32 v70, s2, v70
	v_max_i32_e32 v136, v136, v141
	v_add_u32_e32 v70, s18, v70
	v_cmp_gt_u32_e64 s[0:1], s84, v70
	v_lshlrev_b32_e32 v70, s2, v136
	v_cvt_f32_i32_e32 v141, v70
	v_mov_b32_e32 v70, v163
	v_cmp_gt_u32_e32 vcc, s88, v136
	v_max_f32_e32 v136, v164, v165
	v_pk_mul_f32 v[156:157], v[70:71], v[140:141]
	s_and_b64 vcc, vcc, s[0:1]
	v_sub_f32_e32 v70, v156, v157
	v_mul_f32_e32 v70, 0x3fb8aa3b, v70
	v_max3_f32 v136, v136, v158, v159
	v_cndmask_b32_e32 v70, v188, v70, vcc
	v_max3_f32 v136, v136, v160, v161
	v_max3_f32 v136, v136, v162, v70
	ds_bpermute_b32 v141, v96, v136
	global_load_dwordx4 v[52:55], v[52:53], off
	s_add_i32 s10, s10, 32
	s_cmpk_lg_i32 s10, 0x80
	s_waitcnt lgkmcnt(0)
; __device__ __forceinline__ unsigned pk2(float lo, float hi) { return f2bf(lo) | (f2bf(hi) << 16); }
; template <int DH, bool SOFTMAX, bool PREFETCH, class Spec>
; __device__ __forceinline__ void wave_attn(const Spec& sp, int nch, LAS bf16* vl, int lane, f32x4 (&oacc)[DH / 16], float& m_run, float& l_run) {
;     ...
;             if constexpr (SOFTMAX) {
;                 float cm = pv[0];
; #pragma unroll
;                 for (int r = 1; r < 8; ++r) cm = fmaxf(cm, pv[r]);
;                 cm = fmaxf(cm, __shfl_xor(cm, 16)); cm = fmaxf(cm, __shfl_xor(cm, 32));
;                 const float mn = fmaxf(m_run, cm), sc = exp2f(m_run - mn);
;                 float ls = 0.f;
; #pragma unroll
;                 for (int r = 0; r < 8; ++r) { pv[r] = exp2f(pv[r] - mn); ls += pv[r]; }
;                 ls += __shfl_xor(ls, 16); ls += __shfl_xor(ls, 32);
;                 l_run = l_run * sc + ls; m_run = mn;
; #pragma unroll
;                 for (int dt = 0; dt < DT; ++dt) oacc[dt] = oacc[dt] * sc;
;             }
;             bf16x8 pb; { v4u t; t.x = pk2(pv[0], pv[1]); t.y = pk2(pv[2], pv[3]); t.z = pk2(pv[4], pv[5]); t.w = pk2(pv[6], pv[7]); pb = __builtin_bit_cast(bf16x8, t); }
;             if constexpr (USE_TR) {
; #pragma unroll
;                 for (int d4 = 0; d4 < DT; d4 += 4) { bf16x8 vf4[4]; read_vfrags4_trp<P>(vl + 16 * d4, i, g, vf4);
; #pragma unroll
;                     for (int dt = 0; dt < 4; ++dt) oacc[d4 + dt] = __builtin_amdgcn_mfma_f32_16x16x32_bf16(vf4[dt], pb, oacc[d4 + dt], 0, 0, 0); }
	v_max_f32_e32 v141, v141, v141
	v_max_f32_e32 v136, v136, v141
	ds_bpermute_b32 v141, v97, v136
	s_waitcnt lgkmcnt(0)
	v_max3_f32 v136, v173, v136, v141
	v_sub_f32_e32 v156, v164, v136
	v_sub_f32_e32 v158, v158, v136
	v_sub_f32_e32 v159, v159, v136
	v_exp_f32_e32 v156, v156
	v_sub_f32_e32 v160, v160, v136
	v_sub_f32_e32 v161, v161, v136
	v_mov_b32_e32 v157, v156
	v_sub_f32_e32 v156, v165, v136
	v_sub_f32_e32 v162, v162, v136
	v_sub_f32_e32 v70, v70, v136
	v_exp_f32_e32 v156, v156
	v_sub_f32_e32 v141, v173, v136
	v_exp_f32_e32 v158, v158
	v_mov_b32_e32 v163, v156
	v_exp_f32_e32 v159, v159
	v_add_f32_e32 v156, v157, v163
	v_exp_f32_e32 v160, v160
	v_add_f32_e32 v156, v158, v156
	v_exp_f32_e32 v161, v161
	v_add_f32_e32 v156, v159, v156
	v_exp_f32_e32 v162, v162
	v_add_f32_e32 v156, v160, v156
	v_exp_f32_e32 v70, v70
	v_add_f32_e32 v156, v161, v156
	v_add_f32_e32 v156, v162, v156
	v_mov_b32_e32 v164, v70
	v_add_f32_e32 v70, v164, v156
	v_bfe_u32 v165, v159, 16, 1
	v_exp_f32_e32 v141, v141
	v_bfe_u32 v166, v163, 16, 1
	v_add3_u32 v165, v159, v165, s86
	v_mov_b32_e32 v156, v141
	ds_bpermute_b32 v141, v96, v70
	v_pk_mul_f32 v[2:3], v[2:3], v[156:157] op_sel_hi:[1,0]
	v_pk_mul_f32 v[0:1], v[0:1], v[156:157] op_sel_hi:[1,0]
	v_pk_mul_f32 v[6:7], v[6:7], v[156:157] op_sel_hi:[1,0]
	v_pk_mul_f32 v[4:5], v[4:5], v[156:157] op_sel_hi:[1,0]
	s_waitcnt lgkmcnt(0)
	v_add_f32_e32 v70, v70, v141
	ds_bpermute_b32 v141, v97, v70
	v_pk_mul_f32 v[10:11], v[10:11], v[156:157] op_sel_hi:[1,0]
	v_pk_mul_f32 v[8:9], v[8:9], v[156:157] op_sel_hi:[1,0]
	v_pk_mul_f32 v[14:15], v[14:15], v[156:157] op_sel_hi:[1,0]
	v_pk_mul_f32 v[12:13], v[12:13], v[156:157] op_sel_hi:[1,0]
	s_waitcnt lgkmcnt(0)
	v_add_f32_e32 v70, v70, v141
	v_fmac_f32_e32 v70, v172, v156
	v_bfe_u32 v141, v164, 16, 1
	v_bfe_u32 v156, v161, 16, 1
	v_add3_u32 v156, v161, v156, s86
	v_add3_u32 v141, v164, v141, s86
	v_bfe_u32 v159, v157, 16, 1
	v_bfe_u32 v161, v158, 16, 1
	v_bfe_u32 v164, v160, 16, 1
	v_add3_u32 v163, v163, v166, s86
	v_bfe_u32 v166, v162, 16, 1
	v_add3_u32 v160, v160, v164, s86
	v_add3_u32 v158, v158, v161, s86
	v_add3_u32 v157, v157, v159, s86
	v_add3_u32 v162, v162, v166, s86
	v_lshrrev_b32_e32 v161, 16, v157
	v_lshrrev_b32_e32 v157, 16, v158
	v_lshrrev_b32_e32 v158, 16, v160
	v_lshrrev_b32_e32 v159, 16, v162
	v_and_or_b32 v158, v156, s85, v158
	v_and_or_b32 v157, v165, s85, v157
	v_and_or_b32 v156, v163, s85, v161
	ds_read_b64_tr_b16 v[172:173], v98
	ds_read_b64_tr_b16 v[168:169], v98 offset:32
	ds_read_b64_tr_b16 v[164:165], v98 offset:64
	ds_read_b64_tr_b16 v[160:161], v98 offset:96
	ds_read_b64_tr_b16 v[174:175], v99
	ds_read_b64_tr_b16 v[170:171], v99 offset:32
	ds_read_b64_tr_b16 v[166:167], v99 offset:64
	ds_read_b64_tr_b16 v[162:163], v99 offset:96
	s_waitcnt lgkmcnt(0)
	v_and_or_b32 v159, v141, s85, v159
	v_bfi_b32 v174, s87, v174, v174
	v_bfi_b32 v170, s87, v170, v170
	v_bfi_b32 v166, s87, v166, v166
	v_bfi_b32 v162, s87, v162, v162
	v_mfma_f32_16x16x32_bf16 v[0:3], v[172:175], v[156:159], v[0:3]
	v_mfma_f32_16x16x32_bf16 v[4:7], v[168:171], v[156:159], v[4:7]
	v_mfma_f32_16x16x32_bf16 v[8:11], v[164:167], v[156:159], v[8:11]
	v_mfma_f32_16x16x32_bf16 v[12:15], v[160:163], v[156:159], v[12:15]
	s_cbranch_scc1 .LBB0_323
	s_waitcnt vmcnt(7)
	v_mfma_f32_16x16x32_bf16 v[28:31], v[28:31], v[16:19], 0
	s_waitcnt vmcnt(3)
	ds_write_b128 v122, v[40:43]
	s_waitcnt vmcnt(2)
	ds_write_b128 v123, v[44:47]
	s_waitcnt vmcnt(1)
	ds_write_b128 v124, v[48:51]
	s_waitcnt vmcnt(0)
	ds_write_b128 v125, v[52:55]
	s_movk_i32 s0, 0x110
	v_mfma_f32_16x16x32_bf16 v[16:19], v[36:39], v[16:19], 0
	v_mfma_f32_16x16x32_bf16 v[24:27], v[24:27], v[20:23], v[28:31]
	v_mfma_f32_16x16x32_bf16 v[16:19], v[32:35], v[20:23], v[16:19]
	v_add_u32_e32 v20, s18, v133
	v_cmp_gt_u32_e32 vcc, s84, v20
	s_nop 4
	v_fma_f32 v20, v24, s76, -v134
	s_and_b64 vcc, s[38:39], vcc
	v_mul_f32_e32 v20, 0x3fb8aa3b, v20
	v_cndmask_b32_e32 v21, v188, v20, vcc
	v_add_u32_e32 v20, s18, v135
	v_cmp_gt_u32_e32 vcc, s84, v20
	v_fma_f32 v20, v25, s76, -v139
	s_and_b64 vcc, s[40:41], vcc
	v_mul_f32_e32 v20, 0x3fb8aa3b, v20
	v_cndmask_b32_e32 v22, v188, v20, vcc
	v_add_u32_e32 v20, s18, v142
	v_cmp_gt_u32_e32 vcc, s84, v20
	v_fma_f32 v20, v26, s76, -v143
	s_and_b64 vcc, s[42:43], vcc
	v_mul_f32_e32 v20, 0x3fb8aa3b, v20
	v_cndmask_b32_e32 v23, v188, v20, vcc
	v_add_u32_e32 v20, s18, v144
	v_cmp_gt_u32_e32 vcc, s84, v20
	v_fma_f32 v20, v27, s76, -v145
	s_and_b64 vcc, s[44:45], vcc
	v_mul_f32_e32 v20, 0x3fb8aa3b, v20
	v_cndmask_b32_e32 v24, v188, v20, vcc
	v_add_u32_e32 v20, s18, v146
	v_cmp_gt_u32_e32 vcc, s84, v20
	v_fma_f32 v16, v16, s76, -v147
	s_and_b64 vcc, s[46:47], vcc
	v_mul_f32_e32 v16, 0x3fb8aa3b, v16
	v_add_u32_e32 v20, s18, v148
	v_cndmask_b32_e32 v16, v188, v16, vcc
	v_cmp_gt_u32_e32 vcc, s84, v20
	v_fma_f32 v17, v17, s76, -v149
	s_and_b64 vcc, s[48:49], vcc
	v_mul_f32_e32 v17, 0x3fb8aa3b, v17
	v_add_u32_e32 v20, s18, v150
	v_cndmask_b32_e32 v17, v188, v17, vcc
	v_cmp_gt_u32_e32 vcc, s84, v20
	v_fma_f32 v18, v18, s76, -v151
	s_and_b64 vcc, s[50:51], vcc
	v_mul_f32_e32 v18, 0x3fb8aa3b, v18
	v_add_u32_e32 v20, s18, v152
	v_cndmask_b32_e32 v18, v188, v18, vcc
	v_cmp_gt_u32_e32 vcc, s84, v20
	v_fma_f32 v19, v19, s76, -v153
	v_max_f32_e32 v20, v21, v22
	s_and_b64 vcc, s[52:53], vcc
	v_mul_f32_e32 v19, 0x3fb8aa3b, v19
	v_max3_f32 v20, v20, v23, v24
	v_cndmask_b32_e32 v19, v188, v19, vcc
	v_max3_f32 v20, v20, v16, v17
	v_max3_f32 v20, v20, v18, v19
	ds_bpermute_b32 v25, v96, v20
	s_waitcnt lgkmcnt(0)
; #define LAS __attribute__((address_space(3)))
; __device__ __forceinline__ unsigned pk2(float lo, float hi) { return f2bf(lo) | (f2bf(hi) << 16); }
; template <int DH, bool SOFTMAX, bool PREFETCH, class Spec>
; __device__ __forceinline__ void wave_attn(const Spec& sp, int nch, LAS bf16* vl, int lane, f32x4 (&oacc)[DH / 16], float& m_run, float& l_run) {
;     ...
;             if constexpr (SOFTMAX) {
;                 float cm = pv[0];
; #pragma unroll
;                 for (int r = 1; r < 8; ++r) cm = fmaxf(cm, pv[r]);
;                 cm = fmaxf(cm, __shfl_xor(cm, 16)); cm = fmaxf(cm, __shfl_xor(cm, 32));
;                 const float mn = fmaxf(m_run, cm), sc = exp2f(m_run - mn);
;                 float ls = 0.f;
; #pragma unroll
;                 for (int r = 0; r < 8; ++r) { pv[r] = exp2f(pv[r] - mn); ls += pv[r]; }
;                 ls += __shfl_xor(ls, 16); ls += __shfl_xor(ls, 32);
;                 l_run = l_run * sc + ls; m_run = mn;
; #pragma unroll
;                 for (int dt = 0; dt < DT; ++dt) oacc[dt] = oacc[dt] * sc;
;             }
;             bf16x8 pb; { v4u t; t.x = pk2(pv[0], pv[1]); t.y = pk2(pv[2], pv[3]); t.z = pk2(pv[4], pv[5]); t.w = pk2(pv[6], pv[7]); pb = __builtin_bit_cast(bf16x8, t); }
;             if constexpr (USE_TR) {
; #pragma unroll
;                 for (int d4 = 0; d4 < DT; d4 += 4) { bf16x8 vf4[4]; read_vfrags4_trp<P>(vl + 16 * d4, i, g, vf4);
; #pragma unroll
;                     for (int dt = 0; dt < 4; ++dt) oacc[d4 + dt] = __builtin_amdgcn_mfma_f32_16x16x32_bf16(vf4[dt], pb, oacc[d4 + dt], 0, 0, 0); }
; __device__ __forceinline__ void mixer_phase(const Ctx& C, const bf16* PROJ, bf16* MIX, const float* decay_logit  , const float* ret_gain, const float* att_gain) {
;     ...
;                 if (pat > 0) {
;                     const float m0 = ML[row * 2], l0 = ML[row * 2 + 1];
;                     const float mn = fmaxf(m0, m), a = exp2f(m0 - mn), bb = exp2f(m - mn);
; #pragma unroll
;                     for (int dt = 0; dt < 4; ++dt) { const f32x4 p0 = *(LAS f32x4*)(orow + 16 * dt); o[dt] = p0 * a + o[dt] * bb; }
;                     l = l0 * a + l * bb; m = mn;
;                 }
	v_max_f32_e32 v25, v25, v25
	v_max_f32_e32 v20, v20, v25
	ds_bpermute_b32 v25, v97, v20
	s_waitcnt lgkmcnt(0)
	v_max3_f32 v20, v136, v20, v25
	v_sub_f32_e32 v21, v21, v20
	v_sub_f32_e32 v23, v23, v20
	v_sub_f32_e32 v24, v24, v20
	v_exp_f32_e32 v21, v21
	v_sub_f32_e32 v16, v16, v20
	v_sub_f32_e32 v17, v17, v20
	v_mov_b32_e32 v26, v21
	v_sub_f32_e32 v21, v22, v20
	v_sub_f32_e32 v18, v18, v20
	v_sub_f32_e32 v19, v19, v20
	v_exp_f32_e32 v21, v21
	v_sub_f32_e32 v25, v136, v20
	v_exp_f32_e32 v23, v23
	v_mov_b32_e32 v22, v21
	v_exp_f32_e32 v24, v24
	v_add_f32_e32 v21, v26, v22
	v_exp_f32_e32 v16, v16
	v_add_f32_e32 v21, v23, v21
	v_add_f32_e32 v21, v24, v21
	v_mov_b32_e32 v27, v16
	v_add_f32_e32 v16, v27, v21
	v_bfe_u32 v28, v24, 16, 1
	v_exp_f32_e32 v17, v17
	v_bfe_u32 v29, v22, 16, 1
	v_exp_f32_e32 v18, v18
	v_add_f32_e32 v16, v17, v16
	v_exp_f32_e32 v19, v19
	v_add_f32_e32 v16, v18, v16
	v_add_f32_e32 v21, v19, v16
	v_mov_b32_e32 v16, v25
	v_exp_f32_e32 v16, v16
	v_add3_u32 v22, v22, v29, s86
	v_add3_u32 v24, v24, v28, s86
	ds_bpermute_b32 v25, v96, v21
	v_pk_mul_f32 v[2:3], v[2:3], v[16:17] op_sel_hi:[1,0]
	v_pk_mul_f32 v[0:1], v[0:1], v[16:17] op_sel_hi:[1,0]
	v_pk_mul_f32 v[6:7], v[6:7], v[16:17] op_sel_hi:[1,0]
	v_pk_mul_f32 v[4:5], v[4:5], v[16:17] op_sel_hi:[1,0]
	s_waitcnt lgkmcnt(0)
	v_add_f32_e32 v21, v21, v25
	ds_bpermute_b32 v25, v97, v21
	v_pk_mul_f32 v[10:11], v[10:11], v[16:17] op_sel_hi:[1,0]
	v_pk_mul_f32 v[8:9], v[8:9], v[16:17] op_sel_hi:[1,0]
	v_pk_mul_f32 v[14:15], v[14:15], v[16:17] op_sel_hi:[1,0]
	v_pk_mul_f32 v[12:13], v[12:13], v[16:17] op_sel_hi:[1,0]
	s_waitcnt lgkmcnt(0)
	v_add_f32_e32 v21, v21, v25
	v_fmac_f32_e32 v21, v70, v16
	v_bfe_u32 v16, v19, 16, 1
	v_bfe_u32 v25, v17, 16, 1
	v_add3_u32 v17, v17, v25, s86
	v_add3_u32 v16, v19, v16, s86
	v_bfe_u32 v19, v26, 16, 1
	v_bfe_u32 v25, v23, 16, 1
	v_bfe_u32 v28, v27, 16, 1
	v_bfe_u32 v29, v18, 16, 1
	v_add3_u32 v18, v18, v29, s86
	v_add3_u32 v27, v27, v28, s86
	v_add3_u32 v23, v23, v25, s86
	v_add3_u32 v19, v26, v19, s86
	v_lshrrev_b32_e32 v25, 16, v19
	v_lshrrev_b32_e32 v23, 16, v23
	v_lshrrev_b32_e32 v26, 16, v27
	v_lshrrev_b32_e32 v18, 16, v18
	v_and_or_b32 v19, v16, s85, v18
	v_and_or_b32 v18, v17, s85, v26
	v_and_or_b32 v17, v24, s85, v23
	v_and_or_b32 v16, v22, s85, v25
	ds_read_b64_tr_b16 v[34:35], v98
	ds_read_b64_tr_b16 v[30:31], v98 offset:32
	ds_read_b64_tr_b16 v[26:27], v98 offset:64
	ds_read_b64_tr_b16 v[22:23], v98 offset:96
	ds_read_b64_tr_b16 v[36:37], v99
	ds_read_b64_tr_b16 v[32:33], v99 offset:32
	ds_read_b64_tr_b16 v[28:29], v99 offset:64
	ds_read_b64_tr_b16 v[24:25], v99 offset:96
	s_waitcnt lgkmcnt(0)
	s_andn2_b64 vcc, exec, s[4:5]
	v_bfi_b32 v36, s87, v36, v36
	v_bfi_b32 v32, s87, v32, v32
	v_bfi_b32 v28, s87, v28, v28
	v_bfi_b32 v24, s87, v24, v24
	v_mfma_f32_16x16x32_bf16 v[0:3], v[34:37], v[16:19], v[0:3]
	v_mfma_f32_16x16x32_bf16 v[4:7], v[30:33], v[16:19], v[4:7]
	v_mfma_f32_16x16x32_bf16 v[8:11], v[26:29], v[16:19], v[8:11]
	v_subrev_u32_e32 v29, s13, v155
	v_mfma_f32_16x16x32_bf16 v[12:15], v[22:25], v[16:19], v[12:15]
	v_mul_lo_u32 v16, v29, s0
	v_add_u32_e32 v42, v116, v16
	s_cbranch_vccnz .LBB0_327
	v_lshl_add_u32 v16, v29, 3, 0
	v_add_u32_e32 v16, 0x1a000, v16
	ds_read_b64 v[18:19], v16
	ds_read_b128 v[22:25], v42 offset:36864
	v_max_f32_e32 v17, v20, v20
	s_waitcnt lgkmcnt(1)
	v_max_f32_e32 v16, v18, v18
	v_max_f32_e32 v16, v16, v17
	v_sub_f32_e32 v17, v18, v16
	s_nop 1
	v_exp_f32_e32 v17, v17
	s_nop 0
	v_mov_b32_e32 v18, v17
	v_sub_f32_e32 v17, v20, v16
	s_waitcnt lgkmcnt(0)
	v_pk_mul_f32 v[22:23], v[22:23], v[18:19] op_sel_hi:[1,0]
	v_pk_mul_f32 v[24:25], v[24:25], v[18:19] op_sel_hi:[1,0]
	v_exp_f32_e32 v17, v17
	s_and_b64 vcc, exec, s[6:7]
	v_mov_b32_e32 v26, v17
	v_pk_fma_f32 v[2:3], v[2:3], v[26:27], v[24:25] op_sel_hi:[1,0,1]
	v_pk_fma_f32 v[0:1], v[0:1], v[26:27], v[22:23] op_sel_hi:[1,0,1]
	ds_read_b128 v[22:25], v42 offset:36928
	v_mov_b32_e32 v20, v19
	s_waitcnt lgkmcnt(0)
	v_pk_mul_f32 v[22:23], v[22:23], v[18:19] op_sel_hi:[1,0]
	v_pk_mul_f32 v[24:25], v[24:25], v[18:19] op_sel_hi:[1,0]
	v_pk_fma_f32 v[4:5], v[4:5], v[26:27], v[22:23] op_sel_hi:[1,0,1]
	v_pk_fma_f32 v[6:7], v[6:7], v[26:27], v[24:25] op_sel_hi:[1,0,1]
	ds_read_b128 v[22:25], v42 offset:36992
	s_waitcnt lgkmcnt(0)
	v_pk_mul_f32 v[22:23], v[18:19], v[22:23] op_sel_hi:[0,1]
	v_pk_mul_f32 v[24:25], v[18:19], v[24:25] op_sel_hi:[0,1]
	v_pk_fma_f32 v[10:11], v[10:11], v[26:27], v[24:25] op_sel_hi:[1,0,1]
	v_pk_fma_f32 v[8:9], v[8:9], v[26:27], v[22:23] op_sel_hi:[1,0,1]
	ds_read_b128 v[22:25], v42 offset:37056
	s_waitcnt lgkmcnt(0)
	v_pk_mul_f32 v[22:23], v[18:19], v[22:23] op_sel_hi:[0,1]
	v_pk_mul_f32 v[24:25], v[18:19], v[24:25] op_sel_hi:[0,1]
	v_pk_fma_f32 v[12:13], v[12:13], v[26:27], v[22:23] op_sel_hi:[1,0,1]
	v_mov_b32_e32 v19, v26
	v_mul_f32_e32 v22, v21, v26
	v_pk_fma_f32 v[14:15], v[14:15], v[26:27], v[24:25] op_sel_hi:[1,0,1]
	v_pk_fma_f32 v[18:19], v[20:21], v[18:19], v[22:23] op_sel_hi:[1,1,0]
	s_cbranch_vccz .LBB0_328
	v_mov_b32_e32 v17, v18
	s_mov_b64 s[10:11], -1
	v_mov_b64_e32 v[20:21], v[16:17]
	s_cbranch_execz .LBB0_329
	s_branch .LBB0_330

; __device__ __forceinline__ void peer_up_phase(const Ctx& C, const unsigned char* EU, bf16* XBN, float* RSS, float* xio, const float* gfinal, bool last, const float* SELG, const int* SELI) {
;     ...
;             v4u upA[8], upB[8];
; #pragma unroll
;             for (int k = 0; k < 8; ++k) { const int e = __builtin_amdgcn_readlane(vi0, k); upA[k] = *(const v4u*)(EU + (size_t)e * DM + 16 * gl); }
; #pragma unroll
;             for (int k = 0; k < 8; ++k) { const int e = __builtin_amdgcn_readlane(vi0, 8 + k); upB[k] = *(const v4u*)(EU + (size_t)e * DM + 16 * gl); }
;     ...
; #pragma unroll 1
;             for (int grp = 0; grp < 16; grp += 2) { USTEP(upA, grp); USTEP(upB, grp + 1); }
.Lupl_tok:
	s_add_i32 s2, s14, s20
	s_lshl_b32 s2, s2, 11
	s_add_u32 s16, s10, s2
	s_addc_u32 s17, s11, 0
	s_waitcnt vmcnt(0)
	ds_write_b64 v3, v[6:7]
	ds_write_b64 v3, v[8:9] offset:512
	global_load_dwordx2 v[10:11], v5, s[16:17]
	s_add_i32 s2, s20, 1
	s_and_b32 s2, s2, 31
	s_add_i32 s2, s2, s14
	s_lshl_b32 s2, s2, 9
	s_add_u32 s0, s6, s2
	s_addc_u32 s1, s7, 0
	global_load_dword v6, v4, s[0:1]
	global_load_dword v8, v4, s[0:1] offset:256
	s_add_u32 s0, s4, s2
	s_addc_u32 s1, s5, 0
	global_load_dword v7, v4, s[0:1]
	global_load_dword v9, v4, s[0:1] offset:256
	ds_read_b64 v[12:13], v2
	ds_read_b64 v[14:15], v2 offset:64
	ds_read_b64 v[16:17], v2 offset:128
	ds_read_b64 v[18:19], v2 offset:192
	ds_read_b64 v[20:21], v2 offset:256
	ds_read_b64 v[22:23], v2 offset:320
	ds_read_b64 v[24:25], v2 offset:384
	ds_read_b64 v[26:27], v2 offset:448
	ds_read_b64 v[28:29], v2 offset:512
	ds_read_b64 v[30:31], v2 offset:576
	ds_read_b64 v[32:33], v2 offset:640
	ds_read_b64 v[34:35], v2 offset:704
	ds_read_b64 v[36:37], v2 offset:768
	ds_read_b64 v[38:39], v2 offset:832
	ds_read_b64 v[40:41], v2 offset:896
	ds_read_b64 v[42:43], v2 offset:960
	v_mov_b64_e32 v[112:113], 0
	v_mov_b64_e32 v[114:115], 0
	v_mov_b64_e32 v[116:117], 0
	v_mov_b64_e32 v[118:119], 0
	v_mov_b64_e32 v[120:121], 0
	v_mov_b64_e32 v[122:123], 0
	v_mov_b64_e32 v[124:125], 0
	v_mov_b64_e32 v[126:127], 0
	s_waitcnt lgkmcnt(8)
	v_lshl_add_u32 v13, v13, 7, v1
	global_load_dwordx4 v[48:51], v13, s[8:9]
	v_lshl_add_u32 v15, v15, 7, v1
	global_load_dwordx4 v[52:55], v15, s[8:9]
	v_lshl_add_u32 v17, v17, 7, v1
	global_load_dwordx4 v[56:59], v17, s[8:9]
	v_lshl_add_u32 v19, v19, 7, v1
	global_load_dwordx4 v[60:63], v19, s[8:9]
	v_lshl_add_u32 v21, v21, 7, v1
	global_load_dwordx4 v[64:67], v21, s[8:9]
	v_lshl_add_u32 v23, v23, 7, v1
	global_load_dwordx4 v[68:71], v23, s[8:9]
	v_lshl_add_u32 v25, v25, 7, v1
	global_load_dwordx4 v[72:75], v25, s[8:9]
	v_lshl_add_u32 v27, v27, 7, v1
	global_load_dwordx4 v[76:79], v27, s[8:9]
	s_waitcnt lgkmcnt(0)
	v_lshl_add_u32 v29, v29, 7, v1
	global_load_dwordx4 v[80:83], v29, s[8:9]
	v_lshl_add_u32 v31, v31, 7, v1
	global_load_dwordx4 v[84:87], v31, s[8:9]
	v_lshl_add_u32 v33, v33, 7, v1
	global_load_dwordx4 v[88:91], v33, s[8:9]
	v_lshl_add_u32 v35, v35, 7, v1
	global_load_dwordx4 v[92:95], v35, s[8:9]
	v_lshl_add_u32 v37, v37, 7, v1
	global_load_dwordx4 v[96:99], v37, s[8:9]
	v_lshl_add_u32 v39, v39, 7, v1
	global_load_dwordx4 v[100:103], v39, s[8:9]
	v_lshl_add_u32 v41, v41, 7, v1
	global_load_dwordx4 v[104:107], v41, s[8:9]
	v_lshl_add_u32 v43, v43, 7, v1
	global_load_dwordx4 v[108:111], v43, s[8:9]
	s_waitcnt vmcnt(15)
	v_cvt_pk_f32_fp8_e32 v[144:145], v48
	v_cvt_pk_f32_fp8_sdwa v[146:147], v48 src0_sel:WORD_1
	v_cvt_pk_f32_fp8_e32 v[148:149], v49
	v_cvt_pk_f32_fp8_sdwa v[150:151], v49 src0_sel:WORD_1
	v_cvt_pk_f32_fp8_e32 v[152:153], v50
	v_cvt_pk_f32_fp8_sdwa v[154:155], v50 src0_sel:WORD_1
	v_cvt_pk_f32_fp8_e32 v[156:157], v51
	v_cvt_pk_f32_fp8_sdwa v[158:159], v51 src0_sel:WORD_1
	v_pk_fma_f32 v[112:113], v[144:145], v[12:13], v[112:113] op_sel_hi:[1,0,1]
	v_pk_fma_f32 v[114:115], v[146:147], v[12:13], v[114:115] op_sel_hi:[1,0,1]
	v_pk_fma_f32 v[116:117], v[148:149], v[12:13], v[116:117] op_sel_hi:[1,0,1]
	v_pk_fma_f32 v[118:119], v[150:151], v[12:13], v[118:119] op_sel_hi:[1,0,1]
	v_pk_fma_f32 v[120:121], v[152:153], v[12:13], v[120:121] op_sel_hi:[1,0,1]
	v_pk_fma_f32 v[122:123], v[154:155], v[12:13], v[122:123] op_sel_hi:[1,0,1]
	v_pk_fma_f32 v[124:125], v[156:157], v[12:13], v[124:125] op_sel_hi:[1,0,1]
	v_pk_fma_f32 v[126:127], v[158:159], v[12:13], v[126:127] op_sel_hi:[1,0,1]
	s_waitcnt vmcnt(14)
	v_cvt_pk_f32_fp8_e32 v[144:145], v52
	v_cvt_pk_f32_fp8_sdwa v[146:147], v52 src0_sel:WORD_1
	v_cvt_pk_f32_fp8_e32 v[148:149], v53
	v_cvt_pk_f32_fp8_sdwa v[150:151], v53 src0_sel:WORD_1
	v_cvt_pk_f32_fp8_e32 v[152:153], v54
	v_cvt_pk_f32_fp8_sdwa v[154:155], v54 src0_sel:WORD_1
	v_cvt_pk_f32_fp8_e32 v[156:157], v55
	v_cvt_pk_f32_fp8_sdwa v[158:159], v55 src0_sel:WORD_1
	v_pk_fma_f32 v[112:113], v[144:145], v[14:15], v[112:113] op_sel_hi:[1,0,1]
	v_pk_fma_f32 v[114:115], v[146:147], v[14:15], v[114:115] op_sel_hi:[1,0,1]
	v_pk_fma_f32 v[116:117], v[148:149], v[14:15], v[116:117] op_sel_hi:[1,0,1]
	v_pk_fma_f32 v[118:119], v[150:151], v[14:15], v[118:119] op_sel_hi:[1,0,1]
	v_pk_fma_f32 v[120:121], v[152:153], v[14:15], v[120:121] op_sel_hi:[1,0,1]
	v_pk_fma_f32 v[122:123], v[154:155], v[14:15], v[122:123] op_sel_hi:[1,0,1]
	v_pk_fma_f32 v[124:125], v[156:157], v[14:15], v[124:125] op_sel_hi:[1,0,1]
	v_pk_fma_f32 v[126:127], v[158:159], v[14:15], v[126:127] op_sel_hi:[1,0,1]
	s_waitcnt vmcnt(13)
	v_cvt_pk_f32_fp8_e32 v[144:145], v56
	v_cvt_pk_f32_fp8_sdwa v[146:147], v56 src0_sel:WORD_1
	v_cvt_pk_f32_fp8_e32 v[148:149], v57
	v_cvt_pk_f32_fp8_sdwa v[150:151], v57 src0_sel:WORD_1
	v_cvt_pk_f32_fp8_e32 v[152:153], v58
	v_cvt_pk_f32_fp8_sdwa v[154:155], v58 src0_sel:WORD_1
	v_cvt_pk_f32_fp8_e32 v[156:157], v59
	v_cvt_pk_f32_fp8_sdwa v[158:159], v59 src0_sel:WORD_1
	v_pk_fma_f32 v[112:113], v[144:145], v[16:17], v[112:113] op_sel_hi:[1,0,1]
	v_pk_fma_f32 v[114:115], v[146:147], v[16:17], v[114:115] op_sel_hi:[1,0,1]
	v_pk_fma_f32 v[116:117], v[148:149], v[16:17], v[116:117] op_sel_hi:[1,0,1]
	v_pk_fma_f32 v[118:119], v[150:151], v[16:17], v[118:119] op_sel_hi:[1,0,1]
	v_pk_fma_f32 v[120:121], v[152:153], v[16:17], v[120:121] op_sel_hi:[1,0,1]
	v_pk_fma_f32 v[122:123], v[154:155], v[16:17], v[122:123] op_sel_hi:[1,0,1]
	v_pk_fma_f32 v[124:125], v[156:157], v[16:17], v[124:125] op_sel_hi:[1,0,1]
	v_pk_fma_f32 v[126:127], v[158:159], v[16:17], v[126:127] op_sel_hi:[1,0,1]
	s_waitcnt vmcnt(12)
	v_cvt_pk_f32_fp8_e32 v[144:145], v60
	v_cvt_pk_f32_fp8_sdwa v[146:147], v60 src0_sel:WORD_1
	v_cvt_pk_f32_fp8_e32 v[148:149], v61
	v_cvt_pk_f32_fp8_sdwa v[150:151], v61 src0_sel:WORD_1
	v_cvt_pk_f32_fp8_e32 v[152:153], v62
	v_cvt_pk_f32_fp8_sdwa v[154:155], v62 src0_sel:WORD_1
	v_cvt_pk_f32_fp8_e32 v[156:157], v63
	v_cvt_pk_f32_fp8_sdwa v[158:159], v63 src0_sel:WORD_1
	v_pk_fma_f32 v[112:113], v[144:145], v[18:19], v[112:113] op_sel_hi:[1,0,1]
	v_pk_fma_f32 v[114:115], v[146:147], v[18:19], v[114:115] op_sel_hi:[1,0,1]
	v_pk_fma_f32 v[116:117], v[148:149], v[18:19], v[116:117] op_sel_hi:[1,0,1]
	v_pk_fma_f32 v[118:119], v[150:151], v[18:19], v[118:119] op_sel_hi:[1,0,1]
	v_pk_fma_f32 v[120:121], v[152:153], v[18:19], v[120:121] op_sel_hi:[1,0,1]
	v_pk_fma_f32 v[122:123], v[154:155], v[18:19], v[122:123] op_sel_hi:[1,0,1]
	v_pk_fma_f32 v[124:125], v[156:157], v[18:19], v[124:125] op_sel_hi:[1,0,1]
	v_pk_fma_f32 v[126:127], v[158:159], v[18:19], v[126:127] op_sel_hi:[1,0,1]
	s_waitcnt vmcnt(11)
	v_cvt_pk_f32_fp8_e32 v[144:145], v64
	v_cvt_pk_f32_fp8_sdwa v[146:147], v64 src0_sel:WORD_1
	v_cvt_pk_f32_fp8_e32 v[148:149], v65
	v_cvt_pk_f32_fp8_sdwa v[150:151], v65 src0_sel:WORD_1
	v_cvt_pk_f32_fp8_e32 v[152:153], v66
	v_cvt_pk_f32_fp8_sdwa v[154:155], v66 src0_sel:WORD_1
	v_cvt_pk_f32_fp8_e32 v[156:157], v67
	v_cvt_pk_f32_fp8_sdwa v[158:159], v67 src0_sel:WORD_1
	v_pk_fma_f32 v[112:113], v[144:145], v[20:21], v[112:113] op_sel_hi:[1,0,1]
	v_pk_fma_f32 v[114:115], v[146:147], v[20:21], v[114:115] op_sel_hi:[1,0,1]
	v_pk_fma_f32 v[116:117], v[148:149], v[20:21], v[116:117] op_sel_hi:[1,0,1]
	v_pk_fma_f32 v[118:119], v[150:151], v[20:21], v[118:119] op_sel_hi:[1,0,1]
	v_pk_fma_f32 v[120:121], v[152:153], v[20:21], v[120:121] op_sel_hi:[1,0,1]
	v_pk_fma_f32 v[122:123], v[154:155], v[20:21], v[122:123] op_sel_hi:[1,0,1]
	v_pk_fma_f32 v[124:125], v[156:157], v[20:21], v[124:125] op_sel_hi:[1,0,1]
	v_pk_fma_f32 v[126:127], v[158:159], v[20:21], v[126:127] op_sel_hi:[1,0,1]
	s_waitcnt vmcnt(10)
	v_cvt_pk_f32_fp8_e32 v[144:145], v68
	v_cvt_pk_f32_fp8_sdwa v[146:147], v68 src0_sel:WORD_1
	v_cvt_pk_f32_fp8_e32 v[148:149], v69
	v_cvt_pk_f32_fp8_sdwa v[150:151], v69 src0_sel:WORD_1
	v_cvt_pk_f32_fp8_e32 v[152:153], v70
	v_cvt_pk_f32_fp8_sdwa v[154:155], v70 src0_sel:WORD_1
	v_cvt_pk_f32_fp8_e32 v[156:157], v71
	v_cvt_pk_f32_fp8_sdwa v[158:159], v71 src0_sel:WORD_1
	v_pk_fma_f32 v[112:113], v[144:145], v[22:23], v[112:113] op_sel_hi:[1,0,1]
	v_pk_fma_f32 v[114:115], v[146:147], v[22:23], v[114:115] op_sel_hi:[1,0,1]
	v_pk_fma_f32 v[116:117], v[148:149], v[22:23], v[116:117] op_sel_hi:[1,0,1]
	v_pk_fma_f32 v[118:119], v[150:151], v[22:23], v[118:119] op_sel_hi:[1,0,1]
	v_pk_fma_f32 v[120:121], v[152:153], v[22:23], v[120:121] op_sel_hi:[1,0,1]
	v_pk_fma_f32 v[122:123], v[154:155], v[22:23], v[122:123] op_sel_hi:[1,0,1]
	v_pk_fma_f32 v[124:125], v[156:157], v[22:23], v[124:125] op_sel_hi:[1,0,1]
	v_pk_fma_f32 v[126:127], v[158:159], v[22:23], v[126:127] op_sel_hi:[1,0,1]
	s_waitcnt vmcnt(9)
	v_cvt_pk_f32_fp8_e32 v[144:145], v72
	v_cvt_pk_f32_fp8_sdwa v[146:147], v72 src0_sel:WORD_1
	v_cvt_pk_f32_fp8_e32 v[148:149], v73
	v_cvt_pk_f32_fp8_sdwa v[150:151], v73 src0_sel:WORD_1
	v_cvt_pk_f32_fp8_e32 v[152:153], v74
	v_cvt_pk_f32_fp8_sdwa v[154:155], v74 src0_sel:WORD_1
	v_cvt_pk_f32_fp8_e32 v[156:157], v75
	v_cvt_pk_f32_fp8_sdwa v[158:159], v75 src0_sel:WORD_1
	v_pk_fma_f32 v[112:113], v[144:145], v[24:25], v[112:113] op_sel_hi:[1,0,1]
	v_pk_fma_f32 v[114:115], v[146:147], v[24:25], v[114:115] op_sel_hi:[1,0,1]
	v_pk_fma_f32 v[116:117], v[148:149], v[24:25], v[116:117] op_sel_hi:[1,0,1]
	v_pk_fma_f32 v[118:119], v[150:151], v[24:25], v[118:119] op_sel_hi:[1,0,1]
	v_pk_fma_f32 v[120:121], v[152:153], v[24:25], v[120:121] op_sel_hi:[1,0,1]
	v_pk_fma_f32 v[122:123], v[154:155], v[24:25], v[122:123] op_sel_hi:[1,0,1]
	v_pk_fma_f32 v[124:125], v[156:157], v[24:25], v[124:125] op_sel_hi:[1,0,1]
	v_pk_fma_f32 v[126:127], v[158:159], v[24:25], v[126:127] op_sel_hi:[1,0,1]
	s_waitcnt vmcnt(8)
	v_cvt_pk_f32_fp8_e32 v[144:145], v76
	v_cvt_pk_f32_fp8_sdwa v[146:147], v76 src0_sel:WORD_1
	v_cvt_pk_f32_fp8_e32 v[148:149], v77
	v_cvt_pk_f32_fp8_sdwa v[150:151], v77 src0_sel:WORD_1
	v_cvt_pk_f32_fp8_e32 v[152:153], v78
	v_cvt_pk_f32_fp8_sdwa v[154:155], v78 src0_sel:WORD_1
	v_cvt_pk_f32_fp8_e32 v[156:157], v79
	v_cvt_pk_f32_fp8_sdwa v[158:159], v79 src0_sel:WORD_1
	v_pk_fma_f32 v[112:113], v[144:145], v[26:27], v[112:113] op_sel_hi:[1,0,1]
	v_pk_fma_f32 v[114:115], v[146:147], v[26:27], v[114:115] op_sel_hi:[1,0,1]
	v_pk_fma_f32 v[116:117], v[148:149], v[26:27], v[116:117] op_sel_hi:[1,0,1]
	v_pk_fma_f32 v[118:119], v[150:151], v[26:27], v[118:119] op_sel_hi:[1,0,1]
	v_pk_fma_f32 v[120:121], v[152:153], v[26:27], v[120:121] op_sel_hi:[1,0,1]
	v_pk_fma_f32 v[122:123], v[154:155], v[26:27], v[122:123] op_sel_hi:[1,0,1]
	v_pk_fma_f32 v[124:125], v[156:157], v[26:27], v[124:125] op_sel_hi:[1,0,1]
	v_pk_fma_f32 v[126:127], v[158:159], v[26:27], v[126:127] op_sel_hi:[1,0,1]
	s_waitcnt vmcnt(7)
	v_cvt_pk_f32_fp8_e32 v[144:145], v80
	v_cvt_pk_f32_fp8_sdwa v[146:147], v80 src0_sel:WORD_1
	v_cvt_pk_f32_fp8_e32 v[148:149], v81
	v_cvt_pk_f32_fp8_sdwa v[150:151], v81 src0_sel:WORD_1
	v_cvt_pk_f32_fp8_e32 v[152:153], v82
	v_cvt_pk_f32_fp8_sdwa v[154:155], v82 src0_sel:WORD_1
	v_cvt_pk_f32_fp8_e32 v[156:157], v83
	v_cvt_pk_f32_fp8_sdwa v[158:159], v83 src0_sel:WORD_1
	v_pk_fma_f32 v[112:113], v[144:145], v[28:29], v[112:113] op_sel_hi:[1,0,1]
	v_pk_fma_f32 v[114:115], v[146:147], v[28:29], v[114:115] op_sel_hi:[1,0,1]
	v_pk_fma_f32 v[116:117], v[148:149], v[28:29], v[116:117] op_sel_hi:[1,0,1]
	v_pk_fma_f32 v[118:119], v[150:151], v[28:29], v[118:119] op_sel_hi:[1,0,1]
	v_pk_fma_f32 v[120:121], v[152:153], v[28:29], v[120:121] op_sel_hi:[1,0,1]
	v_pk_fma_f32 v[122:123], v[154:155], v[28:29], v[122:123] op_sel_hi:[1,0,1]
	v_pk_fma_f32 v[124:125], v[156:157], v[28:29], v[124:125] op_sel_hi:[1,0,1]
	v_pk_fma_f32 v[126:127], v[158:159], v[28:29], v[126:127] op_sel_hi:[1,0,1]
	s_waitcnt vmcnt(6)
	v_cvt_pk_f32_fp8_e32 v[144:145], v84
	v_cvt_pk_f32_fp8_sdwa v[146:147], v84 src0_sel:WORD_1
	v_cvt_pk_f32_fp8_e32 v[148:149], v85
	v_cvt_pk_f32_fp8_sdwa v[150:151], v85 src0_sel:WORD_1
	v_cvt_pk_f32_fp8_e32 v[152:153], v86
	v_cvt_pk_f32_fp8_sdwa v[154:155], v86 src0_sel:WORD_1
	v_cvt_pk_f32_fp8_e32 v[156:157], v87
	v_cvt_pk_f32_fp8_sdwa v[158:159], v87 src0_sel:WORD_1
	v_pk_fma_f32 v[112:113], v[144:145], v[30:31], v[112:113] op_sel_hi:[1,0,1]
	v_pk_fma_f32 v[114:115], v[146:147], v[30:31], v[114:115] op_sel_hi:[1,0,1]
	v_pk_fma_f32 v[116:117], v[148:149], v[30:31], v[116:117] op_sel_hi:[1,0,1]
	v_pk_fma_f32 v[118:119], v[150:151], v[30:31], v[118:119] op_sel_hi:[1,0,1]
	v_pk_fma_f32 v[120:121], v[152:153], v[30:31], v[120:121] op_sel_hi:[1,0,1]
	v_pk_fma_f32 v[122:123], v[154:155], v[30:31], v[122:123] op_sel_hi:[1,0,1]
	v_pk_fma_f32 v[124:125], v[156:157], v[30:31], v[124:125] op_sel_hi:[1,0,1]
	v_pk_fma_f32 v[126:127], v[158:159], v[30:31], v[126:127] op_sel_hi:[1,0,1]
	s_waitcnt vmcnt(5)
	v_cvt_pk_f32_fp8_e32 v[144:145], v88
	v_cvt_pk_f32_fp8_sdwa v[146:147], v88 src0_sel:WORD_1
	v_cvt_pk_f32_fp8_e32 v[148:149], v89
	v_cvt_pk_f32_fp8_sdwa v[150:151], v89 src0_sel:WORD_1
	v_cvt_pk_f32_fp8_e32 v[152:153], v90
	v_cvt_pk_f32_fp8_sdwa v[154:155], v90 src0_sel:WORD_1
	v_cvt_pk_f32_fp8_e32 v[156:157], v91
	v_cvt_pk_f32_fp8_sdwa v[158:159], v91 src0_sel:WORD_1
	v_pk_fma_f32 v[112:113], v[144:145], v[32:33], v[112:113] op_sel_hi:[1,0,1]
	v_pk_fma_f32 v[114:115], v[146:147], v[32:33], v[114:115] op_sel_hi:[1,0,1]
	v_pk_fma_f32 v[116:117], v[148:149], v[32:33], v[116:117] op_sel_hi:[1,0,1]
	v_pk_fma_f32 v[118:119], v[150:151], v[32:33], v[118:119] op_sel_hi:[1,0,1]
	v_pk_fma_f32 v[120:121], v[152:153], v[32:33], v[120:121] op_sel_hi:[1,0,1]
	v_pk_fma_f32 v[122:123], v[154:155], v[32:33], v[122:123] op_sel_hi:[1,0,1]
	v_pk_fma_f32 v[124:125], v[156:157], v[32:33], v[124:125] op_sel_hi:[1,0,1]
	v_pk_fma_f32 v[126:127], v[158:159], v[32:33], v[126:127] op_sel_hi:[1,0,1]
	s_waitcnt vmcnt(4)
	v_cvt_pk_f32_fp8_e32 v[144:145], v92
	v_cvt_pk_f32_fp8_sdwa v[146:147], v92 src0_sel:WORD_1
	v_cvt_pk_f32_fp8_e32 v[148:149], v93
	v_cvt_pk_f32_fp8_sdwa v[150:151], v93 src0_sel:WORD_1
	v_cvt_pk_f32_fp8_e32 v[152:153], v94
	v_cvt_pk_f32_fp8_sdwa v[154:155], v94 src0_sel:WORD_1
	v_cvt_pk_f32_fp8_e32 v[156:157], v95
	v_cvt_pk_f32_fp8_sdwa v[158:159], v95 src0_sel:WORD_1
	v_pk_fma_f32 v[112:113], v[144:145], v[34:35], v[112:113] op_sel_hi:[1,0,1]
	v_pk_fma_f32 v[114:115], v[146:147], v[34:35], v[114:115] op_sel_hi:[1,0,1]
	v_pk_fma_f32 v[116:117], v[148:149], v[34:35], v[116:117] op_sel_hi:[1,0,1]
	v_pk_fma_f32 v[118:119], v[150:151], v[34:35], v[118:119] op_sel_hi:[1,0,1]
	v_pk_fma_f32 v[120:121], v[152:153], v[34:35], v[120:121] op_sel_hi:[1,0,1]
	v_pk_fma_f32 v[122:123], v[154:155], v[34:35], v[122:123] op_sel_hi:[1,0,1]
	v_pk_fma_f32 v[124:125], v[156:157], v[34:35], v[124:125] op_sel_hi:[1,0,1]
	v_pk_fma_f32 v[126:127], v[158:159], v[34:35], v[126:127] op_sel_hi:[1,0,1]
	s_waitcnt vmcnt(3)
	v_cvt_pk_f32_fp8_e32 v[144:145], v96
	v_cvt_pk_f32_fp8_sdwa v[146:147], v96 src0_sel:WORD_1
	v_cvt_pk_f32_fp8_e32 v[148:149], v97
	v_cvt_pk_f32_fp8_sdwa v[150:151], v97 src0_sel:WORD_1
	v_cvt_pk_f32_fp8_e32 v[152:153], v98
	v_cvt_pk_f32_fp8_sdwa v[154:155], v98 src0_sel:WORD_1
	v_cvt_pk_f32_fp8_e32 v[156:157], v99
	v_cvt_pk_f32_fp8_sdwa v[158:159], v99 src0_sel:WORD_1
	v_pk_fma_f32 v[112:113], v[144:145], v[36:37], v[112:113] op_sel_hi:[1,0,1]
	v_pk_fma_f32 v[114:115], v[146:147], v[36:37], v[114:115] op_sel_hi:[1,0,1]
	v_pk_fma_f32 v[116:117], v[148:149], v[36:37], v[116:117] op_sel_hi:[1,0,1]
	v_pk_fma_f32 v[118:119], v[150:151], v[36:37], v[118:119] op_sel_hi:[1,0,1]
	v_pk_fma_f32 v[120:121], v[152:153], v[36:37], v[120:121] op_sel_hi:[1,0,1]
	v_pk_fma_f32 v[122:123], v[154:155], v[36:37], v[122:123] op_sel_hi:[1,0,1]
	v_pk_fma_f32 v[124:125], v[156:157], v[36:37], v[124:125] op_sel_hi:[1,0,1]
	v_pk_fma_f32 v[126:127], v[158:159], v[36:37], v[126:127] op_sel_hi:[1,0,1]
	s_waitcnt vmcnt(2)
	v_cvt_pk_f32_fp8_e32 v[144:145], v100
	v_cvt_pk_f32_fp8_sdwa v[146:147], v100 src0_sel:WORD_1
	v_cvt_pk_f32_fp8_e32 v[148:149], v101
	v_cvt_pk_f32_fp8_sdwa v[150:151], v101 src0_sel:WORD_1
	v_cvt_pk_f32_fp8_e32 v[152:153], v102
	v_cvt_pk_f32_fp8_sdwa v[154:155], v102 src0_sel:WORD_1
	v_cvt_pk_f32_fp8_e32 v[156:157], v103
	v_cvt_pk_f32_fp8_sdwa v[158:159], v103 src0_sel:WORD_1
	v_pk_fma_f32 v[112:113], v[144:145], v[38:39], v[112:113] op_sel_hi:[1,0,1]
	v_pk_fma_f32 v[114:115], v[146:147], v[38:39], v[114:115] op_sel_hi:[1,0,1]
	v_pk_fma_f32 v[116:117], v[148:149], v[38:39], v[116:117] op_sel_hi:[1,0,1]
	v_pk_fma_f32 v[118:119], v[150:151], v[38:39], v[118:119] op_sel_hi:[1,0,1]
	v_pk_fma_f32 v[120:121], v[152:153], v[38:39], v[120:121] op_sel_hi:[1,0,1]
	v_pk_fma_f32 v[122:123], v[154:155], v[38:39], v[122:123] op_sel_hi:[1,0,1]
	v_pk_fma_f32 v[124:125], v[156:157], v[38:39], v[124:125] op_sel_hi:[1,0,1]
	v_pk_fma_f32 v[126:127], v[158:159], v[38:39], v[126:127] op_sel_hi:[1,0,1]
	s_waitcnt vmcnt(1)
; __device__ __forceinline__ void peer_up_phase(const Ctx& C, const unsigned char* EU, bf16* XBN, float* RSS, float* xio, const float* gfinal, bool last, const float* SELG, const int* SELI) {
;     ...
; #pragma unroll 1
;             for (int grp = 0; grp < 16; grp += 2) { USTEP(upA, grp); USTEP(upB, grp + 1); }
;     ...
;             f32x4 x0 = (f32x4){bflo(xw0[0]), bfhi(xw0[0]), bflo(xw0[1]), bfhi(xw0[1])}, x1 = (f32x4){bflo(xw0[2]), bfhi(xw0[2]), bflo(xw0[3]), bfhi(xw0[3])};
;             f32x4 x2 = (f32x4){bflo(xw1[0]), bfhi(xw1[0]), bflo(xw1[1]), bfhi(xw1[1])}, x3 = (f32x4){bflo(xw1[2]), bfhi(xw1[2]), bflo(xw1[3]), bfhi(xw1[3])};
;             x0 += (f32x4){y[0].x, y[0].y, y[1].x, y[1].y}; x1 += (f32x4){y[2].x, y[2].y, y[3].x, y[3].y}; x2 += (f32x4){y[4].x, y[4].y, y[5].x, y[5].y}; x3 += (f32x4){y[6].x, y[6].y, y[7].x, y[7].y};
;             if (last) {
;                 const float ss = (x0.x * x0.x + x0.y * x0.y) + (x0.z * x0.z + x0.w * x0.w) + (x1.x * x1.x + x1.y * x1.y) + (x1.z * x1.z + x1.w * x1.w)
;                                + (x2.x * x2.x + x2.y * x2.y) + (x2.z * x2.z + x2.w * x2.w) + (x3.x * x3.x + x3.y * x3.y) + (x3.z * x3.z + x3.w * x3.w);
;                 const float rstd = 1.0f / sqrtf(wave_sum(ss) * (1.f / DM) + RMS_EPS);
;                 float* xr = xio + tok * DM + 16 * gl;
;                 const float* gp = gfinal + 16 * gl;
;                 const f32x4 g0 = *(const f32x4*)gp, g1 = *(const f32x4*)(gp + 4), g2 = *(const f32x4*)(gp + 8), g3 = *(const f32x4*)(gp + 12);
;                 __builtin_nontemporal_store(x0 * rstd * g0, (f32x4*)xr); __builtin_nontemporal_store(x1 * rstd * g1, (f32x4*)(xr + 4)); __builtin_nontemporal_store(x2 * rstd * g2, (f32x4*)(xr + 8)); __builtin_nontemporal_store(x3 * rstd * g3, (f32x4*)(xr + 12));
	v_cvt_pk_f32_fp8_e32 v[144:145], v104
	v_cvt_pk_f32_fp8_sdwa v[146:147], v104 src0_sel:WORD_1
	v_cvt_pk_f32_fp8_e32 v[148:149], v105
	v_cvt_pk_f32_fp8_sdwa v[150:151], v105 src0_sel:WORD_1
	v_cvt_pk_f32_fp8_e32 v[152:153], v106
	v_cvt_pk_f32_fp8_sdwa v[154:155], v106 src0_sel:WORD_1
	v_cvt_pk_f32_fp8_e32 v[156:157], v107
	v_cvt_pk_f32_fp8_sdwa v[158:159], v107 src0_sel:WORD_1
	v_pk_fma_f32 v[112:113], v[144:145], v[40:41], v[112:113] op_sel_hi:[1,0,1]
	v_pk_fma_f32 v[114:115], v[146:147], v[40:41], v[114:115] op_sel_hi:[1,0,1]
	v_pk_fma_f32 v[116:117], v[148:149], v[40:41], v[116:117] op_sel_hi:[1,0,1]
	v_pk_fma_f32 v[118:119], v[150:151], v[40:41], v[118:119] op_sel_hi:[1,0,1]
	v_pk_fma_f32 v[120:121], v[152:153], v[40:41], v[120:121] op_sel_hi:[1,0,1]
	v_pk_fma_f32 v[122:123], v[154:155], v[40:41], v[122:123] op_sel_hi:[1,0,1]
	v_pk_fma_f32 v[124:125], v[156:157], v[40:41], v[124:125] op_sel_hi:[1,0,1]
	v_pk_fma_f32 v[126:127], v[158:159], v[40:41], v[126:127] op_sel_hi:[1,0,1]
	s_waitcnt vmcnt(0)
	v_cvt_pk_f32_fp8_e32 v[144:145], v108
	v_cvt_pk_f32_fp8_sdwa v[146:147], v108 src0_sel:WORD_1
	v_cvt_pk_f32_fp8_e32 v[148:149], v109
	v_cvt_pk_f32_fp8_sdwa v[150:151], v109 src0_sel:WORD_1
	v_cvt_pk_f32_fp8_e32 v[152:153], v110
	v_cvt_pk_f32_fp8_sdwa v[154:155], v110 src0_sel:WORD_1
	v_cvt_pk_f32_fp8_e32 v[156:157], v111
	v_cvt_pk_f32_fp8_sdwa v[158:159], v111 src0_sel:WORD_1
	v_pk_fma_f32 v[112:113], v[144:145], v[42:43], v[112:113] op_sel_hi:[1,0,1]
	v_pk_fma_f32 v[114:115], v[146:147], v[42:43], v[114:115] op_sel_hi:[1,0,1]
	v_pk_fma_f32 v[116:117], v[148:149], v[42:43], v[116:117] op_sel_hi:[1,0,1]
	v_pk_fma_f32 v[118:119], v[150:151], v[42:43], v[118:119] op_sel_hi:[1,0,1]
	v_pk_fma_f32 v[120:121], v[152:153], v[42:43], v[120:121] op_sel_hi:[1,0,1]
	v_pk_fma_f32 v[122:123], v[154:155], v[42:43], v[122:123] op_sel_hi:[1,0,1]
	v_pk_fma_f32 v[124:125], v[156:157], v[42:43], v[124:125] op_sel_hi:[1,0,1]
	v_pk_fma_f32 v[126:127], v[158:159], v[42:43], v[126:127] op_sel_hi:[1,0,1]
	s_nop 1
	v_permlane32_swap_b32_e32 v112, v120
	v_permlane32_swap_b32_e32 v113, v121
	v_permlane32_swap_b32_e32 v114, v122
	v_permlane32_swap_b32_e32 v115, v123
	v_permlane32_swap_b32_e32 v116, v124
	v_permlane32_swap_b32_e32 v117, v125
	v_permlane32_swap_b32_e32 v118, v126
	v_permlane32_swap_b32_e32 v119, v127
	v_add_f32_e32 v112, v112, v120
	v_add_f32_e32 v113, v113, v121
	v_add_f32_e32 v114, v114, v122
	v_add_f32_e32 v115, v115, v123
	v_add_f32_e32 v116, v116, v124
	v_add_f32_e32 v117, v117, v125
	v_add_f32_e32 v118, v118, v126
	v_add_f32_e32 v119, v119, v127
	s_nop 1
	v_permlane16_swap_b32_e32 v112, v116
	v_permlane16_swap_b32_e32 v113, v117
	v_permlane16_swap_b32_e32 v114, v118
	v_permlane16_swap_b32_e32 v115, v119
	v_add_f32_e32 v112, v112, v116
	v_add_f32_e32 v113, v113, v117
	v_add_f32_e32 v114, v114, v118
	v_add_f32_e32 v115, v115, v119
	s_nop 1
	v_add_f32_dpp v112, v112, v112 row_ror:8 row_mask:0xf bank_mask:0xf
	v_add_f32_dpp v113, v113, v113 row_ror:8 row_mask:0xf bank_mask:0xf
	v_add_f32_dpp v114, v114, v114 row_ror:8 row_mask:0xf bank_mask:0xf
	v_add_f32_dpp v115, v115, v115 row_ror:8 row_mask:0xf bank_mask:0xf
	v_lshlrev_b32_e32 v44, 16, v10
	v_and_b32_e32 v45, 0xffff0000, v10
	v_lshlrev_b32_e32 v46, 16, v11
	v_and_b32_e32 v47, 0xffff0000, v11
	v_add_f32_e32 v44, v44, v112
	v_add_f32_e32 v45, v45, v113
	v_add_f32_e32 v46, v46, v114
	v_add_f32_e32 v47, v47, v115
	s_add_i32 s2, s14, s20
	s_lshl_b32 s2, s2, 12
	s_add_u32 s0, s12, s2
	s_addc_u32 s1, s13, 0
	global_store_dwordx4 v161, v[44:47], s[0:1]
	v_mul_f32_e32 v163, v44, v44
	v_fmac_f32_e32 v163, v45, v45
	v_fmac_f32_e32 v163, v46, v46
	v_fmac_f32_e32 v163, v47, v47
	s_nop 1
	v_add_f32_dpp v163, v163, v163 quad_perm:[1,0,3,2] row_mask:0xf bank_mask:0xf
	s_nop 1
	v_add_f32_dpp v163, v163, v163 quad_perm:[2,3,0,1] row_mask:0xf bank_mask:0xf
	s_nop 1
	v_add_f32_dpp v163, v163, v163 row_half_mirror row_mask:0xf bank_mask:0xf
	v_mov_b32_e32 v164, v163
	s_nop 1
	v_permlane16_swap_b32_e32 v163, v164
	v_add_f32_e32 v163, v163, v164
	v_mov_b32_e32 v164, v163
	s_nop 1
	v_permlane32_swap_b32_e32 v163, v164
	v_add_f32_e32 v163, v163, v164
	s_lshl_b32 s2, s20, 2
	v_add_u32_e32 v164, s2, v162
	s_mov_b64 exec, 1
	ds_add_f32 v164, v163
	s_mov_b64 exec, -1
	s_add_i32 s20, s20, 1
	s_cmp_lt_u32 s20, 32
	s_cbranch_scc1 .Lupl_tok
	s_add_i32 s15, s15, 1
	s_cmp_lt_u32 s15, 8
	s_cbranch_scc1 .Lupl_pass
	v_readlane_b32 s8, v249, 4
	v_readlane_b32 s9, v249, 5
	v_readlane_b32 s12, v249, 6
	v_readlane_b32 s13, v249, 7
	v_lshlrev_b32_e32 v8, 6, v177
	s_nop 0
	s_nop 0
	global_load_dwordx4 v[16:19], v8, s[8:9]
	global_load_dwordx4 v[20:23], v8, s[8:9] offset:16
	global_load_dwordx4 v[24:27], v8, s[8:9] offset:32
	global_load_dwordx4 v[28:31], v8, s[8:9] offset:48
	v_subrev_u32_e32 v9, v4, v162
	s_mov_b32 s20, 0
	s_waitcnt vmcnt(0)
